# v23 with s_setprio 0 moved after the post-MFMA barrier so the barrier is signalled directly after the last MFMA
# baseline (speedup 1.0000x reference)
; #define PG8_STAGE(bufoff, gbase, voff) do { _Pragma("unroll") for (int _i = 0; _i < 2; ++_i) \
;         __builtin_amdgcn_global_load_lds((const unsigned*)((const char*)(gbase) + (voff)[_i]), (PG8_LAS unsigned*)(lds + (bufoff) + ldsw + _i * 8192), 16, 0, 0); } while (0)
; #define PG8_LDA(dst, b, h) do { _Pragma("unroll") for (int m = 0; m < 4; ++m) _Pragma("unroll") for (int k = 0; k < 2; ++k) dst[m][k] = *(const PG8_LAS bf16x8*)(lds + PG8_SA(b, h) + aoff + m * 2048 + k * 1024); } while (0)
; #define PG8_LDB(dst, b, h) do { _Pragma("unroll") for (int n = 0; n < 2; ++n) _Pragma("unroll") for (int k = 0; k < 2; ++k) dst[n][k] = *(const PG8_LAS bf16x8*)(lds + PG8_SB(b, h) + boff + n * 2048 + k * 1024); } while (0)
; #define PG8_MMA(ai, bj, At, Bt) do { __builtin_amdgcn_s_setprio(1); _Pragma("unroll") for (int m = 0; m < 4; ++m) _Pragma("unroll") for (int n = 0; n < 2; ++n) _Pragma("unroll") for (int k = 0; k < 2; ++k) \
;         acc[ai][bj][m][n] = __builtin_amdgcn_mfma_f32_16x16x32_bf16(Bt[n][k], At[m][k], acc[ai][bj][m][n], 0, 0, 0); __builtin_amdgcn_s_setprio(0); } while (0)
; #define PG8_WAIT_V(n) asm volatile("s_waitcnt vmcnt(" #n ")" ::: "memory")
; #define PG8_WAIT_L(n) asm volatile("s_waitcnt lgkmcnt(" #n ")" ::: "memory")
; #define PG8_BAR __builtin_amdgcn_s_barrier()
; template <class Epi, class Sched, bool ALIGN_EPI = false, bool SP2 = false>
; __device__ __forceinline__ void gemm_phase(PG8_LAS unsigned char* lds, const Gemm g, const Sched& S, const Epi& E, const int wave_id) {
;     ...
;             const char* a1 = cA + (size_t)(t + 1) * kstep;
;             const char* a2 = last ? nA : cA + (size_t)(t + 2) * kstep; const char* b2 = last ? nB : cB + (size_t)(t + 2) * kstep;
;             const char* a3 = a2 + kstep; const char* b3 = b2 + kstep;
;             if (last && has_next) S.a_ready(nxt);
;             if constexpr (SP2) {
;             PG8_LDB(B0, 0, 0); PG8_LDB(B1, 0, 1); PG8_SCHED; PG8_LDA(At, 0, 0); PG8_STAGE(PG8_SA(1, 1), a1 + hstepA, voffA);
;             PG8_WAIT_V(8); PG8_WAIT_L(0); PG8_BAR; PG8_MMA(0, 0, At, B0); PG8_MMA(0, 1, At, B1); PG8_BAR; PG8_SCHED;
;             PG8_LDA(At, 0, 1); PG8_STAGE(PG8_SB(0, 0), b2, voffB); PG8_STAGE(PG8_SB(0, 1), b2 + hstepB, voffB); PG8_STAGE(PG8_SA(0, 0), a2, voffA);
;             PG8_WAIT_V(8); PG8_WAIT_L(0); PG8_BAR; PG8_MMA(1, 0, At, B0); PG8_MMA(1, 1, At, B1); PG8_BAR; PG8_SCHED;
.LBB0_35:
	s_add_u32 s28, s26, 0xfff00080
	s_addc_u32 s29, s27, -1
	s_add_i32 s86, 0, 0x10000
	s_cmp_eq_u32 s83, 60
	s_cselect_b32 s31, s0, s29
	s_cselect_b32 s30, s1, s28
	v_add_u32_e32 v0, s86, v188
	s_cselect_b32 s29, s3, s38
	s_cselect_b32 s28, s19, s21
	s_add_i32 s91, 0, 0x14000
	ds_read_b128 v[130:133], v0
	ds_read_b128 v[134:137], v0 offset:1024
	ds_read_b128 v[138:141], v0 offset:2048
	ds_read_b128 v[142:145], v0 offset:3072
	v_add_u32_e32 v0, s91, v188
	ds_read_b128 v[146:149], v0
	ds_read_b128 v[150:153], v0 offset:1024
	ds_read_b128 v[166:169], v0 offset:2048
	ds_read_b128 v[178:181], v0 offset:3072
	v_lshl_add_u64 v[186:187], s[26:27], 0, v[162:163]
	s_add_i32 m0, s9, 0xc000
	ds_read_b128 v[182:185], v194
	ds_read_b128 v[196:199], v194 offset:1024
	ds_read_b128 v[200:203], v194 offset:2048
	ds_read_b128 v[204:207], v194 offset:3072
	ds_read_b128 v[208:211], v194 offset:4096
	ds_read_b128 v[212:215], v194 offset:5120
	ds_read_b128 v[216:219], v194 offset:6144
	ds_read_b128 v[220:223], v194 offset:7168
	global_load_lds_dwordx4 v[186:187], off
	v_lshl_add_u64 v[186:187], s[26:27], 0, v[164:165]
	s_add_i32 m0, s9, 0xe000
	s_nop 0
	global_load_lds_dwordx4 v[186:187], off
	s_waitcnt vmcnt(8)
	s_waitcnt lgkmcnt(0)
	s_setprio 1
	s_barrier
	v_mfma_f32_16x16x32_bf16 v[126:129], v[130:133], v[182:185], v[126:129]
	v_mfma_f32_16x16x32_bf16 v[122:125], v[138:141], v[182:185], v[122:125]
	v_mfma_f32_16x16x32_bf16 v[110:113], v[130:133], v[200:203], v[110:113]
	v_mfma_f32_16x16x32_bf16 v[106:109], v[138:141], v[200:203], v[106:109]
	v_mfma_f32_16x16x32_bf16 v[94:97], v[130:133], v[208:211], v[94:97]
	v_mfma_f32_16x16x32_bf16 v[90:93], v[138:141], v[208:211], v[90:93]
	v_mfma_f32_16x16x32_bf16 v[78:81], v[130:133], v[216:219], v[78:81]
	v_mfma_f32_16x16x32_bf16 v[74:77], v[138:141], v[216:219], v[74:77]
	v_mfma_f32_16x16x32_bf16 v[126:129], v[134:137], v[196:199], v[126:129]
	v_mfma_f32_16x16x32_bf16 v[122:125], v[142:145], v[196:199], v[122:125]
	v_mfma_f32_16x16x32_bf16 v[110:113], v[134:137], v[204:207], v[110:113]
	v_mfma_f32_16x16x32_bf16 v[106:109], v[142:145], v[204:207], v[106:109]
	v_mfma_f32_16x16x32_bf16 v[94:97], v[134:137], v[212:215], v[94:97]
	v_mfma_f32_16x16x32_bf16 v[90:93], v[142:145], v[212:215], v[90:93]
	v_mfma_f32_16x16x32_bf16 v[78:81], v[134:137], v[220:223], v[78:81]
	v_mfma_f32_16x16x32_bf16 v[74:77], v[142:145], v[220:223], v[74:77]
	v_mfma_f32_16x16x32_bf16 v[118:121], v[146:149], v[182:185], v[118:121]
	v_mfma_f32_16x16x32_bf16 v[114:117], v[166:169], v[182:185], v[114:117]
	v_mfma_f32_16x16x32_bf16 v[102:105], v[146:149], v[200:203], v[102:105]
	v_mfma_f32_16x16x32_bf16 v[98:101], v[166:169], v[200:203], v[98:101]
	v_mfma_f32_16x16x32_bf16 v[86:89], v[146:149], v[208:211], v[86:89]
	v_mfma_f32_16x16x32_bf16 v[82:85], v[166:169], v[208:211], v[82:85]
	v_mfma_f32_16x16x32_bf16 v[70:73], v[146:149], v[216:219], v[70:73]
	v_mfma_f32_16x16x32_bf16 v[66:69], v[166:169], v[216:219], v[66:69]
	v_mfma_f32_16x16x32_bf16 v[118:121], v[150:153], v[196:199], v[118:121]
	v_mfma_f32_16x16x32_bf16 v[114:117], v[178:181], v[196:199], v[114:117]
	v_mfma_f32_16x16x32_bf16 v[102:105], v[150:153], v[204:207], v[102:105]
	v_mfma_f32_16x16x32_bf16 v[98:101], v[178:181], v[204:207], v[98:101]
	v_mfma_f32_16x16x32_bf16 v[86:89], v[150:153], v[212:215], v[86:89]
	v_mfma_f32_16x16x32_bf16 v[82:85], v[178:181], v[212:215], v[82:85]
	v_mfma_f32_16x16x32_bf16 v[70:73], v[150:153], v[220:223], v[70:73]
	v_mfma_f32_16x16x32_bf16 v[66:69], v[178:181], v[220:223], v[66:69]
	s_barrier
	s_setprio 0
	s_add_i32 s86, s86, s14
	v_lshl_add_u64 v[186:187], s[28:29], 0, v[156:157]
	s_mov_b32 m0, s86
	ds_read_b128 v[182:185], v194 offset:16384
	ds_read_b128 v[196:199], v194 offset:17408
	ds_read_b128 v[200:203], v194 offset:18432
	ds_read_b128 v[204:207], v194 offset:19456
	ds_read_b128 v[208:211], v194 offset:20480
	ds_read_b128 v[212:215], v194 offset:21504
	ds_read_b128 v[216:219], v194 offset:22528
	ds_read_b128 v[220:223], v194 offset:23552
	global_load_lds_dwordx4 v[186:187], off
	s_add_i32 m0, s86, 0x2000
	s_add_u32 s86, s28, 0x100000
	v_lshl_add_u64 v[224:225], s[28:29], 0, v[160:161]
	s_addc_u32 s87, s29, 0
	s_add_i32 s91, s91, s14
	global_load_lds_dwordx4 v[224:225], off
	v_lshl_add_u64 v[234:235], s[86:87], 0, v[156:157]
	s_mov_b32 m0, s91
	v_lshl_add_u64 v[236:237], s[30:31], 0, v[158:159]
	global_load_lds_dwordx4 v[234:235], off
	v_lshl_add_u64 v[234:235], s[86:87], 0, v[160:161]
	s_add_i32 m0, s91, 0x2000
	s_nop 0
	global_load_lds_dwordx4 v[234:235], off
	v_lshl_add_u64 v[234:235], s[30:31], 0, v[154:155]
	s_mov_b32 m0, s9
	s_nop 0
	global_load_lds_dwordx4 v[234:235], off
	s_mov_b32 m0, s15
	s_nop 0
	global_load_lds_dwordx4 v[236:237], off
	s_waitcnt vmcnt(8)
	s_waitcnt lgkmcnt(0)
	s_setprio 1
	s_barrier
; #define PG8_STAGE(bufoff, gbase, voff) do { _Pragma("unroll") for (int _i = 0; _i < 2; ++_i) \
;         __builtin_amdgcn_global_load_lds((const unsigned*)((const char*)(gbase) + (voff)[_i]), (PG8_LAS unsigned*)(lds + (bufoff) + ldsw + _i * 8192), 16, 0, 0); } while (0)
; #define PG8_LDA(dst, b, h) do { _Pragma("unroll") for (int m = 0; m < 4; ++m) _Pragma("unroll") for (int k = 0; k < 2; ++k) dst[m][k] = *(const PG8_LAS bf16x8*)(lds + PG8_SA(b, h) + aoff + m * 2048 + k * 1024); } while (0)
; #define PG8_LDB(dst, b, h) do { _Pragma("unroll") for (int n = 0; n < 2; ++n) _Pragma("unroll") for (int k = 0; k < 2; ++k) dst[n][k] = *(const PG8_LAS bf16x8*)(lds + PG8_SB(b, h) + boff + n * 2048 + k * 1024); } while (0)
; #define PG8_MMA(ai, bj, At, Bt) do { __builtin_amdgcn_s_setprio(1); _Pragma("unroll") for (int m = 0; m < 4; ++m) _Pragma("unroll") for (int n = 0; n < 2; ++n) _Pragma("unroll") for (int k = 0; k < 2; ++k) \
;         acc[ai][bj][m][n] = __builtin_amdgcn_mfma_f32_16x16x32_bf16(Bt[n][k], At[m][k], acc[ai][bj][m][n], 0, 0, 0); __builtin_amdgcn_s_setprio(0); } while (0)
; #define PG8_WAIT_V(n) asm volatile("s_waitcnt vmcnt(" #n ")" ::: "memory")
; #define PG8_WAIT_L(n) asm volatile("s_waitcnt lgkmcnt(" #n ")" ::: "memory")
; #define PG8_BAR __builtin_amdgcn_s_barrier()
; #define PG8_SCHED __builtin_amdgcn_sched_barrier(0)
; template <class Epi, class Sched, bool ALIGN_EPI = false, bool SP2 = false>
; __device__ __forceinline__ void gemm_phase(PG8_LAS unsigned char* lds, const Gemm g, const Sched& S, const Epi& E, const int wave_id) {
;     ...
;             PG8_WAIT_V(8); PG8_WAIT_L(0); PG8_BAR; PG8_MMA(1, 0, At, B0); PG8_MMA(1, 1, At, B1); PG8_BAR; PG8_SCHED;
;             PG8_LDB(B0, 1, 0); PG8_LDB(B1, 1, 1); PG8_SCHED; PG8_LDA(At, 1, 0); PG8_STAGE(PG8_SA(0, 1), a2 + hstepA, voffA);
;             PG8_WAIT_V(8); PG8_WAIT_L(0); PG8_BAR; PG8_MMA(0, 0, At, B0); PG8_MMA(0, 1, At, B1); PG8_BAR; PG8_SCHED;
	v_mfma_f32_16x16x32_bf16 v[62:65], v[130:133], v[182:185], v[62:65]
	v_mfma_f32_16x16x32_bf16 v[58:61], v[138:141], v[182:185], v[58:61]
	v_mfma_f32_16x16x32_bf16 v[46:49], v[130:133], v[200:203], v[46:49]
	v_mfma_f32_16x16x32_bf16 v[42:45], v[138:141], v[200:203], v[42:45]
	v_mfma_f32_16x16x32_bf16 v[30:33], v[130:133], v[208:211], v[30:33]
	v_mfma_f32_16x16x32_bf16 v[26:29], v[138:141], v[208:211], v[26:29]
	v_mfma_f32_16x16x32_bf16 v[14:17], v[130:133], v[216:219], v[14:17]
	v_mfma_f32_16x16x32_bf16 v[10:13], v[138:141], v[216:219], v[10:13]
	v_mfma_f32_16x16x32_bf16 v[62:65], v[134:137], v[196:199], v[62:65]
	v_mfma_f32_16x16x32_bf16 v[58:61], v[142:145], v[196:199], v[58:61]
	v_mfma_f32_16x16x32_bf16 v[46:49], v[134:137], v[204:207], v[46:49]
	v_mfma_f32_16x16x32_bf16 v[42:45], v[142:145], v[204:207], v[42:45]
	v_mfma_f32_16x16x32_bf16 v[30:33], v[134:137], v[212:215], v[30:33]
	v_mfma_f32_16x16x32_bf16 v[26:29], v[142:145], v[212:215], v[26:29]
	v_mfma_f32_16x16x32_bf16 v[14:17], v[134:137], v[220:223], v[14:17]
	v_mfma_f32_16x16x32_bf16 v[10:13], v[142:145], v[220:223], v[10:13]
	v_mfma_f32_16x16x32_bf16 v[54:57], v[146:149], v[182:185], v[54:57]
	v_mfma_f32_16x16x32_bf16 v[50:53], v[166:169], v[182:185], v[50:53]
	v_mfma_f32_16x16x32_bf16 v[38:41], v[146:149], v[200:203], v[38:41]
	v_mfma_f32_16x16x32_bf16 v[34:37], v[166:169], v[200:203], v[34:37]
	v_mfma_f32_16x16x32_bf16 v[22:25], v[146:149], v[208:211], v[22:25]
	v_mfma_f32_16x16x32_bf16 v[18:21], v[166:169], v[208:211], v[18:21]
	v_mfma_f32_16x16x32_bf16 v[6:9], v[146:149], v[216:219], v[6:9]
	v_mfma_f32_16x16x32_bf16 v[2:5], v[166:169], v[216:219], v[2:5]
	v_mfma_f32_16x16x32_bf16 v[54:57], v[150:153], v[196:199], v[54:57]
	v_mfma_f32_16x16x32_bf16 v[50:53], v[178:181], v[196:199], v[50:53]
	v_mfma_f32_16x16x32_bf16 v[38:41], v[150:153], v[204:207], v[38:41]
	v_mfma_f32_16x16x32_bf16 v[34:37], v[178:181], v[204:207], v[34:37]
	v_mfma_f32_16x16x32_bf16 v[22:25], v[150:153], v[212:215], v[22:25]
	v_mfma_f32_16x16x32_bf16 v[18:21], v[178:181], v[212:215], v[18:21]
	v_mfma_f32_16x16x32_bf16 v[6:9], v[150:153], v[220:223], v[6:9]
	v_mfma_f32_16x16x32_bf16 v[2:5], v[178:181], v[220:223], v[2:5]
	s_barrier
	s_setprio 0
	s_add_i32 s86, 0, 0x18000
	v_add_u32_e32 v0, s86, v188
	s_add_i32 s87, 0, 0x1c000
	ds_read_b128 v[130:133], v0
	ds_read_b128 v[134:137], v0 offset:1024
	ds_read_b128 v[138:141], v0 offset:2048
	ds_read_b128 v[142:145], v0 offset:3072
	v_add_u32_e32 v0, s87, v188
	ds_read_b128 v[146:149], v0
	ds_read_b128 v[150:153], v0 offset:1024
	ds_read_b128 v[166:169], v0 offset:2048
	ds_read_b128 v[178:181], v0 offset:3072
	s_add_u32 s30, s30, 0x100000
	s_addc_u32 s31, s31, 0
	s_mov_b32 m0, s34
	v_lshl_add_u64 v[240:241], s[30:31], 0, v[154:155]
	ds_read_b128 v[182:185], v194 offset:32768
	ds_read_b128 v[196:199], v194 offset:33792
	ds_read_b128 v[200:203], v194 offset:34816
	ds_read_b128 v[204:207], v194 offset:35840
	ds_read_b128 v[208:211], v194 offset:36864
	ds_read_b128 v[212:215], v194 offset:37888
	ds_read_b128 v[216:219], v194 offset:38912
	ds_read_b128 v[220:223], v194 offset:39936
	global_load_lds_dwordx4 v[240:241], off
	v_lshl_add_u64 v[240:241], s[30:31], 0, v[158:159]
	s_mov_b32 m0, s35
	s_nop 0
	global_load_lds_dwordx4 v[240:241], off
	s_waitcnt vmcnt(8)
	s_waitcnt lgkmcnt(0)
	s_setprio 1
	s_barrier
	v_mfma_f32_16x16x32_bf16 v[126:129], v[130:133], v[182:185], v[126:129]
	v_mfma_f32_16x16x32_bf16 v[122:125], v[138:141], v[182:185], v[122:125]
	v_mfma_f32_16x16x32_bf16 v[110:113], v[130:133], v[200:203], v[110:113]
	v_mfma_f32_16x16x32_bf16 v[106:109], v[138:141], v[200:203], v[106:109]
	v_mfma_f32_16x16x32_bf16 v[94:97], v[130:133], v[208:211], v[94:97]
	v_mfma_f32_16x16x32_bf16 v[90:93], v[138:141], v[208:211], v[90:93]
	v_mfma_f32_16x16x32_bf16 v[78:81], v[130:133], v[216:219], v[78:81]
	v_mfma_f32_16x16x32_bf16 v[74:77], v[138:141], v[216:219], v[74:77]
	v_mfma_f32_16x16x32_bf16 v[126:129], v[134:137], v[196:199], v[126:129]
	v_mfma_f32_16x16x32_bf16 v[122:125], v[142:145], v[196:199], v[122:125]
	v_mfma_f32_16x16x32_bf16 v[110:113], v[134:137], v[204:207], v[110:113]
	v_mfma_f32_16x16x32_bf16 v[106:109], v[142:145], v[204:207], v[106:109]
	v_mfma_f32_16x16x32_bf16 v[94:97], v[134:137], v[212:215], v[94:97]
	v_mfma_f32_16x16x32_bf16 v[90:93], v[142:145], v[212:215], v[90:93]
	v_mfma_f32_16x16x32_bf16 v[78:81], v[134:137], v[220:223], v[78:81]
	v_mfma_f32_16x16x32_bf16 v[74:77], v[142:145], v[220:223], v[74:77]
	v_mfma_f32_16x16x32_bf16 v[118:121], v[146:149], v[182:185], v[118:121]
	v_mfma_f32_16x16x32_bf16 v[114:117], v[166:169], v[182:185], v[114:117]
	v_mfma_f32_16x16x32_bf16 v[102:105], v[146:149], v[200:203], v[102:105]
	v_mfma_f32_16x16x32_bf16 v[98:101], v[166:169], v[200:203], v[98:101]
	v_mfma_f32_16x16x32_bf16 v[86:89], v[146:149], v[208:211], v[86:89]
	v_mfma_f32_16x16x32_bf16 v[82:85], v[166:169], v[208:211], v[82:85]
	v_mfma_f32_16x16x32_bf16 v[70:73], v[146:149], v[216:219], v[70:73]
	v_mfma_f32_16x16x32_bf16 v[66:69], v[166:169], v[216:219], v[66:69]
	v_mfma_f32_16x16x32_bf16 v[118:121], v[150:153], v[196:199], v[118:121]
	v_mfma_f32_16x16x32_bf16 v[114:117], v[178:181], v[196:199], v[114:117]
	v_mfma_f32_16x16x32_bf16 v[102:105], v[150:153], v[204:207], v[102:105]
	v_mfma_f32_16x16x32_bf16 v[98:101], v[178:181], v[204:207], v[98:101]
	v_mfma_f32_16x16x32_bf16 v[86:89], v[150:153], v[212:215], v[86:89]
	v_mfma_f32_16x16x32_bf16 v[82:85], v[178:181], v[212:215], v[82:85]
	v_mfma_f32_16x16x32_bf16 v[70:73], v[150:153], v[220:223], v[70:73]
	v_mfma_f32_16x16x32_bf16 v[66:69], v[178:181], v[220:223], v[66:69]
	s_barrier
; #define PG8_STAGE(bufoff, gbase, voff) do { _Pragma("unroll") for (int _i = 0; _i < 2; ++_i) \
;         __builtin_amdgcn_global_load_lds((const unsigned*)((const char*)(gbase) + (voff)[_i]), (PG8_LAS unsigned*)(lds + (bufoff) + ldsw + _i * 8192), 16, 0, 0); } while (0)
; #define PG8_LDA(dst, b, h) do { _Pragma("unroll") for (int m = 0; m < 4; ++m) _Pragma("unroll") for (int k = 0; k < 2; ++k) dst[m][k] = *(const PG8_LAS bf16x8*)(lds + PG8_SA(b, h) + aoff + m * 2048 + k * 1024); } while (0)
; #define PG8_MMA(ai, bj, At, Bt) do { __builtin_amdgcn_s_setprio(1); _Pragma("unroll") for (int m = 0; m < 4; ++m) _Pragma("unroll") for (int n = 0; n < 2; ++n) _Pragma("unroll") for (int k = 0; k < 2; ++k) \
;         acc[ai][bj][m][n] = __builtin_amdgcn_mfma_f32_16x16x32_bf16(Bt[n][k], At[m][k], acc[ai][bj][m][n], 0, 0, 0); __builtin_amdgcn_s_setprio(0); } while (0)
; #define PG8_WAIT_V(n) asm volatile("s_waitcnt vmcnt(" #n ")" ::: "memory")
; #define PG8_WAIT_L(n) asm volatile("s_waitcnt lgkmcnt(" #n ")" ::: "memory")
; #define PG8_BAR __builtin_amdgcn_s_barrier()
; #define PG8_SCHED __builtin_amdgcn_sched_barrier(0)
; template <class Epi, class Sched, bool ALIGN_EPI = false, bool SP2 = false>
; __device__ __forceinline__ void gemm_phase(PG8_LAS unsigned char* lds, const Gemm g, const Sched& S, const Epi& E, const int wave_id) {
;     ...
;         for (int t = 0; t < nt; t += 2) {
;     ...
;             PG8_WAIT_V(8); PG8_WAIT_L(0); PG8_BAR; PG8_MMA(0, 0, At, B0); PG8_MMA(0, 1, At, B1); PG8_BAR; PG8_SCHED;
;             PG8_LDA(At, 1, 1); PG8_STAGE(PG8_SB(1, 0), b3, voffB); PG8_STAGE(PG8_SB(1, 1), b3 + hstepB, voffB); PG8_STAGE(PG8_SA(1, 0), a3, voffA);
;             PG8_WAIT_V(8); PG8_WAIT_L(0); PG8_BAR; PG8_MMA(1, 0, At, B0); PG8_MMA(1, 1, At, B1); PG8_BAR; PG8_SCHED;
	s_setprio 0
	s_add_i32 s30, s86, s14
	v_lshl_add_u64 v[186:187], v[186:187], 0, s[62:63]
	s_mov_b32 m0, s30
	ds_read_b128 v[182:185], v194 offset:49152
	ds_read_b128 v[196:199], v194 offset:50176
	ds_read_b128 v[200:203], v194 offset:51200
	ds_read_b128 v[204:207], v194 offset:52224
	ds_read_b128 v[208:211], v194 offset:53248
	ds_read_b128 v[212:215], v194 offset:54272
	ds_read_b128 v[216:219], v194 offset:55296
	ds_read_b128 v[220:223], v194 offset:56320
	global_load_lds_dwordx4 v[186:187], off
	s_add_i32 m0, s30, 0x2000
	s_add_u32 s28, s28, 0x100080
	v_lshl_add_u64 v[186:187], v[224:225], 0, s[62:63]
	s_addc_u32 s29, s29, 0
	s_add_i32 s30, s87, s14
	global_load_lds_dwordx4 v[186:187], off
	v_lshl_add_u64 v[186:187], s[28:29], 0, v[156:157]
	s_mov_b32 m0, s30
	s_nop 0
	global_load_lds_dwordx4 v[186:187], off
	v_lshl_add_u64 v[186:187], s[28:29], 0, v[160:161]
	s_add_i32 m0, s30, 0x2000
	s_nop 0
	global_load_lds_dwordx4 v[186:187], off
	v_lshl_add_u64 v[186:187], v[234:235], 0, s[62:63]
	s_mov_b32 m0, s50
	s_nop 0
	global_load_lds_dwordx4 v[186:187], off
	v_lshl_add_u64 v[186:187], v[236:237], 0, s[62:63]
	s_mov_b32 m0, s76
	s_nop 0
	global_load_lds_dwordx4 v[186:187], off
	s_waitcnt vmcnt(8)
	s_waitcnt lgkmcnt(0)
	s_setprio 1
	s_barrier
	v_mfma_f32_16x16x32_bf16 v[62:65], v[130:133], v[182:185], v[62:65]
	v_mfma_f32_16x16x32_bf16 v[58:61], v[138:141], v[182:185], v[58:61]
	v_mfma_f32_16x16x32_bf16 v[46:49], v[130:133], v[200:203], v[46:49]
	v_mfma_f32_16x16x32_bf16 v[42:45], v[138:141], v[200:203], v[42:45]
	v_mfma_f32_16x16x32_bf16 v[30:33], v[130:133], v[208:211], v[30:33]
	v_mfma_f32_16x16x32_bf16 v[26:29], v[138:141], v[208:211], v[26:29]
	v_mfma_f32_16x16x32_bf16 v[14:17], v[130:133], v[216:219], v[14:17]
	v_mfma_f32_16x16x32_bf16 v[10:13], v[138:141], v[216:219], v[10:13]
	v_mfma_f32_16x16x32_bf16 v[62:65], v[134:137], v[196:199], v[62:65]
	v_mfma_f32_16x16x32_bf16 v[58:61], v[142:145], v[196:199], v[58:61]
	v_mfma_f32_16x16x32_bf16 v[46:49], v[134:137], v[204:207], v[46:49]
	v_mfma_f32_16x16x32_bf16 v[42:45], v[142:145], v[204:207], v[42:45]
	v_mfma_f32_16x16x32_bf16 v[30:33], v[134:137], v[212:215], v[30:33]
	v_mfma_f32_16x16x32_bf16 v[26:29], v[142:145], v[212:215], v[26:29]
	v_mfma_f32_16x16x32_bf16 v[14:17], v[134:137], v[220:223], v[14:17]
	v_mfma_f32_16x16x32_bf16 v[10:13], v[142:145], v[220:223], v[10:13]
	v_mfma_f32_16x16x32_bf16 v[54:57], v[146:149], v[182:185], v[54:57]
	v_mfma_f32_16x16x32_bf16 v[50:53], v[166:169], v[182:185], v[50:53]
	v_mfma_f32_16x16x32_bf16 v[38:41], v[146:149], v[200:203], v[38:41]
	v_mfma_f32_16x16x32_bf16 v[34:37], v[166:169], v[200:203], v[34:37]
	v_mfma_f32_16x16x32_bf16 v[22:25], v[146:149], v[208:211], v[22:25]
	v_mfma_f32_16x16x32_bf16 v[18:21], v[166:169], v[208:211], v[18:21]
	v_mfma_f32_16x16x32_bf16 v[6:9], v[146:149], v[216:219], v[6:9]
	v_mfma_f32_16x16x32_bf16 v[2:5], v[166:169], v[216:219], v[2:5]
	v_mfma_f32_16x16x32_bf16 v[54:57], v[150:153], v[196:199], v[54:57]
	v_mfma_f32_16x16x32_bf16 v[50:53], v[178:181], v[196:199], v[50:53]
	v_mfma_f32_16x16x32_bf16 v[38:41], v[150:153], v[204:207], v[38:41]
	v_mfma_f32_16x16x32_bf16 v[34:37], v[178:181], v[204:207], v[34:37]
	v_mfma_f32_16x16x32_bf16 v[22:25], v[150:153], v[212:215], v[22:25]
	v_mfma_f32_16x16x32_bf16 v[18:21], v[178:181], v[212:215], v[18:21]
	v_mfma_f32_16x16x32_bf16 v[6:9], v[150:153], v[220:223], v[6:9]
	v_mfma_f32_16x16x32_bf16 v[2:5], v[178:181], v[220:223], v[2:5]
	s_barrier
	s_setprio 0
	s_add_i32 s83, s83, 2
	s_add_u32 s26, s26, 0x100
	s_addc_u32 s27, s27, 0
	s_add_u32 s21, s21, 0x100
	s_addc_u32 s38, s38, 0
	s_cmp_gt_u32 s83, 61
	s_cbranch_scc0 .LBB0_35
	s_and_b64 vcc, exec, s[16:17]
	s_cbranch_vccz .LBB0_38
	s_barrier

; #define PG8_STAGE(bufoff, gbase, voff) do { _Pragma("unroll") for (int _i = 0; _i < 2; ++_i) \
;         __builtin_amdgcn_global_load_lds((const unsigned*)((const char*)(gbase) + (voff)[_i]), (PG8_LAS unsigned*)(lds + (bufoff) + ldsw + _i * 8192), 16, 0, 0); } while (0)
; #define PG8_LDA(dst, b, h) do { _Pragma("unroll") for (int m = 0; m < 4; ++m) _Pragma("unroll") for (int k = 0; k < 2; ++k) dst[m][k] = *(const PG8_LAS bf16x8*)(lds + PG8_SA(b, h) + aoff + m * 2048 + k * 1024); } while (0)
; #define PG8_LDB(dst, b, h) do { _Pragma("unroll") for (int n = 0; n < 2; ++n) _Pragma("unroll") for (int k = 0; k < 2; ++k) dst[n][k] = *(const PG8_LAS bf16x8*)(lds + PG8_SB(b, h) + boff + n * 2048 + k * 1024); } while (0)
; #define PG8_MMA(ai, bj, At, Bt) do { __builtin_amdgcn_s_setprio(1); _Pragma("unroll") for (int m = 0; m < 4; ++m) _Pragma("unroll") for (int n = 0; n < 2; ++n) _Pragma("unroll") for (int k = 0; k < 2; ++k) \
;         acc[ai][bj][m][n] = __builtin_amdgcn_mfma_f32_16x16x32_bf16(Bt[n][k], At[m][k], acc[ai][bj][m][n], 0, 0, 0); __builtin_amdgcn_s_setprio(0); } while (0)
; #define PG8_WAIT_V(n) asm volatile("s_waitcnt vmcnt(" #n ")" ::: "memory")
; #define PG8_WAIT_L(n) asm volatile("s_waitcnt lgkmcnt(" #n ")" ::: "memory")
; #define PG8_BAR __builtin_amdgcn_s_barrier()
; template <class Epi, class Sched, bool ALIGN_EPI = false, bool SP2 = false>
; __device__ __forceinline__ void gemm_phase(PG8_LAS unsigned char* lds, const Gemm g, const Sched& S, const Epi& E, const int wave_id) {
;     ...
;             const char* a1 = cA + (size_t)(t + 1) * kstep;
;             const char* a2 = last ? nA : cA + (size_t)(t + 2) * kstep; const char* b2 = last ? nB : cB + (size_t)(t + 2) * kstep;
;             const char* a3 = a2 + kstep; const char* b3 = b2 + kstep;
;             if (last && has_next) S.a_ready(nxt);
;             if constexpr (SP2) {
;             PG8_LDB(B0, 0, 0); PG8_LDB(B1, 0, 1); PG8_SCHED; PG8_LDA(At, 0, 0); PG8_STAGE(PG8_SA(1, 1), a1 + hstepA, voffA);
;             PG8_WAIT_V(8); PG8_WAIT_L(0); PG8_BAR; PG8_MMA(0, 0, At, B0); PG8_MMA(0, 1, At, B1); PG8_BAR; PG8_SCHED;
;             PG8_LDA(At, 0, 1); PG8_STAGE(PG8_SB(0, 0), b2, voffB); PG8_STAGE(PG8_SB(0, 1), b2 + hstepB, voffB); PG8_STAGE(PG8_SA(0, 0), a2, voffA);
;             PG8_WAIT_V(8); PG8_WAIT_L(0); PG8_BAR; PG8_MMA(1, 0, At, B0); PG8_MMA(1, 1, At, B1); PG8_BAR; PG8_SCHED;
.LBB0_69:
	s_add_u32 s18, s16, 0xfff00080
	s_addc_u32 s19, s17, -1
	s_add_i32 s39, 0, 0x10000
	s_cmp_eq_u32 s38, 4
	s_cselect_b32 s21, s30, s19
	s_cselect_b32 s20, s31, s18
	v_add_u32_e32 v0, s39, v139
	s_cselect_b32 s19, s34, s37
	s_cselect_b32 s18, s35, s36
	s_add_i32 s50, 0, 0x14000
	ds_read_b128 v[142:145], v0
	ds_read_b128 v[146:149], v0 offset:1024
	ds_read_b128 v[150:153], v0 offset:2048
	ds_read_b128 v[154:157], v0 offset:3072
	v_add_u32_e32 v0, s50, v139
	ds_read_b128 v[158:161], v0
	ds_read_b128 v[162:165], v0 offset:1024
	ds_read_b128 v[166:169], v0 offset:2048
	ds_read_b128 v[178:181], v0 offset:3072
	v_lshl_add_u64 v[214:215], s[16:17], 0, v[134:135]
	s_add_i32 m0, s3, 0xc000
	ds_read_b128 v[182:185], v141
	ds_read_b128 v[186:189], v141 offset:1024
	ds_read_b128 v[190:193], v141 offset:2048
	ds_read_b128 v[194:197], v141 offset:3072
	ds_read_b128 v[198:201], v141 offset:4096
	ds_read_b128 v[202:205], v141 offset:5120
	ds_read_b128 v[206:209], v141 offset:6144
	ds_read_b128 v[210:213], v141 offset:7168
	global_load_lds_dwordx4 v[214:215], off
	v_lshl_add_u64 v[214:215], s[16:17], 0, v[136:137]
	s_add_i32 m0, s3, 0xe000
	s_nop 0
	global_load_lds_dwordx4 v[214:215], off
	s_waitcnt vmcnt(8)
	s_waitcnt lgkmcnt(0)
	s_setprio 1
	s_barrier
	v_mfma_f32_16x16x32_bf16 v[126:129], v[142:145], v[182:185], v[126:129]
	v_mfma_f32_16x16x32_bf16 v[122:125], v[150:153], v[182:185], v[122:125]
	v_mfma_f32_16x16x32_bf16 v[118:121], v[142:145], v[190:193], v[118:121]
	v_mfma_f32_16x16x32_bf16 v[114:117], v[150:153], v[190:193], v[114:117]
	v_mfma_f32_16x16x32_bf16 v[106:109], v[142:145], v[198:201], v[106:109]
	v_mfma_f32_16x16x32_bf16 v[98:101], v[150:153], v[198:201], v[98:101]
	v_mfma_f32_16x16x32_bf16 v[90:93], v[142:145], v[206:209], v[90:93]
	v_mfma_f32_16x16x32_bf16 v[82:85], v[150:153], v[206:209], v[82:85]
	v_mfma_f32_16x16x32_bf16 v[126:129], v[146:149], v[186:189], v[126:129]
	v_mfma_f32_16x16x32_bf16 v[122:125], v[154:157], v[186:189], v[122:125]
	v_mfma_f32_16x16x32_bf16 v[118:121], v[146:149], v[194:197], v[118:121]
	v_mfma_f32_16x16x32_bf16 v[114:117], v[154:157], v[194:197], v[114:117]
	v_mfma_f32_16x16x32_bf16 v[106:109], v[146:149], v[202:205], v[106:109]
	v_mfma_f32_16x16x32_bf16 v[98:101], v[154:157], v[202:205], v[98:101]
	v_mfma_f32_16x16x32_bf16 v[90:93], v[146:149], v[210:213], v[90:93]
	v_mfma_f32_16x16x32_bf16 v[82:85], v[154:157], v[210:213], v[82:85]
	v_mfma_f32_16x16x32_bf16 v[110:113], v[158:161], v[182:185], v[110:113]
	v_mfma_f32_16x16x32_bf16 v[102:105], v[166:169], v[182:185], v[102:105]
	v_mfma_f32_16x16x32_bf16 v[94:97], v[158:161], v[190:193], v[94:97]
	v_mfma_f32_16x16x32_bf16 v[86:89], v[166:169], v[190:193], v[86:89]
	v_mfma_f32_16x16x32_bf16 v[78:81], v[158:161], v[198:201], v[78:81]
	v_mfma_f32_16x16x32_bf16 v[74:77], v[166:169], v[198:201], v[74:77]
	v_mfma_f32_16x16x32_bf16 v[70:73], v[158:161], v[206:209], v[70:73]
	v_mfma_f32_16x16x32_bf16 v[66:69], v[166:169], v[206:209], v[66:69]
	v_mfma_f32_16x16x32_bf16 v[110:113], v[162:165], v[186:189], v[110:113]
	v_mfma_f32_16x16x32_bf16 v[102:105], v[178:181], v[186:189], v[102:105]
	v_mfma_f32_16x16x32_bf16 v[94:97], v[162:165], v[194:197], v[94:97]
	v_mfma_f32_16x16x32_bf16 v[86:89], v[178:181], v[194:197], v[86:89]
	v_mfma_f32_16x16x32_bf16 v[78:81], v[162:165], v[202:205], v[78:81]
	v_mfma_f32_16x16x32_bf16 v[74:77], v[178:181], v[202:205], v[74:77]
	v_mfma_f32_16x16x32_bf16 v[70:73], v[162:165], v[210:213], v[70:73]
	v_mfma_f32_16x16x32_bf16 v[66:69], v[178:181], v[210:213], v[66:69]
	s_barrier
	s_setprio 0
	s_add_i32 s39, s39, s0
	v_lshl_add_u64 v[214:215], s[18:19], 0, v[132:133]
	s_mov_b32 m0, s39
	ds_read_b128 v[182:185], v141 offset:16384
	ds_read_b128 v[186:189], v141 offset:17408
	ds_read_b128 v[190:193], v141 offset:18432
	ds_read_b128 v[194:197], v141 offset:19456
	ds_read_b128 v[198:201], v141 offset:20480
	ds_read_b128 v[202:205], v141 offset:21504
	ds_read_b128 v[206:209], v141 offset:22528
	ds_read_b128 v[210:213], v141 offset:23552
	global_load_lds_dwordx4 v[214:215], off
	s_add_i32 m0, s39, 0x2000
	s_add_u32 s44, s18, 0x100000
	v_lshl_add_u64 v[216:217], s[18:19], 0, v[130:131]
	s_addc_u32 s45, s19, 0
	s_add_i32 s39, s50, s0
	global_load_lds_dwordx4 v[216:217], off
	v_lshl_add_u64 v[218:219], s[44:45], 0, v[132:133]
	s_mov_b32 m0, s39
	v_lshl_add_u64 v[220:221], s[20:21], 0, v[130:131]
	global_load_lds_dwordx4 v[218:219], off
	v_lshl_add_u64 v[218:219], s[44:45], 0, v[130:131]
	s_add_i32 m0, s39, 0x2000
	s_nop 0
	global_load_lds_dwordx4 v[218:219], off
	v_lshl_add_u64 v[218:219], s[20:21], 0, v[132:133]
	s_mov_b32 m0, s3
	s_nop 0
	global_load_lds_dwordx4 v[218:219], off
	s_mov_b32 m0, s15
	s_nop 0
	global_load_lds_dwordx4 v[220:221], off
	s_waitcnt vmcnt(8)
	s_waitcnt lgkmcnt(0)
	s_setprio 1
	s_barrier
; #define PG8_STAGE(bufoff, gbase, voff) do { _Pragma("unroll") for (int _i = 0; _i < 2; ++_i) \
;         __builtin_amdgcn_global_load_lds((const unsigned*)((const char*)(gbase) + (voff)[_i]), (PG8_LAS unsigned*)(lds + (bufoff) + ldsw + _i * 8192), 16, 0, 0); } while (0)
; #define PG8_LDA(dst, b, h) do { _Pragma("unroll") for (int m = 0; m < 4; ++m) _Pragma("unroll") for (int k = 0; k < 2; ++k) dst[m][k] = *(const PG8_LAS bf16x8*)(lds + PG8_SA(b, h) + aoff + m * 2048 + k * 1024); } while (0)
; #define PG8_LDB(dst, b, h) do { _Pragma("unroll") for (int n = 0; n < 2; ++n) _Pragma("unroll") for (int k = 0; k < 2; ++k) dst[n][k] = *(const PG8_LAS bf16x8*)(lds + PG8_SB(b, h) + boff + n * 2048 + k * 1024); } while (0)
; #define PG8_MMA(ai, bj, At, Bt) do { __builtin_amdgcn_s_setprio(1); _Pragma("unroll") for (int m = 0; m < 4; ++m) _Pragma("unroll") for (int n = 0; n < 2; ++n) _Pragma("unroll") for (int k = 0; k < 2; ++k) \
;         acc[ai][bj][m][n] = __builtin_amdgcn_mfma_f32_16x16x32_bf16(Bt[n][k], At[m][k], acc[ai][bj][m][n], 0, 0, 0); __builtin_amdgcn_s_setprio(0); } while (0)
; #define PG8_WAIT_V(n) asm volatile("s_waitcnt vmcnt(" #n ")" ::: "memory")
; #define PG8_WAIT_L(n) asm volatile("s_waitcnt lgkmcnt(" #n ")" ::: "memory")
; #define PG8_BAR __builtin_amdgcn_s_barrier()
; #define PG8_SCHED __builtin_amdgcn_sched_barrier(0)
; template <class Epi, class Sched, bool ALIGN_EPI = false, bool SP2 = false>
; __device__ __forceinline__ void gemm_phase(PG8_LAS unsigned char* lds, const Gemm g, const Sched& S, const Epi& E, const int wave_id) {
;     ...
;             PG8_WAIT_V(8); PG8_WAIT_L(0); PG8_BAR; PG8_MMA(1, 0, At, B0); PG8_MMA(1, 1, At, B1); PG8_BAR; PG8_SCHED;
;             PG8_LDB(B0, 1, 0); PG8_LDB(B1, 1, 1); PG8_SCHED; PG8_LDA(At, 1, 0); PG8_STAGE(PG8_SA(0, 1), a2 + hstepA, voffA);
;             PG8_WAIT_V(8); PG8_WAIT_L(0); PG8_BAR; PG8_MMA(0, 0, At, B0); PG8_MMA(0, 1, At, B1); PG8_BAR; PG8_SCHED;
;             PG8_LDA(At, 1, 1); PG8_STAGE(PG8_SB(1, 0), b3, voffB); PG8_STAGE(PG8_SB(1, 1), b3 + hstepB, voffB); PG8_STAGE(PG8_SA(1, 0), a3, voffA);
	v_mfma_f32_16x16x32_bf16 v[62:65], v[142:145], v[182:185], v[62:65]
	v_mfma_f32_16x16x32_bf16 v[58:61], v[150:153], v[182:185], v[58:61]
	v_mfma_f32_16x16x32_bf16 v[54:57], v[142:145], v[190:193], v[54:57]
	v_mfma_f32_16x16x32_bf16 v[50:53], v[150:153], v[190:193], v[50:53]
	v_mfma_f32_16x16x32_bf16 v[42:45], v[142:145], v[198:201], v[42:45]
	v_mfma_f32_16x16x32_bf16 v[34:37], v[150:153], v[198:201], v[34:37]
	v_mfma_f32_16x16x32_bf16 v[26:29], v[142:145], v[206:209], v[26:29]
	v_mfma_f32_16x16x32_bf16 v[18:21], v[150:153], v[206:209], v[18:21]
	v_mfma_f32_16x16x32_bf16 v[62:65], v[146:149], v[186:189], v[62:65]
	v_mfma_f32_16x16x32_bf16 v[58:61], v[154:157], v[186:189], v[58:61]
	v_mfma_f32_16x16x32_bf16 v[54:57], v[146:149], v[194:197], v[54:57]
	v_mfma_f32_16x16x32_bf16 v[50:53], v[154:157], v[194:197], v[50:53]
	v_mfma_f32_16x16x32_bf16 v[42:45], v[146:149], v[202:205], v[42:45]
	v_mfma_f32_16x16x32_bf16 v[34:37], v[154:157], v[202:205], v[34:37]
	v_mfma_f32_16x16x32_bf16 v[26:29], v[146:149], v[210:213], v[26:29]
	v_mfma_f32_16x16x32_bf16 v[18:21], v[154:157], v[210:213], v[18:21]
	v_mfma_f32_16x16x32_bf16 v[46:49], v[158:161], v[182:185], v[46:49]
	v_mfma_f32_16x16x32_bf16 v[38:41], v[166:169], v[182:185], v[38:41]
	v_mfma_f32_16x16x32_bf16 v[30:33], v[158:161], v[190:193], v[30:33]
	v_mfma_f32_16x16x32_bf16 v[22:25], v[166:169], v[190:193], v[22:25]
	v_mfma_f32_16x16x32_bf16 v[14:17], v[158:161], v[198:201], v[14:17]
	v_mfma_f32_16x16x32_bf16 v[10:13], v[166:169], v[198:201], v[10:13]
	v_mfma_f32_16x16x32_bf16 v[6:9], v[158:161], v[206:209], v[6:9]
	v_mfma_f32_16x16x32_bf16 v[2:5], v[166:169], v[206:209], v[2:5]
	v_mfma_f32_16x16x32_bf16 v[46:49], v[162:165], v[186:189], v[46:49]
	v_mfma_f32_16x16x32_bf16 v[38:41], v[178:181], v[186:189], v[38:41]
	v_mfma_f32_16x16x32_bf16 v[30:33], v[162:165], v[194:197], v[30:33]
	v_mfma_f32_16x16x32_bf16 v[22:25], v[178:181], v[194:197], v[22:25]
	v_mfma_f32_16x16x32_bf16 v[14:17], v[162:165], v[202:205], v[14:17]
	v_mfma_f32_16x16x32_bf16 v[10:13], v[178:181], v[202:205], v[10:13]
	v_mfma_f32_16x16x32_bf16 v[6:9], v[162:165], v[210:213], v[6:9]
	v_mfma_f32_16x16x32_bf16 v[2:5], v[178:181], v[210:213], v[2:5]
	s_barrier
	s_setprio 0
	s_add_i32 s39, 0, 0x18000
	v_add_u32_e32 v0, s39, v139
	s_add_i32 s44, 0, 0x1c000
	ds_read_b128 v[142:145], v0
	ds_read_b128 v[146:149], v0 offset:1024
	ds_read_b128 v[150:153], v0 offset:2048
	ds_read_b128 v[154:157], v0 offset:3072
	v_add_u32_e32 v0, s44, v139
	ds_read_b128 v[158:161], v0
	ds_read_b128 v[162:165], v0 offset:1024
	ds_read_b128 v[166:169], v0 offset:2048
	ds_read_b128 v[178:181], v0 offset:3072
	s_add_u32 s20, s20, 0x100000
	s_addc_u32 s21, s21, 0
	s_mov_b32 m0, s22
	v_lshl_add_u64 v[222:223], s[20:21], 0, v[132:133]
	ds_read_b128 v[182:185], v141 offset:32768
	ds_read_b128 v[186:189], v141 offset:33792
	ds_read_b128 v[190:193], v141 offset:34816
	ds_read_b128 v[194:197], v141 offset:35840
	ds_read_b128 v[198:201], v141 offset:36864
	ds_read_b128 v[202:205], v141 offset:37888
	ds_read_b128 v[206:209], v141 offset:38912
	ds_read_b128 v[210:213], v141 offset:39936
	global_load_lds_dwordx4 v[222:223], off
	v_lshl_add_u64 v[222:223], s[20:21], 0, v[130:131]
	s_mov_b32 m0, s23
	s_nop 0
	global_load_lds_dwordx4 v[222:223], off
	s_waitcnt vmcnt(8)
	s_waitcnt lgkmcnt(0)
	s_setprio 1
	s_barrier
	v_mfma_f32_16x16x32_bf16 v[126:129], v[142:145], v[182:185], v[126:129]
	v_mfma_f32_16x16x32_bf16 v[122:125], v[150:153], v[182:185], v[122:125]
	v_mfma_f32_16x16x32_bf16 v[118:121], v[142:145], v[190:193], v[118:121]
	v_mfma_f32_16x16x32_bf16 v[114:117], v[150:153], v[190:193], v[114:117]
	v_mfma_f32_16x16x32_bf16 v[106:109], v[142:145], v[198:201], v[106:109]
	v_mfma_f32_16x16x32_bf16 v[98:101], v[150:153], v[198:201], v[98:101]
	v_mfma_f32_16x16x32_bf16 v[90:93], v[142:145], v[206:209], v[90:93]
	v_mfma_f32_16x16x32_bf16 v[82:85], v[150:153], v[206:209], v[82:85]
	v_mfma_f32_16x16x32_bf16 v[126:129], v[146:149], v[186:189], v[126:129]
	v_mfma_f32_16x16x32_bf16 v[122:125], v[154:157], v[186:189], v[122:125]
	v_mfma_f32_16x16x32_bf16 v[118:121], v[146:149], v[194:197], v[118:121]
	v_mfma_f32_16x16x32_bf16 v[114:117], v[154:157], v[194:197], v[114:117]
	v_mfma_f32_16x16x32_bf16 v[106:109], v[146:149], v[202:205], v[106:109]
	v_mfma_f32_16x16x32_bf16 v[98:101], v[154:157], v[202:205], v[98:101]
	v_mfma_f32_16x16x32_bf16 v[90:93], v[146:149], v[210:213], v[90:93]
	v_mfma_f32_16x16x32_bf16 v[82:85], v[154:157], v[210:213], v[82:85]
	v_mfma_f32_16x16x32_bf16 v[110:113], v[158:161], v[182:185], v[110:113]
	v_mfma_f32_16x16x32_bf16 v[102:105], v[166:169], v[182:185], v[102:105]
	v_mfma_f32_16x16x32_bf16 v[94:97], v[158:161], v[190:193], v[94:97]
	v_mfma_f32_16x16x32_bf16 v[86:89], v[166:169], v[190:193], v[86:89]
	v_mfma_f32_16x16x32_bf16 v[78:81], v[158:161], v[198:201], v[78:81]
	v_mfma_f32_16x16x32_bf16 v[74:77], v[166:169], v[198:201], v[74:77]
	v_mfma_f32_16x16x32_bf16 v[70:73], v[158:161], v[206:209], v[70:73]
	v_mfma_f32_16x16x32_bf16 v[66:69], v[166:169], v[206:209], v[66:69]
	v_mfma_f32_16x16x32_bf16 v[110:113], v[162:165], v[186:189], v[110:113]
	v_mfma_f32_16x16x32_bf16 v[102:105], v[178:181], v[186:189], v[102:105]
	v_mfma_f32_16x16x32_bf16 v[94:97], v[162:165], v[194:197], v[94:97]
	v_mfma_f32_16x16x32_bf16 v[86:89], v[178:181], v[194:197], v[86:89]
	v_mfma_f32_16x16x32_bf16 v[78:81], v[162:165], v[202:205], v[78:81]
	v_mfma_f32_16x16x32_bf16 v[74:77], v[178:181], v[202:205], v[74:77]
	v_mfma_f32_16x16x32_bf16 v[70:73], v[162:165], v[210:213], v[70:73]
	v_mfma_f32_16x16x32_bf16 v[66:69], v[178:181], v[210:213], v[66:69]
	s_barrier
; #define PG8_STAGE(bufoff, gbase, voff) do { _Pragma("unroll") for (int _i = 0; _i < 2; ++_i) \
;         __builtin_amdgcn_global_load_lds((const unsigned*)((const char*)(gbase) + (voff)[_i]), (PG8_LAS unsigned*)(lds + (bufoff) + ldsw + _i * 8192), 16, 0, 0); } while (0)
; #define PG8_LDA(dst, b, h) do { _Pragma("unroll") for (int m = 0; m < 4; ++m) _Pragma("unroll") for (int k = 0; k < 2; ++k) dst[m][k] = *(const PG8_LAS bf16x8*)(lds + PG8_SA(b, h) + aoff + m * 2048 + k * 1024); } while (0)
; #define PG8_BAR __builtin_amdgcn_s_barrier()
; template <class Epi, class Sched, bool ALIGN_EPI = false, bool SP2 = false>
; __device__ __forceinline__ void gemm_phase(PG8_LAS unsigned char* lds, const Gemm g, const Sched& S, const Epi& E, const int wave_id) {
;     ...
;             PG8_LDA(At, 1, 1); PG8_STAGE(PG8_SB(1, 0), b3, voffB); PG8_STAGE(PG8_SB(1, 1), b3 + hstepB, voffB); PG8_STAGE(PG8_SA(1, 0), a3, voffA);
;             PG8_WAIT_V(8); PG8_WAIT_L(0); PG8_BAR; PG8_MMA(1, 0, At, B0); PG8_MMA(1, 1, At, B1); PG8_BAR; PG8_SCHED;
;             } else {
;             PG8_LDB(B0, 0, 0); PG8_SCHED; PG8_LDA(At, 0, 0); PG8_STAGE(PG8_SA(1, 1), a1 + hstepA, voffA);
;             PG8_WAIT_L(8); PG8_BAR; PG8_WAIT_L(0); PG8_MMA(0, 0, At, B0); PG8_BAR; PG8_SCHED;
;             PG8_LDB(B1, 0, 1); PG8_STAGE(PG8_SB(0, 0), b2, voffB);
;             PG8_BAR; PG8_WAIT_L(0); PG8_MMA(0, 1, At, B1); PG8_BAR;
;             PG8_LDA(At, 0, 1); PG8_STAGE(PG8_SA(0, 0), a2, voffA);
;             PG8_BAR; PG8_WAIT_L(0); PG8_MMA(1, 0, At, B0); PG8_BAR; PG8_SCHED;
;             PG8_STAGE(PG8_SB(0, 1), b2 + hstepB, voffB);
;             PG8_WAIT_V(6); PG8_BAR; PG8_MMA(1, 1, At, B1); PG8_BAR;
;             PG8_LDB(B0, 1, 0); PG8_SCHED; PG8_LDA(At, 1, 0); PG8_STAGE(PG8_SA(0, 1), a2 + hstepA, voffA);
;             PG8_WAIT_L(8); PG8_BAR; PG8_WAIT_L(0); PG8_MMA(0, 0, At, B0); PG8_BAR; PG8_SCHED;
;             PG8_LDB(B1, 1, 1); PG8_STAGE(PG8_SB(1, 0), b3, voffB);
;             PG8_BAR; PG8_WAIT_L(0); PG8_MMA(0, 1, At, B1); PG8_BAR;
;             PG8_LDA(At, 1, 1); PG8_STAGE(PG8_SA(1, 0), a3, voffA);
;             PG8_BAR; PG8_WAIT_L(0); PG8_MMA(1, 0, At, B0); PG8_BAR; PG8_SCHED;
;             PG8_STAGE(PG8_SB(1, 1), b3 + hstepB, voffB);
;             PG8_WAIT_V(6); PG8_BAR; PG8_MMA(1, 1, At, B1); PG8_BAR;
;             }
;         }
;         if constexpr (ALIGN_EPI) { if (wr == 0) PG8_BAR; }
	s_setprio 0
	s_add_i32 s20, s39, s0
	v_lshl_add_u64 v[214:215], v[214:215], 0, s[62:63]
	s_mov_b32 m0, s20
	ds_read_b128 v[182:185], v141 offset:49152
	ds_read_b128 v[186:189], v141 offset:50176
	ds_read_b128 v[190:193], v141 offset:51200
	ds_read_b128 v[194:197], v141 offset:52224
	ds_read_b128 v[198:201], v141 offset:53248
	ds_read_b128 v[202:205], v141 offset:54272
	ds_read_b128 v[206:209], v141 offset:55296
	ds_read_b128 v[210:213], v141 offset:56320
	global_load_lds_dwordx4 v[214:215], off
	s_add_i32 m0, s20, 0x2000
	s_add_u32 s18, s18, 0x100080
	v_lshl_add_u64 v[214:215], v[216:217], 0, s[62:63]
	s_addc_u32 s19, s19, 0
	s_add_i32 s20, s44, s0
	global_load_lds_dwordx4 v[214:215], off
	v_lshl_add_u64 v[214:215], s[18:19], 0, v[132:133]
	s_mov_b32 m0, s20
	s_nop 0
	global_load_lds_dwordx4 v[214:215], off
	v_lshl_add_u64 v[214:215], s[18:19], 0, v[130:131]
	s_add_i32 m0, s20, 0x2000
	s_nop 0
	global_load_lds_dwordx4 v[214:215], off
	v_lshl_add_u64 v[214:215], v[218:219], 0, s[62:63]
	s_mov_b32 m0, s24
	s_nop 0
	global_load_lds_dwordx4 v[214:215], off
	v_lshl_add_u64 v[214:215], v[220:221], 0, s[62:63]
	s_mov_b32 m0, s25
	s_nop 0
	global_load_lds_dwordx4 v[214:215], off
	s_waitcnt vmcnt(8)
	s_waitcnt lgkmcnt(0)
	s_setprio 1
	s_barrier
	v_mfma_f32_16x16x32_bf16 v[62:65], v[142:145], v[182:185], v[62:65]
	v_mfma_f32_16x16x32_bf16 v[58:61], v[150:153], v[182:185], v[58:61]
	v_mfma_f32_16x16x32_bf16 v[54:57], v[142:145], v[190:193], v[54:57]
	v_mfma_f32_16x16x32_bf16 v[50:53], v[150:153], v[190:193], v[50:53]
	v_mfma_f32_16x16x32_bf16 v[42:45], v[142:145], v[198:201], v[42:45]
	v_mfma_f32_16x16x32_bf16 v[34:37], v[150:153], v[198:201], v[34:37]
	v_mfma_f32_16x16x32_bf16 v[26:29], v[142:145], v[206:209], v[26:29]
	v_mfma_f32_16x16x32_bf16 v[18:21], v[150:153], v[206:209], v[18:21]
	v_mfma_f32_16x16x32_bf16 v[62:65], v[146:149], v[186:189], v[62:65]
	v_mfma_f32_16x16x32_bf16 v[58:61], v[154:157], v[186:189], v[58:61]
	v_mfma_f32_16x16x32_bf16 v[54:57], v[146:149], v[194:197], v[54:57]
	v_mfma_f32_16x16x32_bf16 v[50:53], v[154:157], v[194:197], v[50:53]
	v_mfma_f32_16x16x32_bf16 v[42:45], v[146:149], v[202:205], v[42:45]
	v_mfma_f32_16x16x32_bf16 v[34:37], v[154:157], v[202:205], v[34:37]
	v_mfma_f32_16x16x32_bf16 v[26:29], v[146:149], v[210:213], v[26:29]
	v_mfma_f32_16x16x32_bf16 v[18:21], v[154:157], v[210:213], v[18:21]
	v_mfma_f32_16x16x32_bf16 v[46:49], v[158:161], v[182:185], v[46:49]
	v_mfma_f32_16x16x32_bf16 v[38:41], v[166:169], v[182:185], v[38:41]
	v_mfma_f32_16x16x32_bf16 v[30:33], v[158:161], v[190:193], v[30:33]
	v_mfma_f32_16x16x32_bf16 v[22:25], v[166:169], v[190:193], v[22:25]
	v_mfma_f32_16x16x32_bf16 v[14:17], v[158:161], v[198:201], v[14:17]
	v_mfma_f32_16x16x32_bf16 v[10:13], v[166:169], v[198:201], v[10:13]
	v_mfma_f32_16x16x32_bf16 v[6:9], v[158:161], v[206:209], v[6:9]
	v_mfma_f32_16x16x32_bf16 v[2:5], v[166:169], v[206:209], v[2:5]
	v_mfma_f32_16x16x32_bf16 v[46:49], v[162:165], v[186:189], v[46:49]
	v_mfma_f32_16x16x32_bf16 v[38:41], v[178:181], v[186:189], v[38:41]
	v_mfma_f32_16x16x32_bf16 v[30:33], v[162:165], v[194:197], v[30:33]
	v_mfma_f32_16x16x32_bf16 v[22:25], v[178:181], v[194:197], v[22:25]
	v_mfma_f32_16x16x32_bf16 v[14:17], v[162:165], v[202:205], v[14:17]
	v_mfma_f32_16x16x32_bf16 v[10:13], v[178:181], v[202:205], v[10:13]
	v_mfma_f32_16x16x32_bf16 v[6:9], v[162:165], v[210:213], v[6:9]
	v_mfma_f32_16x16x32_bf16 v[2:5], v[178:181], v[210:213], v[2:5]
	s_barrier
	s_setprio 0
	s_add_i32 s38, s38, 2
	s_add_u32 s16, s16, 0x100
	s_addc_u32 s17, s17, 0
	s_add_u32 s36, s36, 0x100
	s_addc_u32 s37, s37, 0
	s_cmp_gt_u32 s38, 5
	s_cbranch_scc0 .LBB0_69
	s_and_b64 vcc, exec, s[10:11]
	s_cbranch_vccz .LBB0_72
	s_barrier

; #define PG8_STAGE(bufoff, gbase, voff) do { _Pragma("unroll") for (int _i = 0; _i < 2; ++_i) \
;         __builtin_amdgcn_global_load_lds((const unsigned*)((const char*)(gbase) + (voff)[_i]), (PG8_LAS unsigned*)(lds + (bufoff) + ldsw + _i * 8192), 16, 0, 0); } while (0)
; #define PG8_LDA(dst, b, h) do { _Pragma("unroll") for (int m = 0; m < 4; ++m) _Pragma("unroll") for (int k = 0; k < 2; ++k) dst[m][k] = *(const PG8_LAS bf16x8*)(lds + PG8_SA(b, h) + aoff + m * 2048 + k * 1024); } while (0)
; #define PG8_MMA(ai, bj, At, Bt) do { __builtin_amdgcn_s_setprio(1); _Pragma("unroll") for (int m = 0; m < 4; ++m) _Pragma("unroll") for (int n = 0; n < 2; ++n) _Pragma("unroll") for (int k = 0; k < 2; ++k) \
;         acc[ai][bj][m][n] = __builtin_amdgcn_mfma_f32_16x16x32_bf16(Bt[n][k], At[m][k], acc[ai][bj][m][n], 0, 0, 0); __builtin_amdgcn_s_setprio(0); } while (0)
; #define PG8_WAIT_V(n) asm volatile("s_waitcnt vmcnt(" #n ")" ::: "memory")
; #define PG8_WAIT_L(n) asm volatile("s_waitcnt lgkmcnt(" #n ")" ::: "memory")
; #define PG8_BAR __builtin_amdgcn_s_barrier()
; #define PG8_SCHED __builtin_amdgcn_sched_barrier(0)
; template <class Epi, class Sched, bool ALIGN_EPI = false, bool SP2 = false>
; __device__ __forceinline__ void gemm_phase(PG8_LAS unsigned char* lds, const Gemm g, const Sched& S, const Epi& E, const int wave_id) {
;     ...
;             PG8_WAIT_V(8); PG8_WAIT_L(0); PG8_BAR; PG8_MMA(0, 0, At, B0); PG8_MMA(0, 1, At, B1); PG8_BAR; PG8_SCHED;
;             PG8_LDA(At, 0, 1); PG8_STAGE(PG8_SB(0, 0), b2, voffB); PG8_STAGE(PG8_SB(0, 1), b2 + hstepB, voffB); PG8_STAGE(PG8_SA(0, 0), a2, voffA);
;             PG8_WAIT_V(8); PG8_WAIT_L(0); PG8_BAR; PG8_MMA(1, 0, At, B0); PG8_MMA(1, 1, At, B1); PG8_BAR; PG8_SCHED;
.Lrw_1:
	s_waitcnt lgkmcnt(0)
	s_setprio 1
	s_barrier
	v_mfma_f32_16x16x32_bf16 v[134:137], v[138:141], v[190:193], v[134:137]
	v_mfma_f32_16x16x32_bf16 v[130:133], v[146:149], v[190:193], v[130:133]
	v_mfma_f32_16x16x32_bf16 v[118:121], v[138:141], v[198:201], v[118:121]
	v_mfma_f32_16x16x32_bf16 v[114:117], v[146:149], v[198:201], v[114:117]
	v_mfma_f32_16x16x32_bf16 v[102:105], v[138:141], v[214:217], v[102:105]
	v_mfma_f32_16x16x32_bf16 v[98:101], v[146:149], v[214:217], v[98:101]
	v_mfma_f32_16x16x32_bf16 v[86:89], v[138:141], v[222:225], v[86:89]
	v_mfma_f32_16x16x32_bf16 v[82:85], v[146:149], v[222:225], v[82:85]
	v_mfma_f32_16x16x32_bf16 v[134:137], v[142:145], v[194:197], v[134:137]
	v_mfma_f32_16x16x32_bf16 v[130:133], v[150:153], v[194:197], v[130:133]
	v_mfma_f32_16x16x32_bf16 v[118:121], v[142:145], v[210:213], v[118:121]
	v_mfma_f32_16x16x32_bf16 v[114:117], v[150:153], v[210:213], v[114:117]
	v_mfma_f32_16x16x32_bf16 v[102:105], v[142:145], v[218:221], v[102:105]
	v_mfma_f32_16x16x32_bf16 v[98:101], v[150:153], v[218:221], v[98:101]
	v_mfma_f32_16x16x32_bf16 v[86:89], v[142:145], v[234:237], v[86:89]
	v_mfma_f32_16x16x32_bf16 v[82:85], v[150:153], v[234:237], v[82:85]
	v_mfma_f32_16x16x32_bf16 v[126:129], v[154:157], v[190:193], v[126:129]
	v_mfma_f32_16x16x32_bf16 v[122:125], v[162:165], v[190:193], v[122:125]
	v_mfma_f32_16x16x32_bf16 v[110:113], v[154:157], v[198:201], v[110:113]
	v_mfma_f32_16x16x32_bf16 v[106:109], v[162:165], v[198:201], v[106:109]
	v_mfma_f32_16x16x32_bf16 v[94:97], v[154:157], v[214:217], v[94:97]
	v_mfma_f32_16x16x32_bf16 v[90:93], v[162:165], v[214:217], v[90:93]
	v_mfma_f32_16x16x32_bf16 v[78:81], v[154:157], v[222:225], v[78:81]
	v_mfma_f32_16x16x32_bf16 v[74:77], v[162:165], v[222:225], v[74:77]
	v_mfma_f32_16x16x32_bf16 v[126:129], v[158:161], v[194:197], v[126:129]
	v_mfma_f32_16x16x32_bf16 v[122:125], v[166:169], v[194:197], v[122:125]
	v_mfma_f32_16x16x32_bf16 v[110:113], v[158:161], v[210:213], v[110:113]
	v_mfma_f32_16x16x32_bf16 v[106:109], v[166:169], v[210:213], v[106:109]
	v_mfma_f32_16x16x32_bf16 v[94:97], v[158:161], v[218:221], v[94:97]
	v_mfma_f32_16x16x32_bf16 v[90:93], v[166:169], v[218:221], v[90:93]
	v_mfma_f32_16x16x32_bf16 v[78:81], v[158:161], v[234:237], v[78:81]
	v_mfma_f32_16x16x32_bf16 v[74:77], v[166:169], v[234:237], v[74:77]
	s_barrier
	s_setprio 0
	s_add_i32 s10, s37, s15
	v_lshl_add_u64 v[240:241], s[28:29], 0, v[180:181]
	s_mov_b32 m0, s10
	ds_read_b128 v[190:193], v208 offset:16384
	ds_read_b128 v[194:197], v208 offset:17408
	ds_read_b128 v[198:201], v208 offset:18432
	ds_read_b128 v[210:213], v208 offset:19456
	ds_read_b128 v[214:217], v208 offset:20480
	ds_read_b128 v[218:221], v208 offset:21504
	ds_read_b128 v[222:225], v208 offset:22528
	ds_read_b128 v[234:237], v208 offset:23552
	global_load_lds_dwordx4 v[240:241], off
	s_add_i32 m0, s10, 0x2000
	s_add_u32 s10, s28, 0x40000
	v_lshl_add_u64 v[242:243], s[28:29], 0, v[184:185]
	s_addc_u32 s11, s29, 0
	s_add_i32 s37, s39, s15
	global_load_lds_dwordx4 v[242:243], off
	v_lshl_add_u64 v[244:245], s[10:11], 0, v[180:181]
	s_mov_b32 m0, s37
	v_lshl_add_u64 v[246:247], s[30:31], 0, v[182:183]
	global_load_lds_dwordx4 v[244:245], off
	v_lshl_add_u64 v[244:245], s[10:11], 0, v[184:185]
	s_add_i32 m0, s37, 0x2000
	s_nop 0
	global_load_lds_dwordx4 v[244:245], off
	v_lshl_add_u64 v[244:245], s[30:31], 0, v[178:179]
	s_mov_b32 m0, s27
	s_nop 0
	global_load_lds_dwordx4 v[244:245], off
	s_mov_b32 m0, s34
	s_nop 0
	global_load_lds_dwordx4 v[246:247], off
	s_waitcnt vmcnt(24)
	s_cmp_eq_u32 s98, 1
	s_cbranch_scc1 .Lrw_2
	s_waitcnt vmcnt(8)
.Lrw_2:
	s_mov_b32 s98, 0
	s_waitcnt lgkmcnt(0)
	s_setprio 1
	s_barrier
	v_mfma_f32_16x16x32_bf16 v[70:73], v[138:141], v[190:193], v[70:73]
	v_mfma_f32_16x16x32_bf16 v[66:69], v[146:149], v[190:193], v[66:69]
	v_mfma_f32_16x16x32_bf16 v[54:57], v[138:141], v[198:201], v[54:57]
	v_mfma_f32_16x16x32_bf16 v[50:53], v[146:149], v[198:201], v[50:53]
	v_mfma_f32_16x16x32_bf16 v[38:41], v[138:141], v[214:217], v[38:41]
	v_mfma_f32_16x16x32_bf16 v[34:37], v[146:149], v[214:217], v[34:37]
	v_mfma_f32_16x16x32_bf16 v[22:25], v[138:141], v[222:225], v[22:25]
	v_mfma_f32_16x16x32_bf16 v[18:21], v[146:149], v[222:225], v[18:21]
	v_mfma_f32_16x16x32_bf16 v[70:73], v[142:145], v[194:197], v[70:73]
	v_mfma_f32_16x16x32_bf16 v[66:69], v[150:153], v[194:197], v[66:69]
	v_mfma_f32_16x16x32_bf16 v[54:57], v[142:145], v[210:213], v[54:57]
	v_mfma_f32_16x16x32_bf16 v[50:53], v[150:153], v[210:213], v[50:53]
	v_mfma_f32_16x16x32_bf16 v[38:41], v[142:145], v[218:221], v[38:41]
	v_mfma_f32_16x16x32_bf16 v[34:37], v[150:153], v[218:221], v[34:37]
	v_mfma_f32_16x16x32_bf16 v[22:25], v[142:145], v[234:237], v[22:25]
	v_mfma_f32_16x16x32_bf16 v[18:21], v[150:153], v[234:237], v[18:21]
	v_mfma_f32_16x16x32_bf16 v[62:65], v[154:157], v[190:193], v[62:65]
	v_mfma_f32_16x16x32_bf16 v[58:61], v[162:165], v[190:193], v[58:61]
	v_mfma_f32_16x16x32_bf16 v[46:49], v[154:157], v[198:201], v[46:49]
	v_mfma_f32_16x16x32_bf16 v[42:45], v[162:165], v[198:201], v[42:45]
	v_mfma_f32_16x16x32_bf16 v[30:33], v[154:157], v[214:217], v[30:33]
	v_mfma_f32_16x16x32_bf16 v[26:29], v[162:165], v[214:217], v[26:29]
	v_mfma_f32_16x16x32_bf16 v[14:17], v[154:157], v[222:225], v[14:17]
	v_mfma_f32_16x16x32_bf16 v[10:13], v[162:165], v[222:225], v[10:13]
	v_mfma_f32_16x16x32_bf16 v[62:65], v[158:161], v[194:197], v[62:65]
	v_mfma_f32_16x16x32_bf16 v[58:61], v[166:169], v[194:197], v[58:61]
	v_mfma_f32_16x16x32_bf16 v[46:49], v[158:161], v[210:213], v[46:49]
	v_mfma_f32_16x16x32_bf16 v[42:45], v[166:169], v[210:213], v[42:45]
	v_mfma_f32_16x16x32_bf16 v[30:33], v[158:161], v[218:221], v[30:33]
	v_mfma_f32_16x16x32_bf16 v[26:29], v[166:169], v[218:221], v[26:29]
	v_mfma_f32_16x16x32_bf16 v[14:17], v[158:161], v[234:237], v[14:17]
	v_mfma_f32_16x16x32_bf16 v[10:13], v[166:169], v[234:237], v[10:13]
	s_barrier
; #define PG8_STAGE(bufoff, gbase, voff) do { _Pragma("unroll") for (int _i = 0; _i < 2; ++_i) \
;         __builtin_amdgcn_global_load_lds((const unsigned*)((const char*)(gbase) + (voff)[_i]), (PG8_LAS unsigned*)(lds + (bufoff) + ldsw + _i * 8192), 16, 0, 0); } while (0)
; #define PG8_LDA(dst, b, h) do { _Pragma("unroll") for (int m = 0; m < 4; ++m) _Pragma("unroll") for (int k = 0; k < 2; ++k) dst[m][k] = *(const PG8_LAS bf16x8*)(lds + PG8_SA(b, h) + aoff + m * 2048 + k * 1024); } while (0)
; #define PG8_LDB(dst, b, h) do { _Pragma("unroll") for (int n = 0; n < 2; ++n) _Pragma("unroll") for (int k = 0; k < 2; ++k) dst[n][k] = *(const PG8_LAS bf16x8*)(lds + PG8_SB(b, h) + boff + n * 2048 + k * 1024); } while (0)
; #define PG8_MMA(ai, bj, At, Bt) do { __builtin_amdgcn_s_setprio(1); _Pragma("unroll") for (int m = 0; m < 4; ++m) _Pragma("unroll") for (int n = 0; n < 2; ++n) _Pragma("unroll") for (int k = 0; k < 2; ++k) \
;         acc[ai][bj][m][n] = __builtin_amdgcn_mfma_f32_16x16x32_bf16(Bt[n][k], At[m][k], acc[ai][bj][m][n], 0, 0, 0); __builtin_amdgcn_s_setprio(0); } while (0)
; #define PG8_WAIT_V(n) asm volatile("s_waitcnt vmcnt(" #n ")" ::: "memory")
; #define PG8_WAIT_L(n) asm volatile("s_waitcnt lgkmcnt(" #n ")" ::: "memory")
; #define PG8_BAR __builtin_amdgcn_s_barrier()
; #define PG8_SCHED __builtin_amdgcn_sched_barrier(0)
; template <class Epi, class Sched, bool ALIGN_EPI = false, bool SP2 = false>
; __device__ __forceinline__ void gemm_phase(PG8_LAS unsigned char* lds, const Gemm g, const Sched& S, const Epi& E, const int wave_id) {
;     ...
;             PG8_WAIT_V(8); PG8_WAIT_L(0); PG8_BAR; PG8_MMA(1, 0, At, B0); PG8_MMA(1, 1, At, B1); PG8_BAR; PG8_SCHED;
;             PG8_LDB(B0, 1, 0); PG8_LDB(B1, 1, 1); PG8_SCHED; PG8_LDA(At, 1, 0); PG8_STAGE(PG8_SA(0, 1), a2 + hstepA, voffA);
;             PG8_WAIT_V(8); PG8_WAIT_L(0); PG8_BAR; PG8_MMA(0, 0, At, B0); PG8_MMA(0, 1, At, B1); PG8_BAR; PG8_SCHED;
	s_setprio 0
	s_add_i32 s37, 0, 0x18000
	v_add_u32_e32 v0, s37, v203
	s_add_i32 s39, 0, 0x1c000
	ds_read_b128 v[138:141], v0
	ds_read_b128 v[142:145], v0 offset:1024
	ds_read_b128 v[146:149], v0 offset:2048
	ds_read_b128 v[150:153], v0 offset:3072
	v_add_u32_e32 v0, s39, v203
	ds_read_b128 v[154:157], v0
	ds_read_b128 v[158:161], v0 offset:1024
	ds_read_b128 v[162:165], v0 offset:2048
	ds_read_b128 v[166:169], v0 offset:3072
	s_add_u32 s10, s30, 0x40000
	s_addc_u32 s11, s31, 0
	s_mov_b32 m0, s35
	v_lshl_add_u64 v[248:249], s[10:11], 0, v[178:179]
	ds_read_b128 v[190:193], v208 offset:32768
	ds_read_b128 v[194:197], v208 offset:33792
	ds_read_b128 v[198:201], v208 offset:34816
	ds_read_b128 v[210:213], v208 offset:35840
	ds_read_b128 v[214:217], v208 offset:36864
	ds_read_b128 v[218:221], v208 offset:37888
	ds_read_b128 v[222:225], v208 offset:38912
	ds_read_b128 v[234:237], v208 offset:39936
	global_load_lds_dwordx4 v[248:249], off
	v_lshl_add_u64 v[248:249], s[10:11], 0, v[182:183]
	s_mov_b32 m0, s36
	s_nop 0
	global_load_lds_dwordx4 v[248:249], off
	s_waitcnt vmcnt(8)
	s_waitcnt lgkmcnt(0)
	s_setprio 1
	s_barrier
	v_mfma_f32_16x16x32_bf16 v[134:137], v[138:141], v[190:193], v[134:137]
	v_mfma_f32_16x16x32_bf16 v[130:133], v[146:149], v[190:193], v[130:133]
	v_mfma_f32_16x16x32_bf16 v[118:121], v[138:141], v[198:201], v[118:121]
	v_mfma_f32_16x16x32_bf16 v[114:117], v[146:149], v[198:201], v[114:117]
	v_mfma_f32_16x16x32_bf16 v[102:105], v[138:141], v[214:217], v[102:105]
	v_mfma_f32_16x16x32_bf16 v[98:101], v[146:149], v[214:217], v[98:101]
	v_mfma_f32_16x16x32_bf16 v[86:89], v[138:141], v[222:225], v[86:89]
	v_mfma_f32_16x16x32_bf16 v[82:85], v[146:149], v[222:225], v[82:85]
	v_mfma_f32_16x16x32_bf16 v[134:137], v[142:145], v[194:197], v[134:137]
	v_mfma_f32_16x16x32_bf16 v[130:133], v[150:153], v[194:197], v[130:133]
	v_mfma_f32_16x16x32_bf16 v[118:121], v[142:145], v[210:213], v[118:121]
	v_mfma_f32_16x16x32_bf16 v[114:117], v[150:153], v[210:213], v[114:117]
	v_mfma_f32_16x16x32_bf16 v[102:105], v[142:145], v[218:221], v[102:105]
	v_mfma_f32_16x16x32_bf16 v[98:101], v[150:153], v[218:221], v[98:101]
	v_mfma_f32_16x16x32_bf16 v[86:89], v[142:145], v[234:237], v[86:89]
	v_mfma_f32_16x16x32_bf16 v[82:85], v[150:153], v[234:237], v[82:85]
	v_mfma_f32_16x16x32_bf16 v[126:129], v[154:157], v[190:193], v[126:129]
	v_mfma_f32_16x16x32_bf16 v[122:125], v[162:165], v[190:193], v[122:125]
	v_mfma_f32_16x16x32_bf16 v[110:113], v[154:157], v[198:201], v[110:113]
	v_mfma_f32_16x16x32_bf16 v[106:109], v[162:165], v[198:201], v[106:109]
	v_mfma_f32_16x16x32_bf16 v[94:97], v[154:157], v[214:217], v[94:97]
	v_mfma_f32_16x16x32_bf16 v[90:93], v[162:165], v[214:217], v[90:93]
	v_mfma_f32_16x16x32_bf16 v[78:81], v[154:157], v[222:225], v[78:81]
	v_mfma_f32_16x16x32_bf16 v[74:77], v[162:165], v[222:225], v[74:77]
	v_mfma_f32_16x16x32_bf16 v[126:129], v[158:161], v[194:197], v[126:129]
	v_mfma_f32_16x16x32_bf16 v[122:125], v[166:169], v[194:197], v[122:125]
	v_mfma_f32_16x16x32_bf16 v[110:113], v[158:161], v[210:213], v[110:113]
	v_mfma_f32_16x16x32_bf16 v[106:109], v[166:169], v[210:213], v[106:109]
	v_mfma_f32_16x16x32_bf16 v[94:97], v[158:161], v[218:221], v[94:97]
	v_mfma_f32_16x16x32_bf16 v[90:93], v[166:169], v[218:221], v[90:93]
	v_mfma_f32_16x16x32_bf16 v[78:81], v[158:161], v[234:237], v[78:81]
	v_mfma_f32_16x16x32_bf16 v[74:77], v[166:169], v[234:237], v[74:77]
	s_barrier
; #define PG8_STAGE(bufoff, gbase, voff) do { _Pragma("unroll") for (int _i = 0; _i < 2; ++_i) \
;         __builtin_amdgcn_global_load_lds((const unsigned*)((const char*)(gbase) + (voff)[_i]), (PG8_LAS unsigned*)(lds + (bufoff) + ldsw + _i * 8192), 16, 0, 0); } while (0)
; #define PG8_LDA(dst, b, h) do { _Pragma("unroll") for (int m = 0; m < 4; ++m) _Pragma("unroll") for (int k = 0; k < 2; ++k) dst[m][k] = *(const PG8_LAS bf16x8*)(lds + PG8_SA(b, h) + aoff + m * 2048 + k * 1024); } while (0)
; #define PG8_MMA(ai, bj, At, Bt) do { __builtin_amdgcn_s_setprio(1); _Pragma("unroll") for (int m = 0; m < 4; ++m) _Pragma("unroll") for (int n = 0; n < 2; ++n) _Pragma("unroll") for (int k = 0; k < 2; ++k) \
;         acc[ai][bj][m][n] = __builtin_amdgcn_mfma_f32_16x16x32_bf16(Bt[n][k], At[m][k], acc[ai][bj][m][n], 0, 0, 0); __builtin_amdgcn_s_setprio(0); } while (0)
; #define PG8_WAIT_V(n) asm volatile("s_waitcnt vmcnt(" #n ")" ::: "memory")
; #define PG8_WAIT_L(n) asm volatile("s_waitcnt lgkmcnt(" #n ")" ::: "memory")
; #define PG8_BAR __builtin_amdgcn_s_barrier()
; #define PG8_SCHED __builtin_amdgcn_sched_barrier(0)
; template <class Epi, class Sched, bool ALIGN_EPI = false, bool SP2 = false>
; __device__ __forceinline__ void gemm_phase(PG8_LAS unsigned char* lds, const Gemm g, const Sched& S, const Epi& E, const int wave_id) {
;     ...
;         for (int t = 0; t < nt; t += 2) {
;             const bool last = (t == nt - 2);
;     ...
;             PG8_LDA(At, 1, 1); PG8_STAGE(PG8_SB(1, 0), b3, voffB); PG8_STAGE(PG8_SB(1, 1), b3 + hstepB, voffB); PG8_STAGE(PG8_SA(1, 0), a3, voffA);
;             PG8_WAIT_V(8); PG8_WAIT_L(0); PG8_BAR; PG8_MMA(1, 0, At, B0); PG8_MMA(1, 1, At, B1); PG8_BAR; PG8_SCHED;
	s_setprio 0
	s_add_i32 s10, s37, s15
	v_lshl_add_u64 v[240:241], v[240:241], 0, s[62:63]
	s_mov_b32 m0, s10
	ds_read_b128 v[190:193], v208 offset:49152
	ds_read_b128 v[194:197], v208 offset:50176
	ds_read_b128 v[198:201], v208 offset:51200
	ds_read_b128 v[210:213], v208 offset:52224
	ds_read_b128 v[214:217], v208 offset:53248
	ds_read_b128 v[218:221], v208 offset:54272
	ds_read_b128 v[222:225], v208 offset:55296
	ds_read_b128 v[234:237], v208 offset:56320
	global_load_lds_dwordx4 v[240:241], off
	s_add_i32 m0, s10, 0x2000
	s_add_u32 s10, s28, 0x40080
	v_lshl_add_u64 v[240:241], v[242:243], 0, s[62:63]
	s_addc_u32 s11, s29, 0
	s_add_i32 s28, s39, s15
	global_load_lds_dwordx4 v[240:241], off
	v_lshl_add_u64 v[240:241], s[10:11], 0, v[180:181]
	s_mov_b32 m0, s28
	s_nop 0
	global_load_lds_dwordx4 v[240:241], off
	v_lshl_add_u64 v[240:241], s[10:11], 0, v[184:185]
	s_add_i32 m0, s28, 0x2000
	s_nop 0
	global_load_lds_dwordx4 v[240:241], off
	v_lshl_add_u64 v[240:241], v[244:245], 0, s[62:63]
	s_mov_b32 m0, s76
	s_nop 0
	global_load_lds_dwordx4 v[240:241], off
	v_lshl_add_u64 v[240:241], v[246:247], 0, s[62:63]
	s_mov_b32 m0, s77
	s_nop 0
	global_load_lds_dwordx4 v[240:241], off
	s_waitcnt vmcnt(8)
	s_waitcnt lgkmcnt(0)
	s_setprio 1
	s_barrier
	v_mfma_f32_16x16x32_bf16 v[70:73], v[138:141], v[190:193], v[70:73]
	v_mfma_f32_16x16x32_bf16 v[66:69], v[146:149], v[190:193], v[66:69]
	v_mfma_f32_16x16x32_bf16 v[54:57], v[138:141], v[198:201], v[54:57]
	v_mfma_f32_16x16x32_bf16 v[50:53], v[146:149], v[198:201], v[50:53]
	v_mfma_f32_16x16x32_bf16 v[38:41], v[138:141], v[214:217], v[38:41]
	v_mfma_f32_16x16x32_bf16 v[34:37], v[146:149], v[214:217], v[34:37]
	v_mfma_f32_16x16x32_bf16 v[22:25], v[138:141], v[222:225], v[22:25]
	v_mfma_f32_16x16x32_bf16 v[18:21], v[146:149], v[222:225], v[18:21]
	v_mfma_f32_16x16x32_bf16 v[70:73], v[142:145], v[194:197], v[70:73]
	v_mfma_f32_16x16x32_bf16 v[66:69], v[150:153], v[194:197], v[66:69]
	v_mfma_f32_16x16x32_bf16 v[54:57], v[142:145], v[210:213], v[54:57]
	v_mfma_f32_16x16x32_bf16 v[50:53], v[150:153], v[210:213], v[50:53]
	v_mfma_f32_16x16x32_bf16 v[38:41], v[142:145], v[218:221], v[38:41]
	v_mfma_f32_16x16x32_bf16 v[34:37], v[150:153], v[218:221], v[34:37]
	v_mfma_f32_16x16x32_bf16 v[22:25], v[142:145], v[234:237], v[22:25]
	v_mfma_f32_16x16x32_bf16 v[18:21], v[150:153], v[234:237], v[18:21]
	v_mfma_f32_16x16x32_bf16 v[62:65], v[154:157], v[190:193], v[62:65]
	v_mfma_f32_16x16x32_bf16 v[58:61], v[162:165], v[190:193], v[58:61]
	v_mfma_f32_16x16x32_bf16 v[46:49], v[154:157], v[198:201], v[46:49]
	v_mfma_f32_16x16x32_bf16 v[42:45], v[162:165], v[198:201], v[42:45]
	v_mfma_f32_16x16x32_bf16 v[30:33], v[154:157], v[214:217], v[30:33]
	v_mfma_f32_16x16x32_bf16 v[26:29], v[162:165], v[214:217], v[26:29]
	v_mfma_f32_16x16x32_bf16 v[14:17], v[154:157], v[222:225], v[14:17]
	v_mfma_f32_16x16x32_bf16 v[10:13], v[162:165], v[222:225], v[10:13]
	v_mfma_f32_16x16x32_bf16 v[62:65], v[158:161], v[194:197], v[62:65]
	v_mfma_f32_16x16x32_bf16 v[58:61], v[166:169], v[194:197], v[58:61]
	v_mfma_f32_16x16x32_bf16 v[46:49], v[158:161], v[210:213], v[46:49]
	v_mfma_f32_16x16x32_bf16 v[42:45], v[166:169], v[210:213], v[42:45]
	v_mfma_f32_16x16x32_bf16 v[30:33], v[158:161], v[218:221], v[30:33]
	v_mfma_f32_16x16x32_bf16 v[26:29], v[166:169], v[218:221], v[26:29]
	v_mfma_f32_16x16x32_bf16 v[14:17], v[158:161], v[234:237], v[14:17]
	v_mfma_f32_16x16x32_bf16 v[10:13], v[166:169], v[234:237], v[10:13]
	s_barrier
	s_setprio 0
	s_add_i32 s5, s5, 2
	s_add_u32 s8, s8, 0x100
	s_addc_u32 s9, s9, 0
	s_add_u32 s38, s38, 0x100
	s_addc_u32 s4, s4, 0
	s_cmp_gt_u32 s5, 13
	s_cbranch_scc0 .LBB0_90

; #define PG8_STAGE(bufoff, gbase, voff) do { _Pragma("unroll") for (int _i = 0; _i < 2; ++_i) \
;         __builtin_amdgcn_global_load_lds((const unsigned*)((const char*)(gbase) + (voff)[_i]), (PG8_LAS unsigned*)(lds + (bufoff) + ldsw + _i * 8192), 16, 0, 0); } while (0)
; #define PG8_LDA(dst, b, h) do { _Pragma("unroll") for (int m = 0; m < 4; ++m) _Pragma("unroll") for (int k = 0; k < 2; ++k) dst[m][k] = *(const PG8_LAS bf16x8*)(lds + PG8_SA(b, h) + aoff + m * 2048 + k * 1024); } while (0)
; #define PG8_LDB(dst, b, h) do { _Pragma("unroll") for (int n = 0; n < 2; ++n) _Pragma("unroll") for (int k = 0; k < 2; ++k) dst[n][k] = *(const PG8_LAS bf16x8*)(lds + PG8_SB(b, h) + boff + n * 2048 + k * 1024); } while (0)
; #define PG8_MMA(ai, bj, At, Bt) do { __builtin_amdgcn_s_setprio(1); _Pragma("unroll") for (int m = 0; m < 4; ++m) _Pragma("unroll") for (int n = 0; n < 2; ++n) _Pragma("unroll") for (int k = 0; k < 2; ++k) \
;         acc[ai][bj][m][n] = __builtin_amdgcn_mfma_f32_16x16x32_bf16(Bt[n][k], At[m][k], acc[ai][bj][m][n], 0, 0, 0); __builtin_amdgcn_s_setprio(0); } while (0)
; #define PG8_WAIT_V(n) asm volatile("s_waitcnt vmcnt(" #n ")" ::: "memory")
; #define PG8_WAIT_L(n) asm volatile("s_waitcnt lgkmcnt(" #n ")" ::: "memory")
; #define PG8_BAR __builtin_amdgcn_s_barrier()
; template <class Epi, class Sched, bool ALIGN_EPI = false, bool SP2 = false>
; __device__ __forceinline__ void gemm_phase(PG8_LAS unsigned char* lds, const Gemm g, const Sched& S, const Epi& E, const int wave_id) {
;     ...
;             const char* a1 = cA + (size_t)(t + 1) * kstep;
;             const char* a2 = last ? nA : cA + (size_t)(t + 2) * kstep; const char* b2 = last ? nB : cB + (size_t)(t + 2) * kstep;
;             const char* a3 = a2 + kstep; const char* b3 = b2 + kstep;
;             if (last && has_next) S.a_ready(nxt);
;             if constexpr (SP2) {
;             PG8_LDB(B0, 0, 0); PG8_LDB(B1, 0, 1); PG8_SCHED; PG8_LDA(At, 0, 0); PG8_STAGE(PG8_SA(1, 1), a1 + hstepA, voffA);
;             PG8_WAIT_V(8); PG8_WAIT_L(0); PG8_BAR; PG8_MMA(0, 0, At, B0); PG8_MMA(0, 1, At, B1); PG8_BAR; PG8_SCHED;
;             PG8_LDA(At, 0, 1); PG8_STAGE(PG8_SB(0, 0), b2, voffB); PG8_STAGE(PG8_SB(0, 1), b2 + hstepB, voffB); PG8_STAGE(PG8_SA(0, 0), a2, voffA);
;             PG8_WAIT_V(8); PG8_WAIT_L(0); PG8_BAR; PG8_MMA(1, 0, At, B0); PG8_MMA(1, 1, At, B1); PG8_BAR; PG8_SCHED;
.LBB0_189:
	s_add_u32 s10, s12, 0x100
	s_addc_u32 s11, s13, 0
	s_add_i32 s39, 0, 0x10000
	s_cmp_eq_u32 vcc_lo, 28
	s_cselect_b32 s31, s25, s11
	s_cselect_b32 s30, s24, s10
	v_add_u32_e32 v0, s39, v206
	s_cselect_b32 s29, s23, s91
	s_cselect_b32 s28, s87, s38
	s_add_i32 vcc_hi, 0, 0x14000
	ds_read_b128 v[122:125], v0
	ds_read_b128 v[134:137], v0 offset:1024
	ds_read_b128 v[138:141], v0 offset:2048
	ds_read_b128 v[142:145], v0 offset:3072
	v_add_u32_e32 v0, vcc_hi, v206
	ds_read_b128 v[146:149], v0
	ds_read_b128 v[150:153], v0 offset:1024
	ds_read_b128 v[154:157], v0 offset:2048
	ds_read_b128 v[158:161], v0 offset:3072
	v_lshl_add_u64 v[222:223], s[12:13], 0, v[178:179]
	s_add_i32 m0, s17, 0xc000
	ds_read_b128 v[182:185], v212
	ds_read_b128 v[186:189], v212 offset:1024
	ds_read_b128 v[190:193], v212 offset:2048
	ds_read_b128 v[194:197], v212 offset:3072
	ds_read_b128 v[198:201], v212 offset:4096
	ds_read_b128 v[202:205], v212 offset:5120
	ds_read_b128 v[214:217], v212 offset:6144
	ds_read_b128 v[218:221], v212 offset:7168
	global_load_lds_dwordx4 v[222:223], off
	v_lshl_add_u64 v[222:223], s[12:13], 0, v[180:181]
	s_add_i32 m0, s17, 0xe000
	s_nop 0
	global_load_lds_dwordx4 v[222:223], off
	s_waitcnt vmcnt(8)
	s_waitcnt lgkmcnt(0)
	s_setprio 1
	s_barrier
	v_mfma_f32_16x16x32_bf16 v[130:133], v[122:125], v[182:185], v[130:133]
	v_mfma_f32_16x16x32_bf16 v[126:129], v[138:141], v[182:185], v[126:129]
	v_mfma_f32_16x16x32_bf16 v[110:113], v[122:125], v[190:193], v[110:113]
	v_mfma_f32_16x16x32_bf16 v[106:109], v[138:141], v[190:193], v[106:109]
	v_mfma_f32_16x16x32_bf16 v[94:97], v[122:125], v[198:201], v[94:97]
	v_mfma_f32_16x16x32_bf16 v[90:93], v[138:141], v[198:201], v[90:93]
	v_mfma_f32_16x16x32_bf16 v[78:81], v[122:125], v[214:217], v[78:81]
	v_mfma_f32_16x16x32_bf16 v[74:77], v[138:141], v[214:217], v[74:77]
	v_mfma_f32_16x16x32_bf16 v[130:133], v[134:137], v[186:189], v[130:133]
	v_mfma_f32_16x16x32_bf16 v[126:129], v[142:145], v[186:189], v[126:129]
	v_mfma_f32_16x16x32_bf16 v[110:113], v[134:137], v[194:197], v[110:113]
	v_mfma_f32_16x16x32_bf16 v[106:109], v[142:145], v[194:197], v[106:109]
	v_mfma_f32_16x16x32_bf16 v[94:97], v[134:137], v[202:205], v[94:97]
	v_mfma_f32_16x16x32_bf16 v[90:93], v[142:145], v[202:205], v[90:93]
	v_mfma_f32_16x16x32_bf16 v[78:81], v[134:137], v[218:221], v[78:81]
	v_mfma_f32_16x16x32_bf16 v[74:77], v[142:145], v[218:221], v[74:77]
	v_mfma_f32_16x16x32_bf16 v[118:121], v[146:149], v[182:185], v[118:121]
	v_mfma_f32_16x16x32_bf16 v[114:117], v[154:157], v[182:185], v[114:117]
	v_mfma_f32_16x16x32_bf16 v[102:105], v[146:149], v[190:193], v[102:105]
	v_mfma_f32_16x16x32_bf16 v[98:101], v[154:157], v[190:193], v[98:101]
	v_mfma_f32_16x16x32_bf16 v[86:89], v[146:149], v[198:201], v[86:89]
	v_mfma_f32_16x16x32_bf16 v[82:85], v[154:157], v[198:201], v[82:85]
	v_mfma_f32_16x16x32_bf16 v[70:73], v[146:149], v[214:217], v[70:73]
	v_mfma_f32_16x16x32_bf16 v[66:69], v[154:157], v[214:217], v[66:69]
	v_mfma_f32_16x16x32_bf16 v[118:121], v[150:153], v[186:189], v[118:121]
	v_mfma_f32_16x16x32_bf16 v[114:117], v[158:161], v[186:189], v[114:117]
	v_mfma_f32_16x16x32_bf16 v[102:105], v[150:153], v[194:197], v[102:105]
	v_mfma_f32_16x16x32_bf16 v[98:101], v[158:161], v[194:197], v[98:101]
	v_mfma_f32_16x16x32_bf16 v[86:89], v[150:153], v[202:205], v[86:89]
	v_mfma_f32_16x16x32_bf16 v[82:85], v[158:161], v[202:205], v[82:85]
	v_mfma_f32_16x16x32_bf16 v[70:73], v[150:153], v[218:221], v[70:73]
	v_mfma_f32_16x16x32_bf16 v[66:69], v[158:161], v[218:221], v[66:69]
	s_barrier
	s_setprio 0
	s_add_i32 s12, s39, s35
	v_lshl_add_u64 v[222:223], s[28:29], 0, v[164:165]
	s_mov_b32 m0, s12
	ds_read_b128 v[182:185], v212 offset:16384
	ds_read_b128 v[186:189], v212 offset:17408
	ds_read_b128 v[190:193], v212 offset:18432
	ds_read_b128 v[194:197], v212 offset:19456
	ds_read_b128 v[198:201], v212 offset:20480
	ds_read_b128 v[202:205], v212 offset:21504
	ds_read_b128 v[214:217], v212 offset:22528
	ds_read_b128 v[218:221], v212 offset:23552
	global_load_lds_dwordx4 v[222:223], off
	s_add_i32 m0, s12, 0x2000
	s_add_u32 s12, s28, 0x80000
	v_lshl_add_u64 v[224:225], s[28:29], 0, v[168:169]
	s_addc_u32 s13, s29, 0
	s_add_i32 s39, vcc_hi, s35
	global_load_lds_dwordx4 v[224:225], off
	v_lshl_add_u64 v[234:235], s[12:13], 0, v[164:165]
	s_mov_b32 m0, s39
	v_lshl_add_u64 v[236:237], s[30:31], 0, v[166:167]
	global_load_lds_dwordx4 v[234:235], off
	v_lshl_add_u64 v[234:235], s[12:13], 0, v[168:169]
	s_add_i32 m0, s39, 0x2000
	s_nop 0
	global_load_lds_dwordx4 v[234:235], off
	v_lshl_add_u64 v[234:235], s[30:31], 0, v[162:163]
	s_mov_b32 m0, s17
	s_nop 0
	global_load_lds_dwordx4 v[234:235], off
	s_mov_b32 m0, s36
	s_nop 0
	global_load_lds_dwordx4 v[236:237], off
	s_waitcnt vmcnt(8)
	s_waitcnt lgkmcnt(0)
	s_setprio 1
	s_barrier
; #define PG8_STAGE(bufoff, gbase, voff) do { _Pragma("unroll") for (int _i = 0; _i < 2; ++_i) \
;         __builtin_amdgcn_global_load_lds((const unsigned*)((const char*)(gbase) + (voff)[_i]), (PG8_LAS unsigned*)(lds + (bufoff) + ldsw + _i * 8192), 16, 0, 0); } while (0)
; #define PG8_LDA(dst, b, h) do { _Pragma("unroll") for (int m = 0; m < 4; ++m) _Pragma("unroll") for (int k = 0; k < 2; ++k) dst[m][k] = *(const PG8_LAS bf16x8*)(lds + PG8_SA(b, h) + aoff + m * 2048 + k * 1024); } while (0)
; #define PG8_LDB(dst, b, h) do { _Pragma("unroll") for (int n = 0; n < 2; ++n) _Pragma("unroll") for (int k = 0; k < 2; ++k) dst[n][k] = *(const PG8_LAS bf16x8*)(lds + PG8_SB(b, h) + boff + n * 2048 + k * 1024); } while (0)
; #define PG8_MMA(ai, bj, At, Bt) do { __builtin_amdgcn_s_setprio(1); _Pragma("unroll") for (int m = 0; m < 4; ++m) _Pragma("unroll") for (int n = 0; n < 2; ++n) _Pragma("unroll") for (int k = 0; k < 2; ++k) \
;         acc[ai][bj][m][n] = __builtin_amdgcn_mfma_f32_16x16x32_bf16(Bt[n][k], At[m][k], acc[ai][bj][m][n], 0, 0, 0); __builtin_amdgcn_s_setprio(0); } while (0)
; #define PG8_WAIT_V(n) asm volatile("s_waitcnt vmcnt(" #n ")" ::: "memory")
; #define PG8_WAIT_L(n) asm volatile("s_waitcnt lgkmcnt(" #n ")" ::: "memory")
; #define PG8_BAR __builtin_amdgcn_s_barrier()
; #define PG8_SCHED __builtin_amdgcn_sched_barrier(0)
; template <class Epi, class Sched, bool ALIGN_EPI = false, bool SP2 = false>
; __device__ __forceinline__ void gemm_phase(PG8_LAS unsigned char* lds, const Gemm g, const Sched& S, const Epi& E, const int wave_id) {
;     ...
;             PG8_WAIT_V(8); PG8_WAIT_L(0); PG8_BAR; PG8_MMA(1, 0, At, B0); PG8_MMA(1, 1, At, B1); PG8_BAR; PG8_SCHED;
;             PG8_LDB(B0, 1, 0); PG8_LDB(B1, 1, 1); PG8_SCHED; PG8_LDA(At, 1, 0); PG8_STAGE(PG8_SA(0, 1), a2 + hstepA, voffA);
;             PG8_WAIT_V(8); PG8_WAIT_L(0); PG8_BAR; PG8_MMA(0, 0, At, B0); PG8_MMA(0, 1, At, B1); PG8_BAR; PG8_SCHED;
;             PG8_LDA(At, 1, 1); PG8_STAGE(PG8_SB(1, 0), b3, voffB); PG8_STAGE(PG8_SB(1, 1), b3 + hstepB, voffB); PG8_STAGE(PG8_SA(1, 0), a3, voffA);
	v_mfma_f32_16x16x32_bf16 v[62:65], v[122:125], v[182:185], v[62:65]
	v_mfma_f32_16x16x32_bf16 v[58:61], v[138:141], v[182:185], v[58:61]
	v_mfma_f32_16x16x32_bf16 v[46:49], v[122:125], v[190:193], v[46:49]
	v_mfma_f32_16x16x32_bf16 v[42:45], v[138:141], v[190:193], v[42:45]
	v_mfma_f32_16x16x32_bf16 v[30:33], v[122:125], v[198:201], v[30:33]
	v_mfma_f32_16x16x32_bf16 v[26:29], v[138:141], v[198:201], v[26:29]
	v_mfma_f32_16x16x32_bf16 v[14:17], v[122:125], v[214:217], v[14:17]
	v_mfma_f32_16x16x32_bf16 v[10:13], v[138:141], v[214:217], v[10:13]
	v_mfma_f32_16x16x32_bf16 v[62:65], v[134:137], v[186:189], v[62:65]
	v_mfma_f32_16x16x32_bf16 v[58:61], v[142:145], v[186:189], v[58:61]
	v_mfma_f32_16x16x32_bf16 v[46:49], v[134:137], v[194:197], v[46:49]
	v_mfma_f32_16x16x32_bf16 v[42:45], v[142:145], v[194:197], v[42:45]
	v_mfma_f32_16x16x32_bf16 v[30:33], v[134:137], v[202:205], v[30:33]
	v_mfma_f32_16x16x32_bf16 v[26:29], v[142:145], v[202:205], v[26:29]
	v_mfma_f32_16x16x32_bf16 v[14:17], v[134:137], v[218:221], v[14:17]
	v_mfma_f32_16x16x32_bf16 v[10:13], v[142:145], v[218:221], v[10:13]
	v_mfma_f32_16x16x32_bf16 v[54:57], v[146:149], v[182:185], v[54:57]
	v_mfma_f32_16x16x32_bf16 v[50:53], v[154:157], v[182:185], v[50:53]
	v_mfma_f32_16x16x32_bf16 v[38:41], v[146:149], v[190:193], v[38:41]
	v_mfma_f32_16x16x32_bf16 v[34:37], v[154:157], v[190:193], v[34:37]
	v_mfma_f32_16x16x32_bf16 v[22:25], v[146:149], v[198:201], v[22:25]
	v_mfma_f32_16x16x32_bf16 v[18:21], v[154:157], v[198:201], v[18:21]
	v_mfma_f32_16x16x32_bf16 v[6:9], v[146:149], v[214:217], v[6:9]
	v_mfma_f32_16x16x32_bf16 v[2:5], v[154:157], v[214:217], v[2:5]
	v_mfma_f32_16x16x32_bf16 v[54:57], v[150:153], v[186:189], v[54:57]
	v_mfma_f32_16x16x32_bf16 v[50:53], v[158:161], v[186:189], v[50:53]
	v_mfma_f32_16x16x32_bf16 v[38:41], v[150:153], v[194:197], v[38:41]
	v_mfma_f32_16x16x32_bf16 v[34:37], v[158:161], v[194:197], v[34:37]
	v_mfma_f32_16x16x32_bf16 v[22:25], v[150:153], v[202:205], v[22:25]
	v_mfma_f32_16x16x32_bf16 v[18:21], v[158:161], v[202:205], v[18:21]
	v_mfma_f32_16x16x32_bf16 v[6:9], v[150:153], v[218:221], v[6:9]
	v_mfma_f32_16x16x32_bf16 v[2:5], v[158:161], v[218:221], v[2:5]
	s_barrier
	s_setprio 0
	s_add_i32 s39, 0, 0x18000
	v_add_u32_e32 v0, s39, v206
	s_add_i32 vcc_hi, 0, 0x1c000
	ds_read_b128 v[122:125], v0
	ds_read_b128 v[134:137], v0 offset:1024
	ds_read_b128 v[138:141], v0 offset:2048
	ds_read_b128 v[142:145], v0 offset:3072
	v_add_u32_e32 v0, vcc_hi, v206
	ds_read_b128 v[146:149], v0
	ds_read_b128 v[150:153], v0 offset:1024
	ds_read_b128 v[154:157], v0 offset:2048
	ds_read_b128 v[158:161], v0 offset:3072
	s_add_u32 s12, s30, 0x180000
	s_addc_u32 s13, s31, 0
	s_mov_b32 m0, s37
	v_lshl_add_u64 v[240:241], s[12:13], 0, v[162:163]
	ds_read_b128 v[182:185], v212 offset:32768
	ds_read_b128 v[186:189], v212 offset:33792
	ds_read_b128 v[190:193], v212 offset:34816
	ds_read_b128 v[194:197], v212 offset:35840
	ds_read_b128 v[198:201], v212 offset:36864
	ds_read_b128 v[202:205], v212 offset:37888
	ds_read_b128 v[214:217], v212 offset:38912
	ds_read_b128 v[218:221], v212 offset:39936
	global_load_lds_dwordx4 v[240:241], off
	v_lshl_add_u64 v[240:241], s[12:13], 0, v[166:167]
	s_mov_b32 m0, s76
	s_nop 0
	global_load_lds_dwordx4 v[240:241], off
	s_waitcnt vmcnt(8)
	s_waitcnt lgkmcnt(0)
	s_setprio 1
	s_barrier
	v_mfma_f32_16x16x32_bf16 v[130:133], v[122:125], v[182:185], v[130:133]
	v_mfma_f32_16x16x32_bf16 v[126:129], v[138:141], v[182:185], v[126:129]
	v_mfma_f32_16x16x32_bf16 v[110:113], v[122:125], v[190:193], v[110:113]
	v_mfma_f32_16x16x32_bf16 v[106:109], v[138:141], v[190:193], v[106:109]
	v_mfma_f32_16x16x32_bf16 v[94:97], v[122:125], v[198:201], v[94:97]
	v_mfma_f32_16x16x32_bf16 v[90:93], v[138:141], v[198:201], v[90:93]
	v_mfma_f32_16x16x32_bf16 v[78:81], v[122:125], v[214:217], v[78:81]
	v_mfma_f32_16x16x32_bf16 v[74:77], v[138:141], v[214:217], v[74:77]
	v_mfma_f32_16x16x32_bf16 v[130:133], v[134:137], v[186:189], v[130:133]
	v_mfma_f32_16x16x32_bf16 v[126:129], v[142:145], v[186:189], v[126:129]
	v_mfma_f32_16x16x32_bf16 v[110:113], v[134:137], v[194:197], v[110:113]
	v_mfma_f32_16x16x32_bf16 v[106:109], v[142:145], v[194:197], v[106:109]
	v_mfma_f32_16x16x32_bf16 v[94:97], v[134:137], v[202:205], v[94:97]
	v_mfma_f32_16x16x32_bf16 v[90:93], v[142:145], v[202:205], v[90:93]
	v_mfma_f32_16x16x32_bf16 v[78:81], v[134:137], v[218:221], v[78:81]
	v_mfma_f32_16x16x32_bf16 v[74:77], v[142:145], v[218:221], v[74:77]
	v_mfma_f32_16x16x32_bf16 v[118:121], v[146:149], v[182:185], v[118:121]
	v_mfma_f32_16x16x32_bf16 v[114:117], v[154:157], v[182:185], v[114:117]
	v_mfma_f32_16x16x32_bf16 v[102:105], v[146:149], v[190:193], v[102:105]
	v_mfma_f32_16x16x32_bf16 v[98:101], v[154:157], v[190:193], v[98:101]
	v_mfma_f32_16x16x32_bf16 v[86:89], v[146:149], v[198:201], v[86:89]
	v_mfma_f32_16x16x32_bf16 v[82:85], v[154:157], v[198:201], v[82:85]
	v_mfma_f32_16x16x32_bf16 v[70:73], v[146:149], v[214:217], v[70:73]
	v_mfma_f32_16x16x32_bf16 v[66:69], v[154:157], v[214:217], v[66:69]
	v_mfma_f32_16x16x32_bf16 v[118:121], v[150:153], v[186:189], v[118:121]
	v_mfma_f32_16x16x32_bf16 v[114:117], v[158:161], v[186:189], v[114:117]
	v_mfma_f32_16x16x32_bf16 v[102:105], v[150:153], v[194:197], v[102:105]
	v_mfma_f32_16x16x32_bf16 v[98:101], v[158:161], v[194:197], v[98:101]
	v_mfma_f32_16x16x32_bf16 v[86:89], v[150:153], v[202:205], v[86:89]
	v_mfma_f32_16x16x32_bf16 v[82:85], v[158:161], v[202:205], v[82:85]
	v_mfma_f32_16x16x32_bf16 v[70:73], v[150:153], v[218:221], v[70:73]
	v_mfma_f32_16x16x32_bf16 v[66:69], v[158:161], v[218:221], v[66:69]
	s_barrier
; #define PG8_STAGE(bufoff, gbase, voff) do { _Pragma("unroll") for (int _i = 0; _i < 2; ++_i) \
;         __builtin_amdgcn_global_load_lds((const unsigned*)((const char*)(gbase) + (voff)[_i]), (PG8_LAS unsigned*)(lds + (bufoff) + ldsw + _i * 8192), 16, 0, 0); } while (0)
; #define PG8_LDA(dst, b, h) do { _Pragma("unroll") for (int m = 0; m < 4; ++m) _Pragma("unroll") for (int k = 0; k < 2; ++k) dst[m][k] = *(const PG8_LAS bf16x8*)(lds + PG8_SA(b, h) + aoff + m * 2048 + k * 1024); } while (0)
; #define PG8_BAR __builtin_amdgcn_s_barrier()
; template <class Epi, class Sched, bool ALIGN_EPI = false, bool SP2 = false>
; __device__ __forceinline__ void gemm_phase(PG8_LAS unsigned char* lds, const Gemm g, const Sched& S, const Epi& E, const int wave_id) {
;     ...
;             PG8_LDA(At, 1, 1); PG8_STAGE(PG8_SB(1, 0), b3, voffB); PG8_STAGE(PG8_SB(1, 1), b3 + hstepB, voffB); PG8_STAGE(PG8_SA(1, 0), a3, voffA);
;             PG8_WAIT_V(8); PG8_WAIT_L(0); PG8_BAR; PG8_MMA(1, 0, At, B0); PG8_MMA(1, 1, At, B1); PG8_BAR; PG8_SCHED;
;             } else {
;             PG8_LDB(B0, 0, 0); PG8_SCHED; PG8_LDA(At, 0, 0); PG8_STAGE(PG8_SA(1, 1), a1 + hstepA, voffA);
;             PG8_WAIT_L(8); PG8_BAR; PG8_WAIT_L(0); PG8_MMA(0, 0, At, B0); PG8_BAR; PG8_SCHED;
;             PG8_LDB(B1, 0, 1); PG8_STAGE(PG8_SB(0, 0), b2, voffB);
;             PG8_BAR; PG8_WAIT_L(0); PG8_MMA(0, 1, At, B1); PG8_BAR;
;             PG8_LDA(At, 0, 1); PG8_STAGE(PG8_SA(0, 0), a2, voffA);
;             PG8_BAR; PG8_WAIT_L(0); PG8_MMA(1, 0, At, B0); PG8_BAR; PG8_SCHED;
;             PG8_STAGE(PG8_SB(0, 1), b2 + hstepB, voffB);
;             PG8_WAIT_V(6); PG8_BAR; PG8_MMA(1, 1, At, B1); PG8_BAR;
;             PG8_LDB(B0, 1, 0); PG8_SCHED; PG8_LDA(At, 1, 0); PG8_STAGE(PG8_SA(0, 1), a2 + hstepA, voffA);
;             PG8_WAIT_L(8); PG8_BAR; PG8_WAIT_L(0); PG8_MMA(0, 0, At, B0); PG8_BAR; PG8_SCHED;
;             PG8_LDB(B1, 1, 1); PG8_STAGE(PG8_SB(1, 0), b3, voffB);
;             PG8_BAR; PG8_WAIT_L(0); PG8_MMA(0, 1, At, B1); PG8_BAR;
;             PG8_LDA(At, 1, 1); PG8_STAGE(PG8_SA(1, 0), a3, voffA);
;             PG8_BAR; PG8_WAIT_L(0); PG8_MMA(1, 0, At, B0); PG8_BAR; PG8_SCHED;
;             PG8_STAGE(PG8_SB(1, 1), b3 + hstepB, voffB);
;             PG8_WAIT_V(6); PG8_BAR; PG8_MMA(1, 1, At, B1); PG8_BAR;
;             }
;         }
;         if constexpr (ALIGN_EPI) { if (wr == 0) PG8_BAR; }
	s_setprio 0
	s_add_i32 s12, s39, s35
	v_lshl_add_u64 v[222:223], v[222:223], 0, s[62:63]
	s_mov_b32 m0, s12
	ds_read_b128 v[182:185], v212 offset:49152
	ds_read_b128 v[186:189], v212 offset:50176
	ds_read_b128 v[190:193], v212 offset:51200
	ds_read_b128 v[194:197], v212 offset:52224
	ds_read_b128 v[198:201], v212 offset:53248
	ds_read_b128 v[202:205], v212 offset:54272
	ds_read_b128 v[214:217], v212 offset:55296
	ds_read_b128 v[218:221], v212 offset:56320
	global_load_lds_dwordx4 v[222:223], off
	s_add_i32 m0, s12, 0x2000
	s_add_u32 s12, s28, 0x80080
	v_lshl_add_u64 v[222:223], v[224:225], 0, s[62:63]
	s_addc_u32 s13, s29, 0
	s_add_i32 s28, vcc_hi, s35
	global_load_lds_dwordx4 v[222:223], off
	v_lshl_add_u64 v[222:223], s[12:13], 0, v[164:165]
	s_mov_b32 m0, s28
	s_nop 0
	global_load_lds_dwordx4 v[222:223], off
	v_lshl_add_u64 v[222:223], s[12:13], 0, v[168:169]
	s_add_i32 m0, s28, 0x2000
	s_nop 0
	global_load_lds_dwordx4 v[222:223], off
	v_lshl_add_u64 v[222:223], v[234:235], 0, s[62:63]
	s_mov_b32 m0, s80
	s_nop 0
	global_load_lds_dwordx4 v[222:223], off
	v_lshl_add_u64 v[222:223], v[236:237], 0, s[62:63]
	s_mov_b32 m0, s81
	s_nop 0
	global_load_lds_dwordx4 v[222:223], off
	s_waitcnt vmcnt(8)
	s_waitcnt lgkmcnt(0)
	s_setprio 1
	s_barrier
	v_mfma_f32_16x16x32_bf16 v[62:65], v[122:125], v[182:185], v[62:65]
	v_mfma_f32_16x16x32_bf16 v[58:61], v[138:141], v[182:185], v[58:61]
	v_mfma_f32_16x16x32_bf16 v[46:49], v[122:125], v[190:193], v[46:49]
	v_mfma_f32_16x16x32_bf16 v[42:45], v[138:141], v[190:193], v[42:45]
	v_mfma_f32_16x16x32_bf16 v[30:33], v[122:125], v[198:201], v[30:33]
	v_mfma_f32_16x16x32_bf16 v[26:29], v[138:141], v[198:201], v[26:29]
	v_mfma_f32_16x16x32_bf16 v[14:17], v[122:125], v[214:217], v[14:17]
	v_mfma_f32_16x16x32_bf16 v[10:13], v[138:141], v[214:217], v[10:13]
	v_mfma_f32_16x16x32_bf16 v[62:65], v[134:137], v[186:189], v[62:65]
	v_mfma_f32_16x16x32_bf16 v[58:61], v[142:145], v[186:189], v[58:61]
	v_mfma_f32_16x16x32_bf16 v[46:49], v[134:137], v[194:197], v[46:49]
	v_mfma_f32_16x16x32_bf16 v[42:45], v[142:145], v[194:197], v[42:45]
	v_mfma_f32_16x16x32_bf16 v[30:33], v[134:137], v[202:205], v[30:33]
	v_mfma_f32_16x16x32_bf16 v[26:29], v[142:145], v[202:205], v[26:29]
	v_mfma_f32_16x16x32_bf16 v[14:17], v[134:137], v[218:221], v[14:17]
	v_mfma_f32_16x16x32_bf16 v[10:13], v[142:145], v[218:221], v[10:13]
	v_mfma_f32_16x16x32_bf16 v[54:57], v[146:149], v[182:185], v[54:57]
	v_mfma_f32_16x16x32_bf16 v[50:53], v[154:157], v[182:185], v[50:53]
	v_mfma_f32_16x16x32_bf16 v[38:41], v[146:149], v[190:193], v[38:41]
	v_mfma_f32_16x16x32_bf16 v[34:37], v[154:157], v[190:193], v[34:37]
	v_mfma_f32_16x16x32_bf16 v[22:25], v[146:149], v[198:201], v[22:25]
	v_mfma_f32_16x16x32_bf16 v[18:21], v[154:157], v[198:201], v[18:21]
	v_mfma_f32_16x16x32_bf16 v[6:9], v[146:149], v[214:217], v[6:9]
	v_mfma_f32_16x16x32_bf16 v[2:5], v[154:157], v[214:217], v[2:5]
	v_mfma_f32_16x16x32_bf16 v[54:57], v[150:153], v[186:189], v[54:57]
	v_mfma_f32_16x16x32_bf16 v[50:53], v[158:161], v[186:189], v[50:53]
	v_mfma_f32_16x16x32_bf16 v[38:41], v[150:153], v[194:197], v[38:41]
	v_mfma_f32_16x16x32_bf16 v[34:37], v[158:161], v[194:197], v[34:37]
	v_mfma_f32_16x16x32_bf16 v[22:25], v[150:153], v[202:205], v[22:25]
	v_mfma_f32_16x16x32_bf16 v[18:21], v[158:161], v[202:205], v[18:21]
	v_mfma_f32_16x16x32_bf16 v[6:9], v[150:153], v[218:221], v[6:9]
	v_mfma_f32_16x16x32_bf16 v[2:5], v[158:161], v[218:221], v[2:5]
	s_barrier
	s_setprio 0
	s_add_i32 vcc_lo, vcc_lo, 2
	s_add_u32 s38, s38, 0x100
	s_addc_u32 s91, s91, 0
	s_cmp_gt_u32 vcc_lo, 29
	s_mov_b64 s[12:13], s[10:11]
	s_cbranch_scc0 .LBB0_189
	s_and_b64 vcc, exec, s[20:21]
	s_cbranch_vccz .LBB0_192
	s_barrier

; #define PG8_STAGE(bufoff, gbase, voff) do { _Pragma("unroll") for (int _i = 0; _i < 2; ++_i) \
;         __builtin_amdgcn_global_load_lds((const unsigned*)((const char*)(gbase) + (voff)[_i]), (PG8_LAS unsigned*)(lds + (bufoff) + ldsw + _i * 8192), 16, 0, 0); } while (0)
; #define PG8_LDA(dst, b, h) do { _Pragma("unroll") for (int m = 0; m < 4; ++m) _Pragma("unroll") for (int k = 0; k < 2; ++k) dst[m][k] = *(const PG8_LAS bf16x8*)(lds + PG8_SA(b, h) + aoff + m * 2048 + k * 1024); } while (0)
; #define PG8_LDB(dst, b, h) do { _Pragma("unroll") for (int n = 0; n < 2; ++n) _Pragma("unroll") for (int k = 0; k < 2; ++k) dst[n][k] = *(const PG8_LAS bf16x8*)(lds + PG8_SB(b, h) + boff + n * 2048 + k * 1024); } while (0)
; #define PG8_MMA(ai, bj, At, Bt) do { __builtin_amdgcn_s_setprio(1); _Pragma("unroll") for (int m = 0; m < 4; ++m) _Pragma("unroll") for (int n = 0; n < 2; ++n) _Pragma("unroll") for (int k = 0; k < 2; ++k) \
;         acc[ai][bj][m][n] = __builtin_amdgcn_mfma_f32_16x16x32_bf16(Bt[n][k], At[m][k], acc[ai][bj][m][n], 0, 0, 0); __builtin_amdgcn_s_setprio(0); } while (0)
; #define PG8_WAIT_V(n) asm volatile("s_waitcnt vmcnt(" #n ")" ::: "memory")
; #define PG8_WAIT_L(n) asm volatile("s_waitcnt lgkmcnt(" #n ")" ::: "memory")
; #define PG8_BAR __builtin_amdgcn_s_barrier()
; template <class Epi, class Sched, bool ALIGN_EPI = false, bool SP2 = false>
; __device__ __forceinline__ void gemm_phase(PG8_LAS unsigned char* lds, const Gemm g, const Sched& S, const Epi& E, const int wave_id) {
;     ...
;             const char* a1 = cA + (size_t)(t + 1) * kstep;
;             const char* a2 = last ? nA : cA + (size_t)(t + 2) * kstep; const char* b2 = last ? nB : cB + (size_t)(t + 2) * kstep;
;             const char* a3 = a2 + kstep; const char* b3 = b2 + kstep;
;             if (last && has_next) S.a_ready(nxt);
;             if constexpr (SP2) {
;             PG8_LDB(B0, 0, 0); PG8_LDB(B1, 0, 1); PG8_SCHED; PG8_LDA(At, 0, 0); PG8_STAGE(PG8_SA(1, 1), a1 + hstepA, voffA);
;             PG8_WAIT_V(8); PG8_WAIT_L(0); PG8_BAR; PG8_MMA(0, 0, At, B0); PG8_MMA(0, 1, At, B1); PG8_BAR; PG8_SCHED;
;             PG8_LDA(At, 0, 1); PG8_STAGE(PG8_SB(0, 0), b2, voffB); PG8_STAGE(PG8_SB(0, 1), b2 + hstepB, voffB); PG8_STAGE(PG8_SA(0, 0), a2, voffA);
;             PG8_WAIT_V(8); PG8_WAIT_L(0); PG8_BAR; PG8_MMA(1, 0, At, B0); PG8_MMA(1, 1, At, B1); PG8_BAR; PG8_SCHED;
.LBB0_297:
	s_add_u32 s12, s10, 0xfffc0080
	s_addc_u32 s13, s11, -1
	s_add_i32 s20, 0, 0x10000
	s_cmp_eq_u32 vcc_lo, 12
	s_cselect_b32 s35, s15, s13
	s_cselect_b32 s34, s27, s12
	v_add_u32_e32 v0, s20, v206
	s_cselect_b32 s13, s25, s38
	s_cselect_b32 s12, s36, s37
	s_add_i32 vcc_hi, 0, 0x14000
	ds_read_b128 v[122:125], v0
	ds_read_b128 v[134:137], v0 offset:1024
	ds_read_b128 v[138:141], v0 offset:2048
	ds_read_b128 v[142:145], v0 offset:3072
	v_add_u32_e32 v0, vcc_hi, v206
	ds_read_b128 v[146:149], v0
	ds_read_b128 v[150:153], v0 offset:1024
	ds_read_b128 v[154:157], v0 offset:2048
	ds_read_b128 v[158:161], v0 offset:3072
	v_lshl_add_u64 v[222:223], s[10:11], 0, v[178:179]
	s_add_i32 m0, s17, 0xc000
	ds_read_b128 v[182:185], v212
	ds_read_b128 v[186:189], v212 offset:1024
	ds_read_b128 v[190:193], v212 offset:2048
	ds_read_b128 v[194:197], v212 offset:3072
	ds_read_b128 v[198:201], v212 offset:4096
	ds_read_b128 v[202:205], v212 offset:5120
	ds_read_b128 v[214:217], v212 offset:6144
	ds_read_b128 v[218:221], v212 offset:7168
	global_load_lds_dwordx4 v[222:223], off
	v_lshl_add_u64 v[222:223], s[10:11], 0, v[180:181]
	s_add_i32 m0, s17, 0xe000
	s_nop 0
	global_load_lds_dwordx4 v[222:223], off
	s_waitcnt vmcnt(8)
	s_waitcnt lgkmcnt(0)
	s_setprio 1
	s_barrier
	v_mfma_f32_16x16x32_bf16 v[130:133], v[122:125], v[182:185], v[130:133]
	v_mfma_f32_16x16x32_bf16 v[126:129], v[138:141], v[182:185], v[126:129]
	v_mfma_f32_16x16x32_bf16 v[110:113], v[122:125], v[190:193], v[110:113]
	v_mfma_f32_16x16x32_bf16 v[106:109], v[138:141], v[190:193], v[106:109]
	v_mfma_f32_16x16x32_bf16 v[94:97], v[122:125], v[198:201], v[94:97]
	v_mfma_f32_16x16x32_bf16 v[90:93], v[138:141], v[198:201], v[90:93]
	v_mfma_f32_16x16x32_bf16 v[78:81], v[122:125], v[214:217], v[78:81]
	v_mfma_f32_16x16x32_bf16 v[74:77], v[138:141], v[214:217], v[74:77]
	v_mfma_f32_16x16x32_bf16 v[130:133], v[134:137], v[186:189], v[130:133]
	v_mfma_f32_16x16x32_bf16 v[126:129], v[142:145], v[186:189], v[126:129]
	v_mfma_f32_16x16x32_bf16 v[110:113], v[134:137], v[194:197], v[110:113]
	v_mfma_f32_16x16x32_bf16 v[106:109], v[142:145], v[194:197], v[106:109]
	v_mfma_f32_16x16x32_bf16 v[94:97], v[134:137], v[202:205], v[94:97]
	v_mfma_f32_16x16x32_bf16 v[90:93], v[142:145], v[202:205], v[90:93]
	v_mfma_f32_16x16x32_bf16 v[78:81], v[134:137], v[218:221], v[78:81]
	v_mfma_f32_16x16x32_bf16 v[74:77], v[142:145], v[218:221], v[74:77]
	v_mfma_f32_16x16x32_bf16 v[118:121], v[146:149], v[182:185], v[118:121]
	v_mfma_f32_16x16x32_bf16 v[114:117], v[154:157], v[182:185], v[114:117]
	v_mfma_f32_16x16x32_bf16 v[102:105], v[146:149], v[190:193], v[102:105]
	v_mfma_f32_16x16x32_bf16 v[98:101], v[154:157], v[190:193], v[98:101]
	v_mfma_f32_16x16x32_bf16 v[86:89], v[146:149], v[198:201], v[86:89]
	v_mfma_f32_16x16x32_bf16 v[82:85], v[154:157], v[198:201], v[82:85]
	v_mfma_f32_16x16x32_bf16 v[70:73], v[146:149], v[214:217], v[70:73]
	v_mfma_f32_16x16x32_bf16 v[66:69], v[154:157], v[214:217], v[66:69]
	v_mfma_f32_16x16x32_bf16 v[118:121], v[150:153], v[186:189], v[118:121]
	v_mfma_f32_16x16x32_bf16 v[114:117], v[158:161], v[186:189], v[114:117]
	v_mfma_f32_16x16x32_bf16 v[102:105], v[150:153], v[194:197], v[102:105]
	v_mfma_f32_16x16x32_bf16 v[98:101], v[158:161], v[194:197], v[98:101]
	v_mfma_f32_16x16x32_bf16 v[86:89], v[150:153], v[202:205], v[86:89]
	v_mfma_f32_16x16x32_bf16 v[82:85], v[158:161], v[202:205], v[82:85]
	v_mfma_f32_16x16x32_bf16 v[70:73], v[150:153], v[218:221], v[70:73]
	v_mfma_f32_16x16x32_bf16 v[66:69], v[158:161], v[218:221], v[66:69]
	s_barrier
	s_setprio 0
	s_add_i32 s20, s20, s76
	v_lshl_add_u64 v[222:223], s[12:13], 0, v[164:165]
	s_mov_b32 m0, s20
	ds_read_b128 v[182:185], v212 offset:16384
	ds_read_b128 v[186:189], v212 offset:17408
	ds_read_b128 v[190:193], v212 offset:18432
	ds_read_b128 v[194:197], v212 offset:19456
	ds_read_b128 v[198:201], v212 offset:20480
	ds_read_b128 v[202:205], v212 offset:21504
	ds_read_b128 v[214:217], v212 offset:22528
	ds_read_b128 v[218:221], v212 offset:23552
	global_load_lds_dwordx4 v[222:223], off
	s_add_i32 m0, s20, 0x2000
	s_add_u32 s20, s12, 0x40000
	v_lshl_add_u64 v[224:225], s[12:13], 0, v[168:169]
	s_addc_u32 s21, s13, 0
	s_add_i32 vcc_hi, vcc_hi, s76
	global_load_lds_dwordx4 v[224:225], off
	v_lshl_add_u64 v[234:235], s[20:21], 0, v[164:165]
	s_mov_b32 m0, vcc_hi
	v_lshl_add_u64 v[236:237], s[34:35], 0, v[166:167]
	global_load_lds_dwordx4 v[234:235], off
	v_lshl_add_u64 v[234:235], s[20:21], 0, v[168:169]
	s_add_i32 m0, vcc_hi, 0x2000
	s_nop 0
	global_load_lds_dwordx4 v[234:235], off
	v_lshl_add_u64 v[234:235], s[34:35], 0, v[162:163]
	s_mov_b32 m0, s17
	s_nop 0
	global_load_lds_dwordx4 v[234:235], off
	s_mov_b32 m0, s19
	s_nop 0
	global_load_lds_dwordx4 v[236:237], off
	s_waitcnt vmcnt(8)
	s_waitcnt lgkmcnt(0)
	s_setprio 1
	s_barrier
; #define PG8_STAGE(bufoff, gbase, voff) do { _Pragma("unroll") for (int _i = 0; _i < 2; ++_i) \
;         __builtin_amdgcn_global_load_lds((const unsigned*)((const char*)(gbase) + (voff)[_i]), (PG8_LAS unsigned*)(lds + (bufoff) + ldsw + _i * 8192), 16, 0, 0); } while (0)
; #define PG8_LDA(dst, b, h) do { _Pragma("unroll") for (int m = 0; m < 4; ++m) _Pragma("unroll") for (int k = 0; k < 2; ++k) dst[m][k] = *(const PG8_LAS bf16x8*)(lds + PG8_SA(b, h) + aoff + m * 2048 + k * 1024); } while (0)
; #define PG8_LDB(dst, b, h) do { _Pragma("unroll") for (int n = 0; n < 2; ++n) _Pragma("unroll") for (int k = 0; k < 2; ++k) dst[n][k] = *(const PG8_LAS bf16x8*)(lds + PG8_SB(b, h) + boff + n * 2048 + k * 1024); } while (0)
; #define PG8_MMA(ai, bj, At, Bt) do { __builtin_amdgcn_s_setprio(1); _Pragma("unroll") for (int m = 0; m < 4; ++m) _Pragma("unroll") for (int n = 0; n < 2; ++n) _Pragma("unroll") for (int k = 0; k < 2; ++k) \
;         acc[ai][bj][m][n] = __builtin_amdgcn_mfma_f32_16x16x32_bf16(Bt[n][k], At[m][k], acc[ai][bj][m][n], 0, 0, 0); __builtin_amdgcn_s_setprio(0); } while (0)
; #define PG8_WAIT_V(n) asm volatile("s_waitcnt vmcnt(" #n ")" ::: "memory")
; #define PG8_WAIT_L(n) asm volatile("s_waitcnt lgkmcnt(" #n ")" ::: "memory")
; #define PG8_BAR __builtin_amdgcn_s_barrier()
; #define PG8_SCHED __builtin_amdgcn_sched_barrier(0)
; template <class Epi, class Sched, bool ALIGN_EPI = false, bool SP2 = false>
; __device__ __forceinline__ void gemm_phase(PG8_LAS unsigned char* lds, const Gemm g, const Sched& S, const Epi& E, const int wave_id) {
;     ...
;             PG8_WAIT_V(8); PG8_WAIT_L(0); PG8_BAR; PG8_MMA(1, 0, At, B0); PG8_MMA(1, 1, At, B1); PG8_BAR; PG8_SCHED;
;             PG8_LDB(B0, 1, 0); PG8_LDB(B1, 1, 1); PG8_SCHED; PG8_LDA(At, 1, 0); PG8_STAGE(PG8_SA(0, 1), a2 + hstepA, voffA);
;             PG8_WAIT_V(8); PG8_WAIT_L(0); PG8_BAR; PG8_MMA(0, 0, At, B0); PG8_MMA(0, 1, At, B1); PG8_BAR; PG8_SCHED;
;             PG8_LDA(At, 1, 1); PG8_STAGE(PG8_SB(1, 0), b3, voffB); PG8_STAGE(PG8_SB(1, 1), b3 + hstepB, voffB); PG8_STAGE(PG8_SA(1, 0), a3, voffA);
	v_mfma_f32_16x16x32_bf16 v[62:65], v[122:125], v[182:185], v[62:65]
	v_mfma_f32_16x16x32_bf16 v[58:61], v[138:141], v[182:185], v[58:61]
	v_mfma_f32_16x16x32_bf16 v[46:49], v[122:125], v[190:193], v[46:49]
	v_mfma_f32_16x16x32_bf16 v[42:45], v[138:141], v[190:193], v[42:45]
	v_mfma_f32_16x16x32_bf16 v[30:33], v[122:125], v[198:201], v[30:33]
	v_mfma_f32_16x16x32_bf16 v[26:29], v[138:141], v[198:201], v[26:29]
	v_mfma_f32_16x16x32_bf16 v[14:17], v[122:125], v[214:217], v[14:17]
	v_mfma_f32_16x16x32_bf16 v[10:13], v[138:141], v[214:217], v[10:13]
	v_mfma_f32_16x16x32_bf16 v[62:65], v[134:137], v[186:189], v[62:65]
	v_mfma_f32_16x16x32_bf16 v[58:61], v[142:145], v[186:189], v[58:61]
	v_mfma_f32_16x16x32_bf16 v[46:49], v[134:137], v[194:197], v[46:49]
	v_mfma_f32_16x16x32_bf16 v[42:45], v[142:145], v[194:197], v[42:45]
	v_mfma_f32_16x16x32_bf16 v[30:33], v[134:137], v[202:205], v[30:33]
	v_mfma_f32_16x16x32_bf16 v[26:29], v[142:145], v[202:205], v[26:29]
	v_mfma_f32_16x16x32_bf16 v[14:17], v[134:137], v[218:221], v[14:17]
	v_mfma_f32_16x16x32_bf16 v[10:13], v[142:145], v[218:221], v[10:13]
	v_mfma_f32_16x16x32_bf16 v[54:57], v[146:149], v[182:185], v[54:57]
	v_mfma_f32_16x16x32_bf16 v[50:53], v[154:157], v[182:185], v[50:53]
	v_mfma_f32_16x16x32_bf16 v[38:41], v[146:149], v[190:193], v[38:41]
	v_mfma_f32_16x16x32_bf16 v[34:37], v[154:157], v[190:193], v[34:37]
	v_mfma_f32_16x16x32_bf16 v[22:25], v[146:149], v[198:201], v[22:25]
	v_mfma_f32_16x16x32_bf16 v[18:21], v[154:157], v[198:201], v[18:21]
	v_mfma_f32_16x16x32_bf16 v[6:9], v[146:149], v[214:217], v[6:9]
	v_mfma_f32_16x16x32_bf16 v[2:5], v[154:157], v[214:217], v[2:5]
	v_mfma_f32_16x16x32_bf16 v[54:57], v[150:153], v[186:189], v[54:57]
	v_mfma_f32_16x16x32_bf16 v[50:53], v[158:161], v[186:189], v[50:53]
	v_mfma_f32_16x16x32_bf16 v[38:41], v[150:153], v[194:197], v[38:41]
	v_mfma_f32_16x16x32_bf16 v[34:37], v[158:161], v[194:197], v[34:37]
	v_mfma_f32_16x16x32_bf16 v[22:25], v[150:153], v[202:205], v[22:25]
	v_mfma_f32_16x16x32_bf16 v[18:21], v[158:161], v[202:205], v[18:21]
	v_mfma_f32_16x16x32_bf16 v[6:9], v[150:153], v[218:221], v[6:9]
	v_mfma_f32_16x16x32_bf16 v[2:5], v[158:161], v[218:221], v[2:5]
	s_barrier
	s_setprio 0
	s_add_i32 vcc_hi, 0, 0x18000
	v_add_u32_e32 v0, vcc_hi, v206
	s_add_i32 s39, 0, 0x1c000
	ds_read_b128 v[122:125], v0
	ds_read_b128 v[134:137], v0 offset:1024
	ds_read_b128 v[138:141], v0 offset:2048
	ds_read_b128 v[142:145], v0 offset:3072
	v_add_u32_e32 v0, s39, v206
	ds_read_b128 v[146:149], v0
	ds_read_b128 v[150:153], v0 offset:1024
	ds_read_b128 v[154:157], v0 offset:2048
	ds_read_b128 v[158:161], v0 offset:3072
	s_add_u32 s20, s34, 0x40000
	s_addc_u32 s21, s35, 0
	s_mov_b32 m0, s77
	v_lshl_add_u64 v[240:241], s[20:21], 0, v[162:163]
	ds_read_b128 v[182:185], v212 offset:32768
	ds_read_b128 v[186:189], v212 offset:33792
	ds_read_b128 v[190:193], v212 offset:34816
	ds_read_b128 v[194:197], v212 offset:35840
	ds_read_b128 v[198:201], v212 offset:36864
	ds_read_b128 v[202:205], v212 offset:37888
	ds_read_b128 v[214:217], v212 offset:38912
	ds_read_b128 v[218:221], v212 offset:39936
	global_load_lds_dwordx4 v[240:241], off
	v_lshl_add_u64 v[240:241], s[20:21], 0, v[166:167]
	s_mov_b32 m0, s80
	s_nop 0
	global_load_lds_dwordx4 v[240:241], off
	s_waitcnt vmcnt(8)
	s_waitcnt lgkmcnt(0)
	s_setprio 1
	s_barrier
	v_mfma_f32_16x16x32_bf16 v[130:133], v[122:125], v[182:185], v[130:133]
	v_mfma_f32_16x16x32_bf16 v[126:129], v[138:141], v[182:185], v[126:129]
	v_mfma_f32_16x16x32_bf16 v[110:113], v[122:125], v[190:193], v[110:113]
	v_mfma_f32_16x16x32_bf16 v[106:109], v[138:141], v[190:193], v[106:109]
	v_mfma_f32_16x16x32_bf16 v[94:97], v[122:125], v[198:201], v[94:97]
	v_mfma_f32_16x16x32_bf16 v[90:93], v[138:141], v[198:201], v[90:93]
	v_mfma_f32_16x16x32_bf16 v[78:81], v[122:125], v[214:217], v[78:81]
	v_mfma_f32_16x16x32_bf16 v[74:77], v[138:141], v[214:217], v[74:77]
	v_mfma_f32_16x16x32_bf16 v[130:133], v[134:137], v[186:189], v[130:133]
	v_mfma_f32_16x16x32_bf16 v[126:129], v[142:145], v[186:189], v[126:129]
	v_mfma_f32_16x16x32_bf16 v[110:113], v[134:137], v[194:197], v[110:113]
	v_mfma_f32_16x16x32_bf16 v[106:109], v[142:145], v[194:197], v[106:109]
	v_mfma_f32_16x16x32_bf16 v[94:97], v[134:137], v[202:205], v[94:97]
	v_mfma_f32_16x16x32_bf16 v[90:93], v[142:145], v[202:205], v[90:93]
	v_mfma_f32_16x16x32_bf16 v[78:81], v[134:137], v[218:221], v[78:81]
	v_mfma_f32_16x16x32_bf16 v[74:77], v[142:145], v[218:221], v[74:77]
	v_mfma_f32_16x16x32_bf16 v[118:121], v[146:149], v[182:185], v[118:121]
	v_mfma_f32_16x16x32_bf16 v[114:117], v[154:157], v[182:185], v[114:117]
	v_mfma_f32_16x16x32_bf16 v[102:105], v[146:149], v[190:193], v[102:105]
	v_mfma_f32_16x16x32_bf16 v[98:101], v[154:157], v[190:193], v[98:101]
	v_mfma_f32_16x16x32_bf16 v[86:89], v[146:149], v[198:201], v[86:89]
	v_mfma_f32_16x16x32_bf16 v[82:85], v[154:157], v[198:201], v[82:85]
	v_mfma_f32_16x16x32_bf16 v[70:73], v[146:149], v[214:217], v[70:73]
	v_mfma_f32_16x16x32_bf16 v[66:69], v[154:157], v[214:217], v[66:69]
	v_mfma_f32_16x16x32_bf16 v[118:121], v[150:153], v[186:189], v[118:121]
	v_mfma_f32_16x16x32_bf16 v[114:117], v[158:161], v[186:189], v[114:117]
	v_mfma_f32_16x16x32_bf16 v[102:105], v[150:153], v[194:197], v[102:105]
	v_mfma_f32_16x16x32_bf16 v[98:101], v[158:161], v[194:197], v[98:101]
	v_mfma_f32_16x16x32_bf16 v[86:89], v[150:153], v[202:205], v[86:89]
	v_mfma_f32_16x16x32_bf16 v[82:85], v[158:161], v[202:205], v[82:85]
	v_mfma_f32_16x16x32_bf16 v[70:73], v[150:153], v[218:221], v[70:73]
	v_mfma_f32_16x16x32_bf16 v[66:69], v[158:161], v[218:221], v[66:69]
	s_barrier
; #define PG8_STAGE(bufoff, gbase, voff) do { _Pragma("unroll") for (int _i = 0; _i < 2; ++_i) \
;         __builtin_amdgcn_global_load_lds((const unsigned*)((const char*)(gbase) + (voff)[_i]), (PG8_LAS unsigned*)(lds + (bufoff) + ldsw + _i * 8192), 16, 0, 0); } while (0)
; #define PG8_LDA(dst, b, h) do { _Pragma("unroll") for (int m = 0; m < 4; ++m) _Pragma("unroll") for (int k = 0; k < 2; ++k) dst[m][k] = *(const PG8_LAS bf16x8*)(lds + PG8_SA(b, h) + aoff + m * 2048 + k * 1024); } while (0)
; #define PG8_MMA(ai, bj, At, Bt) do { __builtin_amdgcn_s_setprio(1); _Pragma("unroll") for (int m = 0; m < 4; ++m) _Pragma("unroll") for (int n = 0; n < 2; ++n) _Pragma("unroll") for (int k = 0; k < 2; ++k) \
;         acc[ai][bj][m][n] = __builtin_amdgcn_mfma_f32_16x16x32_bf16(Bt[n][k], At[m][k], acc[ai][bj][m][n], 0, 0, 0); __builtin_amdgcn_s_setprio(0); } while (0)
; #define PG8_WAIT_V(n) asm volatile("s_waitcnt vmcnt(" #n ")" ::: "memory")
; #define PG8_WAIT_L(n) asm volatile("s_waitcnt lgkmcnt(" #n ")" ::: "memory")
; #define PG8_BAR __builtin_amdgcn_s_barrier()
; #define PG8_SCHED __builtin_amdgcn_sched_barrier(0)
; template <class Epi, class Sched, bool ALIGN_EPI = false, bool SP2 = false>
; __device__ __forceinline__ void gemm_phase(PG8_LAS unsigned char* lds, const Gemm g, const Sched& S, const Epi& E, const int wave_id) {
;     ...
;         for (int t = 0; t < nt; t += 2) {
;             const bool last = (t == nt - 2);
;     ...
;             PG8_LDA(At, 1, 1); PG8_STAGE(PG8_SB(1, 0), b3, voffB); PG8_STAGE(PG8_SB(1, 1), b3 + hstepB, voffB); PG8_STAGE(PG8_SA(1, 0), a3, voffA);
;             PG8_WAIT_V(8); PG8_WAIT_L(0); PG8_BAR; PG8_MMA(1, 0, At, B0); PG8_MMA(1, 1, At, B1); PG8_BAR; PG8_SCHED;
	s_setprio 0
	s_add_i32 s20, vcc_hi, s76
	v_lshl_add_u64 v[222:223], v[222:223], 0, s[62:63]
	s_mov_b32 m0, s20
	ds_read_b128 v[182:185], v212 offset:49152
	ds_read_b128 v[186:189], v212 offset:50176
	ds_read_b128 v[190:193], v212 offset:51200
	ds_read_b128 v[194:197], v212 offset:52224
	ds_read_b128 v[198:201], v212 offset:53248
	ds_read_b128 v[202:205], v212 offset:54272
	ds_read_b128 v[214:217], v212 offset:55296
	ds_read_b128 v[218:221], v212 offset:56320
	global_load_lds_dwordx4 v[222:223], off
	s_add_i32 m0, s20, 0x2000
	s_add_u32 s12, s12, 0x40080
	v_lshl_add_u64 v[222:223], v[224:225], 0, s[62:63]
	s_addc_u32 s13, s13, 0
	s_add_i32 s20, s39, s76
	global_load_lds_dwordx4 v[222:223], off
	v_lshl_add_u64 v[222:223], s[12:13], 0, v[164:165]
	s_mov_b32 m0, s20
	s_nop 0
	global_load_lds_dwordx4 v[222:223], off
	v_lshl_add_u64 v[222:223], s[12:13], 0, v[168:169]
	s_add_i32 m0, s20, 0x2000
	s_nop 0
	global_load_lds_dwordx4 v[222:223], off
	v_lshl_add_u64 v[222:223], v[234:235], 0, s[62:63]
	s_mov_b32 m0, s82
	s_nop 0
	global_load_lds_dwordx4 v[222:223], off
	v_lshl_add_u64 v[222:223], v[236:237], 0, s[62:63]
	s_mov_b32 m0, s83
	s_nop 0
	global_load_lds_dwordx4 v[222:223], off
	s_waitcnt vmcnt(8)
	s_waitcnt lgkmcnt(0)
	s_setprio 1
	s_barrier
	v_mfma_f32_16x16x32_bf16 v[62:65], v[122:125], v[182:185], v[62:65]
	v_mfma_f32_16x16x32_bf16 v[58:61], v[138:141], v[182:185], v[58:61]
	v_mfma_f32_16x16x32_bf16 v[46:49], v[122:125], v[190:193], v[46:49]
	v_mfma_f32_16x16x32_bf16 v[42:45], v[138:141], v[190:193], v[42:45]
	v_mfma_f32_16x16x32_bf16 v[30:33], v[122:125], v[198:201], v[30:33]
	v_mfma_f32_16x16x32_bf16 v[26:29], v[138:141], v[198:201], v[26:29]
	v_mfma_f32_16x16x32_bf16 v[14:17], v[122:125], v[214:217], v[14:17]
	v_mfma_f32_16x16x32_bf16 v[10:13], v[138:141], v[214:217], v[10:13]
	v_mfma_f32_16x16x32_bf16 v[62:65], v[134:137], v[186:189], v[62:65]
	v_mfma_f32_16x16x32_bf16 v[58:61], v[142:145], v[186:189], v[58:61]
	v_mfma_f32_16x16x32_bf16 v[46:49], v[134:137], v[194:197], v[46:49]
	v_mfma_f32_16x16x32_bf16 v[42:45], v[142:145], v[194:197], v[42:45]
	v_mfma_f32_16x16x32_bf16 v[30:33], v[134:137], v[202:205], v[30:33]
	v_mfma_f32_16x16x32_bf16 v[26:29], v[142:145], v[202:205], v[26:29]
	v_mfma_f32_16x16x32_bf16 v[14:17], v[134:137], v[218:221], v[14:17]
	v_mfma_f32_16x16x32_bf16 v[10:13], v[142:145], v[218:221], v[10:13]
	v_mfma_f32_16x16x32_bf16 v[54:57], v[146:149], v[182:185], v[54:57]
	v_mfma_f32_16x16x32_bf16 v[50:53], v[154:157], v[182:185], v[50:53]
	v_mfma_f32_16x16x32_bf16 v[38:41], v[146:149], v[190:193], v[38:41]
	v_mfma_f32_16x16x32_bf16 v[34:37], v[154:157], v[190:193], v[34:37]
	v_mfma_f32_16x16x32_bf16 v[22:25], v[146:149], v[198:201], v[22:25]
	v_mfma_f32_16x16x32_bf16 v[18:21], v[154:157], v[198:201], v[18:21]
	v_mfma_f32_16x16x32_bf16 v[6:9], v[146:149], v[214:217], v[6:9]
	v_mfma_f32_16x16x32_bf16 v[2:5], v[154:157], v[214:217], v[2:5]
	v_mfma_f32_16x16x32_bf16 v[54:57], v[150:153], v[186:189], v[54:57]
	v_mfma_f32_16x16x32_bf16 v[50:53], v[158:161], v[186:189], v[50:53]
	v_mfma_f32_16x16x32_bf16 v[38:41], v[150:153], v[194:197], v[38:41]
	v_mfma_f32_16x16x32_bf16 v[34:37], v[158:161], v[194:197], v[34:37]
	v_mfma_f32_16x16x32_bf16 v[22:25], v[150:153], v[202:205], v[22:25]
	v_mfma_f32_16x16x32_bf16 v[18:21], v[158:161], v[202:205], v[18:21]
	v_mfma_f32_16x16x32_bf16 v[6:9], v[150:153], v[218:221], v[6:9]
	v_mfma_f32_16x16x32_bf16 v[2:5], v[158:161], v[218:221], v[2:5]
	s_barrier
	s_setprio 0
	s_add_i32 vcc_lo, vcc_lo, 2
	s_add_u32 s10, s10, 0x100
	s_addc_u32 s11, s11, 0
	s_add_u32 s37, s37, 0x100
	s_addc_u32 s38, s38, 0
	s_cmp_gt_u32 vcc_lo, 13
	s_cbranch_scc0 .LBB0_297
	s_and_b64 vcc, exec, s[22:23]
	s_cbranch_vccz .LBB0_300
	s_barrier

; #define PG8_STAGE(bufoff, gbase, voff) do { _Pragma("unroll") for (int _i = 0; _i < 2; ++_i) \
;         __builtin_amdgcn_global_load_lds((const unsigned*)((const char*)(gbase) + (voff)[_i]), (PG8_LAS unsigned*)(lds + (bufoff) + ldsw + _i * 8192), 16, 0, 0); } while (0)
; #define PG8_LDA(dst, b, h) do { _Pragma("unroll") for (int m = 0; m < 4; ++m) _Pragma("unroll") for (int k = 0; k < 2; ++k) dst[m][k] = *(const PG8_LAS bf16x8*)(lds + PG8_SA(b, h) + aoff + m * 2048 + k * 1024); } while (0)
; #define PG8_MMA(ai, bj, At, Bt) do { __builtin_amdgcn_s_setprio(1); _Pragma("unroll") for (int m = 0; m < 4; ++m) _Pragma("unroll") for (int n = 0; n < 2; ++n) _Pragma("unroll") for (int k = 0; k < 2; ++k) \
;         acc[ai][bj][m][n] = __builtin_amdgcn_mfma_f32_16x16x32_bf16(Bt[n][k], At[m][k], acc[ai][bj][m][n], 0, 0, 0); __builtin_amdgcn_s_setprio(0); } while (0)
; #define PG8_WAIT_V(n) asm volatile("s_waitcnt vmcnt(" #n ")" ::: "memory")
; #define PG8_WAIT_L(n) asm volatile("s_waitcnt lgkmcnt(" #n ")" ::: "memory")
; #define PG8_BAR __builtin_amdgcn_s_barrier()
; #define PG8_SCHED __builtin_amdgcn_sched_barrier(0)
; template <class Epi, class Sched, bool ALIGN_EPI = false, bool SP2 = false>
; __device__ __forceinline__ void gemm_phase(PG8_LAS unsigned char* lds, const Gemm g, const Sched& S, const Epi& E, const int wave_id) {
;     ...
;             PG8_WAIT_V(8); PG8_WAIT_L(0); PG8_BAR; PG8_MMA(0, 0, At, B0); PG8_MMA(0, 1, At, B1); PG8_BAR; PG8_SCHED;
;             PG8_LDA(At, 0, 1); PG8_STAGE(PG8_SB(0, 0), b2, voffB); PG8_STAGE(PG8_SB(0, 1), b2 + hstepB, voffB); PG8_STAGE(PG8_SA(0, 0), a2, voffA);
;             PG8_WAIT_V(8); PG8_WAIT_L(0); PG8_BAR; PG8_MMA(1, 0, At, B0); PG8_MMA(1, 1, At, B1); PG8_BAR; PG8_SCHED;
.Lrw_3:
	s_waitcnt lgkmcnt(0)
	s_setprio 1
	s_barrier
	v_mfma_f32_16x16x32_bf16 v[134:137], v[138:141], v[190:193], v[134:137]
	v_mfma_f32_16x16x32_bf16 v[130:133], v[146:149], v[190:193], v[130:133]
	v_mfma_f32_16x16x32_bf16 v[122:125], v[138:141], v[198:201], v[122:125]
	v_mfma_f32_16x16x32_bf16 v[114:117], v[146:149], v[198:201], v[114:117]
	v_mfma_f32_16x16x32_bf16 v[106:109], v[138:141], v[216:219], v[106:109]
	v_mfma_f32_16x16x32_bf16 v[98:101], v[146:149], v[216:219], v[98:101]
	v_mfma_f32_16x16x32_bf16 v[90:93], v[138:141], v[240:243], v[90:93]
	v_mfma_f32_16x16x32_bf16 v[82:85], v[146:149], v[240:243], v[82:85]
	v_mfma_f32_16x16x32_bf16 v[134:137], v[142:145], v[194:197], v[134:137]
	v_mfma_f32_16x16x32_bf16 v[130:133], v[150:153], v[194:197], v[130:133]
	v_mfma_f32_16x16x32_bf16 v[122:125], v[142:145], v[202:205], v[122:125]
	v_mfma_f32_16x16x32_bf16 v[114:117], v[150:153], v[202:205], v[114:117]
	v_mfma_f32_16x16x32_bf16 v[106:109], v[142:145], v[220:223], v[106:109]
	v_mfma_f32_16x16x32_bf16 v[98:101], v[150:153], v[220:223], v[98:101]
	v_mfma_f32_16x16x32_bf16 v[90:93], v[142:145], v[244:247], v[90:93]
	v_mfma_f32_16x16x32_bf16 v[82:85], v[150:153], v[244:247], v[82:85]
	v_mfma_f32_16x16x32_bf16 v[126:129], v[154:157], v[190:193], v[126:129]
	v_mfma_f32_16x16x32_bf16 v[118:121], v[162:165], v[190:193], v[118:121]
	v_mfma_f32_16x16x32_bf16 v[110:113], v[154:157], v[198:201], v[110:113]
	v_mfma_f32_16x16x32_bf16 v[102:105], v[162:165], v[198:201], v[102:105]
	v_mfma_f32_16x16x32_bf16 v[94:97], v[154:157], v[216:219], v[94:97]
	v_mfma_f32_16x16x32_bf16 v[86:89], v[162:165], v[216:219], v[86:89]
	v_mfma_f32_16x16x32_bf16 v[78:81], v[154:157], v[240:243], v[78:81]
	v_mfma_f32_16x16x32_bf16 v[74:77], v[162:165], v[240:243], v[74:77]
	v_mfma_f32_16x16x32_bf16 v[126:129], v[158:161], v[194:197], v[126:129]
	v_mfma_f32_16x16x32_bf16 v[118:121], v[166:169], v[194:197], v[118:121]
	v_mfma_f32_16x16x32_bf16 v[110:113], v[158:161], v[202:205], v[110:113]
	v_mfma_f32_16x16x32_bf16 v[102:105], v[166:169], v[202:205], v[102:105]
	v_mfma_f32_16x16x32_bf16 v[94:97], v[158:161], v[220:223], v[94:97]
	v_mfma_f32_16x16x32_bf16 v[86:89], v[166:169], v[220:223], v[86:89]
	v_mfma_f32_16x16x32_bf16 v[78:81], v[158:161], v[244:247], v[78:81]
	v_mfma_f32_16x16x32_bf16 v[74:77], v[166:169], v[244:247], v[74:77]
	s_barrier
	s_setprio 0
	s_add_i32 s0, s35, s23
	v_lshl_add_u64 v[206:207], s[26:27], 0, v[180:181]
	s_mov_b32 m0, s0
	ds_read_b128 v[190:193], v215 offset:16384
	ds_read_b128 v[194:197], v215 offset:17408
	ds_read_b128 v[198:201], v215 offset:18432
	ds_read_b128 v[202:205], v215 offset:19456
	ds_read_b128 v[216:219], v215 offset:20480
	ds_read_b128 v[220:223], v215 offset:21504
	ds_read_b128 v[240:243], v215 offset:22528
	ds_read_b128 v[244:247], v215 offset:23552
	global_load_lds_dwordx4 v[206:207], off
	s_add_i32 m0, s0, 0x2000
	s_add_u32 s0, s26, 0x40000
	v_lshl_add_u64 v[224:225], s[26:27], 0, v[184:185]
	s_addc_u32 s1, s27, 0
	s_add_i32 s35, s36, s23
	global_load_lds_dwordx4 v[224:225], off
	v_lshl_add_u64 v[234:235], s[0:1], 0, v[180:181]
	s_mov_b32 m0, s35
	v_lshl_add_u64 v[236:237], s[28:29], 0, v[182:183]
	global_load_lds_dwordx4 v[234:235], off
	v_lshl_add_u64 v[234:235], s[0:1], 0, v[184:185]
	s_add_i32 m0, s35, 0x2000
	s_nop 0
	global_load_lds_dwordx4 v[234:235], off
	v_lshl_add_u64 v[234:235], s[28:29], 0, v[178:179]
	s_mov_b32 m0, s25
	s_nop 0
	global_load_lds_dwordx4 v[234:235], off
	s_mov_b32 m0, s30
	s_nop 0
	global_load_lds_dwordx4 v[236:237], off
	s_waitcnt vmcnt(24)
	s_cmp_eq_u32 s98, 1
	s_cbranch_scc1 .Lrw_4
	s_waitcnt vmcnt(8)
.Lrw_4:
	s_mov_b32 s98, 0
	s_waitcnt lgkmcnt(0)
	s_setprio 1
	s_barrier
	v_mfma_f32_16x16x32_bf16 v[70:73], v[138:141], v[190:193], v[70:73]
	v_mfma_f32_16x16x32_bf16 v[66:69], v[146:149], v[190:193], v[66:69]
	v_mfma_f32_16x16x32_bf16 v[58:61], v[138:141], v[198:201], v[58:61]
	v_mfma_f32_16x16x32_bf16 v[50:53], v[146:149], v[198:201], v[50:53]
	v_mfma_f32_16x16x32_bf16 v[42:45], v[138:141], v[216:219], v[42:45]
	v_mfma_f32_16x16x32_bf16 v[34:37], v[146:149], v[216:219], v[34:37]
	v_mfma_f32_16x16x32_bf16 v[26:29], v[138:141], v[240:243], v[26:29]
	v_mfma_f32_16x16x32_bf16 v[18:21], v[146:149], v[240:243], v[18:21]
	v_mfma_f32_16x16x32_bf16 v[70:73], v[142:145], v[194:197], v[70:73]
	v_mfma_f32_16x16x32_bf16 v[66:69], v[150:153], v[194:197], v[66:69]
	v_mfma_f32_16x16x32_bf16 v[58:61], v[142:145], v[202:205], v[58:61]
	v_mfma_f32_16x16x32_bf16 v[50:53], v[150:153], v[202:205], v[50:53]
	v_mfma_f32_16x16x32_bf16 v[42:45], v[142:145], v[220:223], v[42:45]
	v_mfma_f32_16x16x32_bf16 v[34:37], v[150:153], v[220:223], v[34:37]
	v_mfma_f32_16x16x32_bf16 v[26:29], v[142:145], v[244:247], v[26:29]
	v_mfma_f32_16x16x32_bf16 v[18:21], v[150:153], v[244:247], v[18:21]
	v_mfma_f32_16x16x32_bf16 v[62:65], v[154:157], v[190:193], v[62:65]
	v_mfma_f32_16x16x32_bf16 v[54:57], v[162:165], v[190:193], v[54:57]
	v_mfma_f32_16x16x32_bf16 v[46:49], v[154:157], v[198:201], v[46:49]
	v_mfma_f32_16x16x32_bf16 v[38:41], v[162:165], v[198:201], v[38:41]
	v_mfma_f32_16x16x32_bf16 v[30:33], v[154:157], v[216:219], v[30:33]
	v_mfma_f32_16x16x32_bf16 v[22:25], v[162:165], v[216:219], v[22:25]
	v_mfma_f32_16x16x32_bf16 v[14:17], v[154:157], v[240:243], v[14:17]
	v_mfma_f32_16x16x32_bf16 v[10:13], v[162:165], v[240:243], v[10:13]
	v_mfma_f32_16x16x32_bf16 v[62:65], v[158:161], v[194:197], v[62:65]
	v_mfma_f32_16x16x32_bf16 v[54:57], v[166:169], v[194:197], v[54:57]
	v_mfma_f32_16x16x32_bf16 v[46:49], v[158:161], v[202:205], v[46:49]
	v_mfma_f32_16x16x32_bf16 v[38:41], v[166:169], v[202:205], v[38:41]
	v_mfma_f32_16x16x32_bf16 v[30:33], v[158:161], v[220:223], v[30:33]
	v_mfma_f32_16x16x32_bf16 v[22:25], v[166:169], v[220:223], v[22:25]
	v_mfma_f32_16x16x32_bf16 v[14:17], v[158:161], v[244:247], v[14:17]
	v_mfma_f32_16x16x32_bf16 v[10:13], v[166:169], v[244:247], v[10:13]
	s_barrier
; #define PG8_STAGE(bufoff, gbase, voff) do { _Pragma("unroll") for (int _i = 0; _i < 2; ++_i) \
;         __builtin_amdgcn_global_load_lds((const unsigned*)((const char*)(gbase) + (voff)[_i]), (PG8_LAS unsigned*)(lds + (bufoff) + ldsw + _i * 8192), 16, 0, 0); } while (0)
; #define PG8_LDA(dst, b, h) do { _Pragma("unroll") for (int m = 0; m < 4; ++m) _Pragma("unroll") for (int k = 0; k < 2; ++k) dst[m][k] = *(const PG8_LAS bf16x8*)(lds + PG8_SA(b, h) + aoff + m * 2048 + k * 1024); } while (0)
; #define PG8_LDB(dst, b, h) do { _Pragma("unroll") for (int n = 0; n < 2; ++n) _Pragma("unroll") for (int k = 0; k < 2; ++k) dst[n][k] = *(const PG8_LAS bf16x8*)(lds + PG8_SB(b, h) + boff + n * 2048 + k * 1024); } while (0)
; #define PG8_MMA(ai, bj, At, Bt) do { __builtin_amdgcn_s_setprio(1); _Pragma("unroll") for (int m = 0; m < 4; ++m) _Pragma("unroll") for (int n = 0; n < 2; ++n) _Pragma("unroll") for (int k = 0; k < 2; ++k) \
;         acc[ai][bj][m][n] = __builtin_amdgcn_mfma_f32_16x16x32_bf16(Bt[n][k], At[m][k], acc[ai][bj][m][n], 0, 0, 0); __builtin_amdgcn_s_setprio(0); } while (0)
; #define PG8_WAIT_V(n) asm volatile("s_waitcnt vmcnt(" #n ")" ::: "memory")
; #define PG8_WAIT_L(n) asm volatile("s_waitcnt lgkmcnt(" #n ")" ::: "memory")
; #define PG8_BAR __builtin_amdgcn_s_barrier()
; #define PG8_SCHED __builtin_amdgcn_sched_barrier(0)
; template <class Epi, class Sched, bool ALIGN_EPI = false, bool SP2 = false>
; __device__ __forceinline__ void gemm_phase(PG8_LAS unsigned char* lds, const Gemm g, const Sched& S, const Epi& E, const int wave_id) {
;     ...
;             PG8_WAIT_V(8); PG8_WAIT_L(0); PG8_BAR; PG8_MMA(1, 0, At, B0); PG8_MMA(1, 1, At, B1); PG8_BAR; PG8_SCHED;
;             PG8_LDB(B0, 1, 0); PG8_LDB(B1, 1, 1); PG8_SCHED; PG8_LDA(At, 1, 0); PG8_STAGE(PG8_SA(0, 1), a2 + hstepA, voffA);
;             PG8_WAIT_V(8); PG8_WAIT_L(0); PG8_BAR; PG8_MMA(0, 0, At, B0); PG8_MMA(0, 1, At, B1); PG8_BAR; PG8_SCHED;
	s_setprio 0
	s_add_i32 s35, 0, 0x18000
	v_add_u32_e32 v0, s35, v210
	s_add_i32 s36, 0, 0x1c000
	ds_read_b128 v[138:141], v0
	ds_read_b128 v[142:145], v0 offset:1024
	ds_read_b128 v[146:149], v0 offset:2048
	ds_read_b128 v[150:153], v0 offset:3072
	v_add_u32_e32 v0, s36, v210
	ds_read_b128 v[154:157], v0
	ds_read_b128 v[158:161], v0 offset:1024
	ds_read_b128 v[162:165], v0 offset:2048
	ds_read_b128 v[166:169], v0 offset:3072
	s_add_u32 s0, s28, 0x40000
	s_addc_u32 s1, s29, 0
	s_mov_b32 m0, s31
	v_lshl_add_u64 v[248:249], s[0:1], 0, v[178:179]
	ds_read_b128 v[190:193], v215 offset:32768
	ds_read_b128 v[194:197], v215 offset:33792
	ds_read_b128 v[198:201], v215 offset:34816
	ds_read_b128 v[202:205], v215 offset:35840
	ds_read_b128 v[216:219], v215 offset:36864
	ds_read_b128 v[220:223], v215 offset:37888
	ds_read_b128 v[240:243], v215 offset:38912
	ds_read_b128 v[244:247], v215 offset:39936
	global_load_lds_dwordx4 v[248:249], off
	v_lshl_add_u64 v[248:249], s[0:1], 0, v[182:183]
	s_mov_b32 m0, s34
	s_nop 0
	global_load_lds_dwordx4 v[248:249], off
	s_waitcnt vmcnt(8)
	s_waitcnt lgkmcnt(0)
	s_setprio 1
	s_barrier
	v_mfma_f32_16x16x32_bf16 v[134:137], v[138:141], v[190:193], v[134:137]
	v_mfma_f32_16x16x32_bf16 v[130:133], v[146:149], v[190:193], v[130:133]
	v_mfma_f32_16x16x32_bf16 v[122:125], v[138:141], v[198:201], v[122:125]
	v_mfma_f32_16x16x32_bf16 v[114:117], v[146:149], v[198:201], v[114:117]
	v_mfma_f32_16x16x32_bf16 v[106:109], v[138:141], v[216:219], v[106:109]
	v_mfma_f32_16x16x32_bf16 v[98:101], v[146:149], v[216:219], v[98:101]
	v_mfma_f32_16x16x32_bf16 v[90:93], v[138:141], v[240:243], v[90:93]
	v_mfma_f32_16x16x32_bf16 v[82:85], v[146:149], v[240:243], v[82:85]
	v_mfma_f32_16x16x32_bf16 v[134:137], v[142:145], v[194:197], v[134:137]
	v_mfma_f32_16x16x32_bf16 v[130:133], v[150:153], v[194:197], v[130:133]
	v_mfma_f32_16x16x32_bf16 v[122:125], v[142:145], v[202:205], v[122:125]
	v_mfma_f32_16x16x32_bf16 v[114:117], v[150:153], v[202:205], v[114:117]
	v_mfma_f32_16x16x32_bf16 v[106:109], v[142:145], v[220:223], v[106:109]
	v_mfma_f32_16x16x32_bf16 v[98:101], v[150:153], v[220:223], v[98:101]
	v_mfma_f32_16x16x32_bf16 v[90:93], v[142:145], v[244:247], v[90:93]
	v_mfma_f32_16x16x32_bf16 v[82:85], v[150:153], v[244:247], v[82:85]
	v_mfma_f32_16x16x32_bf16 v[126:129], v[154:157], v[190:193], v[126:129]
	v_mfma_f32_16x16x32_bf16 v[118:121], v[162:165], v[190:193], v[118:121]
	v_mfma_f32_16x16x32_bf16 v[110:113], v[154:157], v[198:201], v[110:113]
	v_mfma_f32_16x16x32_bf16 v[102:105], v[162:165], v[198:201], v[102:105]
	v_mfma_f32_16x16x32_bf16 v[94:97], v[154:157], v[216:219], v[94:97]
	v_mfma_f32_16x16x32_bf16 v[86:89], v[162:165], v[216:219], v[86:89]
	v_mfma_f32_16x16x32_bf16 v[78:81], v[154:157], v[240:243], v[78:81]
	v_mfma_f32_16x16x32_bf16 v[74:77], v[162:165], v[240:243], v[74:77]
	v_mfma_f32_16x16x32_bf16 v[126:129], v[158:161], v[194:197], v[126:129]
	v_mfma_f32_16x16x32_bf16 v[118:121], v[166:169], v[194:197], v[118:121]
	v_mfma_f32_16x16x32_bf16 v[110:113], v[158:161], v[202:205], v[110:113]
	v_mfma_f32_16x16x32_bf16 v[102:105], v[166:169], v[202:205], v[102:105]
	v_mfma_f32_16x16x32_bf16 v[94:97], v[158:161], v[220:223], v[94:97]
	v_mfma_f32_16x16x32_bf16 v[86:89], v[166:169], v[220:223], v[86:89]
	v_mfma_f32_16x16x32_bf16 v[78:81], v[158:161], v[244:247], v[78:81]
	v_mfma_f32_16x16x32_bf16 v[74:77], v[166:169], v[244:247], v[74:77]
	s_barrier
; #define PG8_STAGE(bufoff, gbase, voff) do { _Pragma("unroll") for (int _i = 0; _i < 2; ++_i) \
;         __builtin_amdgcn_global_load_lds((const unsigned*)((const char*)(gbase) + (voff)[_i]), (PG8_LAS unsigned*)(lds + (bufoff) + ldsw + _i * 8192), 16, 0, 0); } while (0)
; #define PG8_LDA(dst, b, h) do { _Pragma("unroll") for (int m = 0; m < 4; ++m) _Pragma("unroll") for (int k = 0; k < 2; ++k) dst[m][k] = *(const PG8_LAS bf16x8*)(lds + PG8_SA(b, h) + aoff + m * 2048 + k * 1024); } while (0)
; #define PG8_MMA(ai, bj, At, Bt) do { __builtin_amdgcn_s_setprio(1); _Pragma("unroll") for (int m = 0; m < 4; ++m) _Pragma("unroll") for (int n = 0; n < 2; ++n) _Pragma("unroll") for (int k = 0; k < 2; ++k) \
;         acc[ai][bj][m][n] = __builtin_amdgcn_mfma_f32_16x16x32_bf16(Bt[n][k], At[m][k], acc[ai][bj][m][n], 0, 0, 0); __builtin_amdgcn_s_setprio(0); } while (0)
; #define PG8_WAIT_V(n) asm volatile("s_waitcnt vmcnt(" #n ")" ::: "memory")
; #define PG8_WAIT_L(n) asm volatile("s_waitcnt lgkmcnt(" #n ")" ::: "memory")
; #define PG8_BAR __builtin_amdgcn_s_barrier()
; #define PG8_SCHED __builtin_amdgcn_sched_barrier(0)
; template <class Epi, class Sched, bool ALIGN_EPI = false, bool SP2 = false>
; __device__ __forceinline__ void gemm_phase(PG8_LAS unsigned char* lds, const Gemm g, const Sched& S, const Epi& E, const int wave_id) {
;     ...
;         for (int t = 0; t < nt; t += 2) {
;             const bool last = (t == nt - 2);
;     ...
;             PG8_LDA(At, 1, 1); PG8_STAGE(PG8_SB(1, 0), b3, voffB); PG8_STAGE(PG8_SB(1, 1), b3 + hstepB, voffB); PG8_STAGE(PG8_SA(1, 0), a3, voffA);
;             PG8_WAIT_V(8); PG8_WAIT_L(0); PG8_BAR; PG8_MMA(1, 0, At, B0); PG8_MMA(1, 1, At, B1); PG8_BAR; PG8_SCHED;
	s_setprio 0
	s_add_i32 s0, s35, s23
	v_lshl_add_u64 v[206:207], v[206:207], 0, s[62:63]
	s_mov_b32 m0, s0
	ds_read_b128 v[190:193], v215 offset:49152
	ds_read_b128 v[194:197], v215 offset:50176
	ds_read_b128 v[198:201], v215 offset:51200
	ds_read_b128 v[202:205], v215 offset:52224
	ds_read_b128 v[216:219], v215 offset:53248
	ds_read_b128 v[220:223], v215 offset:54272
	ds_read_b128 v[240:243], v215 offset:55296
	ds_read_b128 v[244:247], v215 offset:56320
	global_load_lds_dwordx4 v[206:207], off
	s_add_i32 m0, s0, 0x2000
	s_add_u32 s0, s26, 0x40080
	v_lshl_add_u64 v[206:207], v[224:225], 0, s[62:63]
	s_addc_u32 s1, s27, 0
	s_add_i32 s26, s36, s23
	global_load_lds_dwordx4 v[206:207], off
	v_lshl_add_u64 v[206:207], s[0:1], 0, v[180:181]
	s_mov_b32 m0, s26
	s_nop 0
	global_load_lds_dwordx4 v[206:207], off
	v_lshl_add_u64 v[206:207], s[0:1], 0, v[184:185]
	s_add_i32 m0, s26, 0x2000
	s_nop 0
	global_load_lds_dwordx4 v[206:207], off
	v_lshl_add_u64 v[206:207], v[234:235], 0, s[62:63]
	s_mov_b32 m0, s44
	s_nop 0
	global_load_lds_dwordx4 v[206:207], off
	v_lshl_add_u64 v[206:207], v[236:237], 0, s[62:63]
	s_mov_b32 m0, s45
	s_nop 0
	global_load_lds_dwordx4 v[206:207], off
	s_waitcnt vmcnt(8)
	s_waitcnt lgkmcnt(0)
	s_setprio 1
	s_barrier
	v_mfma_f32_16x16x32_bf16 v[70:73], v[138:141], v[190:193], v[70:73]
	v_mfma_f32_16x16x32_bf16 v[66:69], v[146:149], v[190:193], v[66:69]
	v_mfma_f32_16x16x32_bf16 v[58:61], v[138:141], v[198:201], v[58:61]
	v_mfma_f32_16x16x32_bf16 v[50:53], v[146:149], v[198:201], v[50:53]
	v_mfma_f32_16x16x32_bf16 v[42:45], v[138:141], v[216:219], v[42:45]
	v_mfma_f32_16x16x32_bf16 v[34:37], v[146:149], v[216:219], v[34:37]
	v_mfma_f32_16x16x32_bf16 v[26:29], v[138:141], v[240:243], v[26:29]
	v_mfma_f32_16x16x32_bf16 v[18:21], v[146:149], v[240:243], v[18:21]
	v_mfma_f32_16x16x32_bf16 v[70:73], v[142:145], v[194:197], v[70:73]
	v_mfma_f32_16x16x32_bf16 v[66:69], v[150:153], v[194:197], v[66:69]
	v_mfma_f32_16x16x32_bf16 v[58:61], v[142:145], v[202:205], v[58:61]
	v_mfma_f32_16x16x32_bf16 v[50:53], v[150:153], v[202:205], v[50:53]
	v_mfma_f32_16x16x32_bf16 v[42:45], v[142:145], v[220:223], v[42:45]
	v_mfma_f32_16x16x32_bf16 v[34:37], v[150:153], v[220:223], v[34:37]
	v_mfma_f32_16x16x32_bf16 v[26:29], v[142:145], v[244:247], v[26:29]
	v_mfma_f32_16x16x32_bf16 v[18:21], v[150:153], v[244:247], v[18:21]
	v_mfma_f32_16x16x32_bf16 v[62:65], v[154:157], v[190:193], v[62:65]
	v_mfma_f32_16x16x32_bf16 v[54:57], v[162:165], v[190:193], v[54:57]
	v_mfma_f32_16x16x32_bf16 v[46:49], v[154:157], v[198:201], v[46:49]
	v_mfma_f32_16x16x32_bf16 v[38:41], v[162:165], v[198:201], v[38:41]
	v_mfma_f32_16x16x32_bf16 v[30:33], v[154:157], v[216:219], v[30:33]
	v_mfma_f32_16x16x32_bf16 v[22:25], v[162:165], v[216:219], v[22:25]
	v_mfma_f32_16x16x32_bf16 v[14:17], v[154:157], v[240:243], v[14:17]
	v_mfma_f32_16x16x32_bf16 v[10:13], v[162:165], v[240:243], v[10:13]
	v_mfma_f32_16x16x32_bf16 v[62:65], v[158:161], v[194:197], v[62:65]
	v_mfma_f32_16x16x32_bf16 v[54:57], v[166:169], v[194:197], v[54:57]
	v_mfma_f32_16x16x32_bf16 v[46:49], v[158:161], v[202:205], v[46:49]
	v_mfma_f32_16x16x32_bf16 v[38:41], v[166:169], v[202:205], v[38:41]
	v_mfma_f32_16x16x32_bf16 v[30:33], v[158:161], v[220:223], v[30:33]
	v_mfma_f32_16x16x32_bf16 v[22:25], v[166:169], v[220:223], v[22:25]
	v_mfma_f32_16x16x32_bf16 v[14:17], v[158:161], v[244:247], v[14:17]
	v_mfma_f32_16x16x32_bf16 v[10:13], v[166:169], v[244:247], v[10:13]
	s_barrier
	s_setprio 0
	s_add_i32 s5, s5, 2
	s_add_u32 s8, s8, 0x100
	s_addc_u32 s9, s9, 0
	s_add_u32 vcc_hi, vcc_hi, 0x100
	s_addc_u32 s4, s4, 0
	s_cmp_gt_u32 s5, 13
	s_cbranch_scc0 .LBB0_576

; #define PG8_STAGE(bufoff, gbase, voff) do { _Pragma("unroll") for (int _i = 0; _i < 2; ++_i) \
;         __builtin_amdgcn_global_load_lds((const unsigned*)((const char*)(gbase) + (voff)[_i]), (PG8_LAS unsigned*)(lds + (bufoff) + ldsw + _i * 8192), 16, 0, 0); } while (0)
; #define PG8_LDA(dst, b, h) do { _Pragma("unroll") for (int m = 0; m < 4; ++m) _Pragma("unroll") for (int k = 0; k < 2; ++k) dst[m][k] = *(const PG8_LAS bf16x8*)(lds + PG8_SA(b, h) + aoff + m * 2048 + k * 1024); } while (0)
; #define PG8_MMA(ai, bj, At, Bt) do { __builtin_amdgcn_s_setprio(1); _Pragma("unroll") for (int m = 0; m < 4; ++m) _Pragma("unroll") for (int n = 0; n < 2; ++n) _Pragma("unroll") for (int k = 0; k < 2; ++k) \
;         acc[ai][bj][m][n] = __builtin_amdgcn_mfma_f32_16x16x32_bf16(Bt[n][k], At[m][k], acc[ai][bj][m][n], 0, 0, 0); __builtin_amdgcn_s_setprio(0); } while (0)
; #define PG8_WAIT_V(n) asm volatile("s_waitcnt vmcnt(" #n ")" ::: "memory")
; #define PG8_WAIT_L(n) asm volatile("s_waitcnt lgkmcnt(" #n ")" ::: "memory")
; #define PG8_BAR __builtin_amdgcn_s_barrier()
; #define PG8_SCHED __builtin_amdgcn_sched_barrier(0)
; template <class Epi, class Sched, bool ALIGN_EPI = false, bool SP2 = false>
; __device__ __forceinline__ void gemm_phase(PG8_LAS unsigned char* lds, const Gemm g, const Sched& S, const Epi& E, const int wave_id) {
;     ...
;             PG8_WAIT_V(8); PG8_WAIT_L(0); PG8_BAR; PG8_MMA(0, 0, At, B0); PG8_MMA(0, 1, At, B1); PG8_BAR; PG8_SCHED;
;             PG8_LDA(At, 0, 1); PG8_STAGE(PG8_SB(0, 0), b2, voffB); PG8_STAGE(PG8_SB(0, 1), b2 + hstepB, voffB); PG8_STAGE(PG8_SA(0, 0), a2, voffA);
;             PG8_WAIT_V(8); PG8_WAIT_L(0); PG8_BAR; PG8_MMA(1, 0, At, B0); PG8_MMA(1, 1, At, B1); PG8_BAR; PG8_SCHED;
.Lrw_5:
	s_waitcnt lgkmcnt(0)
	s_setprio 1
	s_barrier
	v_mfma_f32_16x16x32_bf16 v[166:169], v[114:117], v[190:193], v[166:169]
	v_mfma_f32_16x16x32_bf16 v[162:165], v[122:125], v[190:193], v[162:165]
	v_mfma_f32_16x16x32_bf16 v[134:137], v[114:117], v[202:205], v[134:137]
	v_mfma_f32_16x16x32_bf16 v[126:129], v[122:125], v[202:205], v[126:129]
	v_mfma_f32_16x16x32_bf16 v[102:105], v[114:117], v[210:213], v[102:105]
	v_mfma_f32_16x16x32_bf16 v[98:101], v[122:125], v[210:213], v[98:101]
	v_mfma_f32_16x16x32_bf16 v[86:89], v[114:117], v[218:221], v[86:89]
	v_mfma_f32_16x16x32_bf16 v[82:85], v[122:125], v[218:221], v[82:85]
	v_mfma_f32_16x16x32_bf16 v[166:169], v[118:121], v[194:197], v[166:169]
	v_mfma_f32_16x16x32_bf16 v[162:165], v[130:133], v[194:197], v[162:165]
	v_mfma_f32_16x16x32_bf16 v[134:137], v[118:121], v[206:209], v[134:137]
	v_mfma_f32_16x16x32_bf16 v[126:129], v[130:133], v[206:209], v[126:129]
	v_mfma_f32_16x16x32_bf16 v[102:105], v[118:121], v[214:217], v[102:105]
	v_mfma_f32_16x16x32_bf16 v[98:101], v[130:133], v[214:217], v[98:101]
	v_mfma_f32_16x16x32_bf16 v[86:89], v[118:121], v[222:225], v[86:89]
	v_mfma_f32_16x16x32_bf16 v[82:85], v[130:133], v[222:225], v[82:85]
	v_mfma_f32_16x16x32_bf16 v[158:161], v[138:141], v[190:193], v[158:161]
	v_mfma_f32_16x16x32_bf16 v[146:149], v[150:153], v[190:193], v[146:149]
	v_mfma_f32_16x16x32_bf16 v[110:113], v[138:141], v[202:205], v[110:113]
	v_mfma_f32_16x16x32_bf16 v[106:109], v[150:153], v[202:205], v[106:109]
	v_mfma_f32_16x16x32_bf16 v[94:97], v[138:141], v[210:213], v[94:97]
	v_mfma_f32_16x16x32_bf16 v[90:93], v[150:153], v[210:213], v[90:93]
	v_mfma_f32_16x16x32_bf16 v[78:81], v[138:141], v[218:221], v[78:81]
	v_mfma_f32_16x16x32_bf16 v[74:77], v[150:153], v[218:221], v[74:77]
	v_mfma_f32_16x16x32_bf16 v[158:161], v[142:145], v[194:197], v[158:161]
	v_mfma_f32_16x16x32_bf16 v[146:149], v[154:157], v[194:197], v[146:149]
	v_mfma_f32_16x16x32_bf16 v[110:113], v[142:145], v[206:209], v[110:113]
	v_mfma_f32_16x16x32_bf16 v[106:109], v[154:157], v[206:209], v[106:109]
	v_mfma_f32_16x16x32_bf16 v[94:97], v[142:145], v[214:217], v[94:97]
	v_mfma_f32_16x16x32_bf16 v[90:93], v[154:157], v[214:217], v[90:93]
	v_mfma_f32_16x16x32_bf16 v[78:81], v[142:145], v[222:225], v[78:81]
	v_mfma_f32_16x16x32_bf16 v[74:77], v[154:157], v[222:225], v[74:77]
	s_barrier
	s_setprio 0
	s_add_i32 s1, s38, s23
	v_lshl_add_u64 v[198:199], s[26:27], 0, v[180:181]
	s_mov_b32 m0, s1
	ds_read_b128 v[190:193], v245 offset:16384
	ds_read_b128 v[194:197], v245 offset:17408
	ds_read_b128 v[202:205], v245 offset:18432
	ds_read_b128 v[206:209], v245 offset:19456
	ds_read_b128 v[210:213], v245 offset:20480
	ds_read_b128 v[214:217], v245 offset:21504
	ds_read_b128 v[218:221], v245 offset:22528
	ds_read_b128 v[222:225], v245 offset:23552
	global_load_lds_dwordx4 v[198:199], off
	s_add_i32 m0, s1, 0x2000
	s_add_u32 s38, s26, 0x40000
	v_lshl_add_u64 v[234:235], s[26:27], 0, v[184:185]
	s_addc_u32 s39, s27, 0
	s_add_i32 s0, s0, s23
	global_load_lds_dwordx4 v[234:235], off
	v_lshl_add_u64 v[236:237], s[38:39], 0, v[180:181]
	s_mov_b32 m0, s0
	v_lshl_add_u64 v[246:247], s[28:29], 0, v[182:183]
	global_load_lds_dwordx4 v[236:237], off
	v_lshl_add_u64 v[236:237], s[38:39], 0, v[184:185]
	s_add_i32 m0, s0, 0x2000
	s_nop 0
	global_load_lds_dwordx4 v[236:237], off
	v_lshl_add_u64 v[236:237], s[28:29], 0, v[178:179]
	s_mov_b32 m0, s30
	s_nop 0
	global_load_lds_dwordx4 v[236:237], off
	s_mov_b32 m0, s31
	s_nop 0
	global_load_lds_dwordx4 v[246:247], off
	s_waitcnt vmcnt(24)
	s_cmp_eq_u32 s98, 1
	s_cbranch_scc1 .Lrw_6
	s_waitcnt vmcnt(8)
.Lrw_6:
	s_mov_b32 s98, 0
	s_waitcnt lgkmcnt(0)
	s_setprio 1
	s_barrier
	v_mfma_f32_16x16x32_bf16 v[70:73], v[114:117], v[190:193], v[70:73]
	v_mfma_f32_16x16x32_bf16 v[66:69], v[122:125], v[190:193], v[66:69]
	v_mfma_f32_16x16x32_bf16 v[54:57], v[114:117], v[202:205], v[54:57]
	v_mfma_f32_16x16x32_bf16 v[50:53], v[122:125], v[202:205], v[50:53]
	v_mfma_f32_16x16x32_bf16 v[38:41], v[114:117], v[210:213], v[38:41]
	v_mfma_f32_16x16x32_bf16 v[34:37], v[122:125], v[210:213], v[34:37]
	v_mfma_f32_16x16x32_bf16 v[22:25], v[114:117], v[218:221], v[22:25]
	v_mfma_f32_16x16x32_bf16 v[18:21], v[122:125], v[218:221], v[18:21]
	v_mfma_f32_16x16x32_bf16 v[70:73], v[118:121], v[194:197], v[70:73]
	v_mfma_f32_16x16x32_bf16 v[66:69], v[130:133], v[194:197], v[66:69]
	v_mfma_f32_16x16x32_bf16 v[54:57], v[118:121], v[206:209], v[54:57]
	v_mfma_f32_16x16x32_bf16 v[50:53], v[130:133], v[206:209], v[50:53]
	v_mfma_f32_16x16x32_bf16 v[38:41], v[118:121], v[214:217], v[38:41]
	v_mfma_f32_16x16x32_bf16 v[34:37], v[130:133], v[214:217], v[34:37]
	v_mfma_f32_16x16x32_bf16 v[22:25], v[118:121], v[222:225], v[22:25]
	v_mfma_f32_16x16x32_bf16 v[18:21], v[130:133], v[222:225], v[18:21]
	v_mfma_f32_16x16x32_bf16 v[62:65], v[138:141], v[190:193], v[62:65]
	v_mfma_f32_16x16x32_bf16 v[58:61], v[150:153], v[190:193], v[58:61]
	v_mfma_f32_16x16x32_bf16 v[46:49], v[138:141], v[202:205], v[46:49]
	v_mfma_f32_16x16x32_bf16 v[42:45], v[150:153], v[202:205], v[42:45]
	v_mfma_f32_16x16x32_bf16 v[30:33], v[138:141], v[210:213], v[30:33]
	v_mfma_f32_16x16x32_bf16 v[26:29], v[150:153], v[210:213], v[26:29]
	v_mfma_f32_16x16x32_bf16 v[14:17], v[138:141], v[218:221], v[14:17]
	v_mfma_f32_16x16x32_bf16 v[10:13], v[150:153], v[218:221], v[10:13]
	v_mfma_f32_16x16x32_bf16 v[62:65], v[142:145], v[194:197], v[62:65]
	v_mfma_f32_16x16x32_bf16 v[58:61], v[154:157], v[194:197], v[58:61]
	v_mfma_f32_16x16x32_bf16 v[46:49], v[142:145], v[206:209], v[46:49]
	v_mfma_f32_16x16x32_bf16 v[42:45], v[154:157], v[206:209], v[42:45]
	v_mfma_f32_16x16x32_bf16 v[30:33], v[142:145], v[214:217], v[30:33]
	v_mfma_f32_16x16x32_bf16 v[26:29], v[154:157], v[214:217], v[26:29]
	v_mfma_f32_16x16x32_bf16 v[14:17], v[142:145], v[222:225], v[14:17]
	v_mfma_f32_16x16x32_bf16 v[10:13], v[154:157], v[222:225], v[10:13]
	s_barrier
; #define PG8_STAGE(bufoff, gbase, voff) do { _Pragma("unroll") for (int _i = 0; _i < 2; ++_i) \
;         __builtin_amdgcn_global_load_lds((const unsigned*)((const char*)(gbase) + (voff)[_i]), (PG8_LAS unsigned*)(lds + (bufoff) + ldsw + _i * 8192), 16, 0, 0); } while (0)
; #define PG8_LDA(dst, b, h) do { _Pragma("unroll") for (int m = 0; m < 4; ++m) _Pragma("unroll") for (int k = 0; k < 2; ++k) dst[m][k] = *(const PG8_LAS bf16x8*)(lds + PG8_SA(b, h) + aoff + m * 2048 + k * 1024); } while (0)
; #define PG8_LDB(dst, b, h) do { _Pragma("unroll") for (int n = 0; n < 2; ++n) _Pragma("unroll") for (int k = 0; k < 2; ++k) dst[n][k] = *(const PG8_LAS bf16x8*)(lds + PG8_SB(b, h) + boff + n * 2048 + k * 1024); } while (0)
; #define PG8_MMA(ai, bj, At, Bt) do { __builtin_amdgcn_s_setprio(1); _Pragma("unroll") for (int m = 0; m < 4; ++m) _Pragma("unroll") for (int n = 0; n < 2; ++n) _Pragma("unroll") for (int k = 0; k < 2; ++k) \
;         acc[ai][bj][m][n] = __builtin_amdgcn_mfma_f32_16x16x32_bf16(Bt[n][k], At[m][k], acc[ai][bj][m][n], 0, 0, 0); __builtin_amdgcn_s_setprio(0); } while (0)
; #define PG8_WAIT_V(n) asm volatile("s_waitcnt vmcnt(" #n ")" ::: "memory")
; #define PG8_WAIT_L(n) asm volatile("s_waitcnt lgkmcnt(" #n ")" ::: "memory")
; #define PG8_BAR __builtin_amdgcn_s_barrier()
; #define PG8_SCHED __builtin_amdgcn_sched_barrier(0)
; template <class Epi, class Sched, bool ALIGN_EPI = false, bool SP2 = false>
; __device__ __forceinline__ void gemm_phase(PG8_LAS unsigned char* lds, const Gemm g, const Sched& S, const Epi& E, const int wave_id) {
;     ...
;             PG8_WAIT_V(8); PG8_WAIT_L(0); PG8_BAR; PG8_MMA(1, 0, At, B0); PG8_MMA(1, 1, At, B1); PG8_BAR; PG8_SCHED;
;             PG8_LDB(B0, 1, 0); PG8_LDB(B1, 1, 1); PG8_SCHED; PG8_LDA(At, 1, 0); PG8_STAGE(PG8_SA(0, 1), a2 + hstepA, voffA);
;             PG8_WAIT_V(8); PG8_WAIT_L(0); PG8_BAR; PG8_MMA(0, 0, At, B0); PG8_MMA(0, 1, At, B1); PG8_BAR; PG8_SCHED;
	s_setprio 0
	s_add_i32 s0, 0, 0x18000
	v_add_u32_e32 v0, s0, v240
	s_add_i32 s1, 0, 0x1c000
	ds_read_b128 v[114:117], v0
	ds_read_b128 v[118:121], v0 offset:1024
	ds_read_b128 v[122:125], v0 offset:2048
	ds_read_b128 v[130:133], v0 offset:3072
	v_add_u32_e32 v0, s1, v240
	ds_read_b128 v[138:141], v0
	ds_read_b128 v[142:145], v0 offset:1024
	ds_read_b128 v[150:153], v0 offset:2048
	ds_read_b128 v[154:157], v0 offset:3072
	s_add_u32 s28, s28, 0x40000
	s_addc_u32 s29, s29, 0
	s_mov_b32 m0, s34
	v_lshl_add_u64 v[248:249], s[28:29], 0, v[178:179]
	ds_read_b128 v[190:193], v245 offset:32768
	ds_read_b128 v[194:197], v245 offset:33792
	ds_read_b128 v[202:205], v245 offset:34816
	ds_read_b128 v[206:209], v245 offset:35840
	ds_read_b128 v[210:213], v245 offset:36864
	ds_read_b128 v[214:217], v245 offset:37888
	ds_read_b128 v[218:221], v245 offset:38912
	ds_read_b128 v[222:225], v245 offset:39936
	global_load_lds_dwordx4 v[248:249], off
	v_lshl_add_u64 v[248:249], s[28:29], 0, v[182:183]
	s_mov_b32 m0, s35
	s_nop 0
	global_load_lds_dwordx4 v[248:249], off
	s_waitcnt vmcnt(8)
	s_waitcnt lgkmcnt(0)
	s_setprio 1
	s_barrier
	v_mfma_f32_16x16x32_bf16 v[166:169], v[114:117], v[190:193], v[166:169]
	v_mfma_f32_16x16x32_bf16 v[162:165], v[122:125], v[190:193], v[162:165]
	v_mfma_f32_16x16x32_bf16 v[134:137], v[114:117], v[202:205], v[134:137]
	v_mfma_f32_16x16x32_bf16 v[126:129], v[122:125], v[202:205], v[126:129]
	v_mfma_f32_16x16x32_bf16 v[102:105], v[114:117], v[210:213], v[102:105]
	v_mfma_f32_16x16x32_bf16 v[98:101], v[122:125], v[210:213], v[98:101]
	v_mfma_f32_16x16x32_bf16 v[86:89], v[114:117], v[218:221], v[86:89]
	v_mfma_f32_16x16x32_bf16 v[82:85], v[122:125], v[218:221], v[82:85]
	v_mfma_f32_16x16x32_bf16 v[166:169], v[118:121], v[194:197], v[166:169]
	v_mfma_f32_16x16x32_bf16 v[162:165], v[130:133], v[194:197], v[162:165]
	v_mfma_f32_16x16x32_bf16 v[134:137], v[118:121], v[206:209], v[134:137]
	v_mfma_f32_16x16x32_bf16 v[126:129], v[130:133], v[206:209], v[126:129]
	v_mfma_f32_16x16x32_bf16 v[102:105], v[118:121], v[214:217], v[102:105]
	v_mfma_f32_16x16x32_bf16 v[98:101], v[130:133], v[214:217], v[98:101]
	v_mfma_f32_16x16x32_bf16 v[86:89], v[118:121], v[222:225], v[86:89]
	v_mfma_f32_16x16x32_bf16 v[82:85], v[130:133], v[222:225], v[82:85]
	v_mfma_f32_16x16x32_bf16 v[158:161], v[138:141], v[190:193], v[158:161]
	v_mfma_f32_16x16x32_bf16 v[146:149], v[150:153], v[190:193], v[146:149]
	v_mfma_f32_16x16x32_bf16 v[110:113], v[138:141], v[202:205], v[110:113]
	v_mfma_f32_16x16x32_bf16 v[106:109], v[150:153], v[202:205], v[106:109]
	v_mfma_f32_16x16x32_bf16 v[94:97], v[138:141], v[210:213], v[94:97]
	v_mfma_f32_16x16x32_bf16 v[90:93], v[150:153], v[210:213], v[90:93]
	v_mfma_f32_16x16x32_bf16 v[78:81], v[138:141], v[218:221], v[78:81]
	v_mfma_f32_16x16x32_bf16 v[74:77], v[150:153], v[218:221], v[74:77]
	v_mfma_f32_16x16x32_bf16 v[158:161], v[142:145], v[194:197], v[158:161]
	v_mfma_f32_16x16x32_bf16 v[146:149], v[154:157], v[194:197], v[146:149]
	v_mfma_f32_16x16x32_bf16 v[110:113], v[142:145], v[206:209], v[110:113]
	v_mfma_f32_16x16x32_bf16 v[106:109], v[154:157], v[206:209], v[106:109]
	v_mfma_f32_16x16x32_bf16 v[94:97], v[142:145], v[214:217], v[94:97]
	v_mfma_f32_16x16x32_bf16 v[90:93], v[154:157], v[214:217], v[90:93]
	v_mfma_f32_16x16x32_bf16 v[78:81], v[142:145], v[222:225], v[78:81]
	v_mfma_f32_16x16x32_bf16 v[74:77], v[154:157], v[222:225], v[74:77]
	s_barrier
; #define PG8_STAGE(bufoff, gbase, voff) do { _Pragma("unroll") for (int _i = 0; _i < 2; ++_i) \
;         __builtin_amdgcn_global_load_lds((const unsigned*)((const char*)(gbase) + (voff)[_i]), (PG8_LAS unsigned*)(lds + (bufoff) + ldsw + _i * 8192), 16, 0, 0); } while (0)
; #define PG8_LDA(dst, b, h) do { _Pragma("unroll") for (int m = 0; m < 4; ++m) _Pragma("unroll") for (int k = 0; k < 2; ++k) dst[m][k] = *(const PG8_LAS bf16x8*)(lds + PG8_SA(b, h) + aoff + m * 2048 + k * 1024); } while (0)
; #define PG8_MMA(ai, bj, At, Bt) do { __builtin_amdgcn_s_setprio(1); _Pragma("unroll") for (int m = 0; m < 4; ++m) _Pragma("unroll") for (int n = 0; n < 2; ++n) _Pragma("unroll") for (int k = 0; k < 2; ++k) \
;         acc[ai][bj][m][n] = __builtin_amdgcn_mfma_f32_16x16x32_bf16(Bt[n][k], At[m][k], acc[ai][bj][m][n], 0, 0, 0); __builtin_amdgcn_s_setprio(0); } while (0)
; #define PG8_WAIT_V(n) asm volatile("s_waitcnt vmcnt(" #n ")" ::: "memory")
; #define PG8_WAIT_L(n) asm volatile("s_waitcnt lgkmcnt(" #n ")" ::: "memory")
; #define PG8_BAR __builtin_amdgcn_s_barrier()
; #define PG8_SCHED __builtin_amdgcn_sched_barrier(0)
; template <class Epi, class Sched, bool ALIGN_EPI = false, bool SP2 = false>
; __device__ __forceinline__ void gemm_phase(PG8_LAS unsigned char* lds, const Gemm g, const Sched& S, const Epi& E, const int wave_id) {
;     ...
;         for (int t = 0; t < nt; t += 2) {
;             const bool last = (t == nt - 2);
;     ...
;             PG8_LDA(At, 1, 1); PG8_STAGE(PG8_SB(1, 0), b3, voffB); PG8_STAGE(PG8_SB(1, 1), b3 + hstepB, voffB); PG8_STAGE(PG8_SA(1, 0), a3, voffA);
;             PG8_WAIT_V(8); PG8_WAIT_L(0); PG8_BAR; PG8_MMA(1, 0, At, B0); PG8_MMA(1, 1, At, B1); PG8_BAR; PG8_SCHED;
	s_setprio 0
	s_add_i32 s0, s0, s23
	v_lshl_add_u64 v[198:199], v[198:199], 0, s[62:63]
	s_mov_b32 m0, s0
	ds_read_b128 v[190:193], v245 offset:49152
	ds_read_b128 v[194:197], v245 offset:50176
	ds_read_b128 v[202:205], v245 offset:51200
	ds_read_b128 v[206:209], v245 offset:52224
	ds_read_b128 v[210:213], v245 offset:53248
	ds_read_b128 v[214:217], v245 offset:54272
	ds_read_b128 v[218:221], v245 offset:55296
	ds_read_b128 v[222:225], v245 offset:56320
	global_load_lds_dwordx4 v[198:199], off
	s_add_i32 m0, s0, 0x2000
	s_add_u32 s26, s26, 0x40080
	v_lshl_add_u64 v[198:199], v[234:235], 0, s[62:63]
	s_addc_u32 s27, s27, 0
	s_add_i32 s0, s1, s23
	global_load_lds_dwordx4 v[198:199], off
	v_lshl_add_u64 v[198:199], s[26:27], 0, v[180:181]
	s_mov_b32 m0, s0
	s_nop 0
	global_load_lds_dwordx4 v[198:199], off
	v_lshl_add_u64 v[198:199], s[26:27], 0, v[184:185]
	s_add_i32 m0, s0, 0x2000
	s_nop 0
	global_load_lds_dwordx4 v[198:199], off
	v_lshl_add_u64 v[198:199], v[236:237], 0, s[62:63]
	s_mov_b32 m0, s45
	s_nop 0
	global_load_lds_dwordx4 v[198:199], off
	v_lshl_add_u64 v[198:199], v[246:247], 0, s[62:63]
	s_mov_b32 m0, s76
	s_nop 0
	global_load_lds_dwordx4 v[198:199], off
	s_waitcnt vmcnt(8)
	s_waitcnt lgkmcnt(0)
	s_setprio 1
	s_barrier
	v_mfma_f32_16x16x32_bf16 v[70:73], v[114:117], v[190:193], v[70:73]
	v_mfma_f32_16x16x32_bf16 v[66:69], v[122:125], v[190:193], v[66:69]
	v_mfma_f32_16x16x32_bf16 v[54:57], v[114:117], v[202:205], v[54:57]
	v_mfma_f32_16x16x32_bf16 v[50:53], v[122:125], v[202:205], v[50:53]
	v_mfma_f32_16x16x32_bf16 v[38:41], v[114:117], v[210:213], v[38:41]
	v_mfma_f32_16x16x32_bf16 v[34:37], v[122:125], v[210:213], v[34:37]
	v_mfma_f32_16x16x32_bf16 v[22:25], v[114:117], v[218:221], v[22:25]
	v_mfma_f32_16x16x32_bf16 v[18:21], v[122:125], v[218:221], v[18:21]
	v_mfma_f32_16x16x32_bf16 v[70:73], v[118:121], v[194:197], v[70:73]
	v_mfma_f32_16x16x32_bf16 v[66:69], v[130:133], v[194:197], v[66:69]
	v_mfma_f32_16x16x32_bf16 v[54:57], v[118:121], v[206:209], v[54:57]
	v_mfma_f32_16x16x32_bf16 v[50:53], v[130:133], v[206:209], v[50:53]
	v_mfma_f32_16x16x32_bf16 v[38:41], v[118:121], v[214:217], v[38:41]
	v_mfma_f32_16x16x32_bf16 v[34:37], v[130:133], v[214:217], v[34:37]
	v_mfma_f32_16x16x32_bf16 v[22:25], v[118:121], v[222:225], v[22:25]
	v_mfma_f32_16x16x32_bf16 v[18:21], v[130:133], v[222:225], v[18:21]
	v_mfma_f32_16x16x32_bf16 v[62:65], v[138:141], v[190:193], v[62:65]
	v_mfma_f32_16x16x32_bf16 v[58:61], v[150:153], v[190:193], v[58:61]
	v_mfma_f32_16x16x32_bf16 v[46:49], v[138:141], v[202:205], v[46:49]
	v_mfma_f32_16x16x32_bf16 v[42:45], v[150:153], v[202:205], v[42:45]
	v_mfma_f32_16x16x32_bf16 v[30:33], v[138:141], v[210:213], v[30:33]
	v_mfma_f32_16x16x32_bf16 v[26:29], v[150:153], v[210:213], v[26:29]
	v_mfma_f32_16x16x32_bf16 v[14:17], v[138:141], v[218:221], v[14:17]
	v_mfma_f32_16x16x32_bf16 v[10:13], v[150:153], v[218:221], v[10:13]
	v_mfma_f32_16x16x32_bf16 v[62:65], v[142:145], v[194:197], v[62:65]
	v_mfma_f32_16x16x32_bf16 v[58:61], v[154:157], v[194:197], v[58:61]
	v_mfma_f32_16x16x32_bf16 v[46:49], v[142:145], v[206:209], v[46:49]
	v_mfma_f32_16x16x32_bf16 v[42:45], v[154:157], v[206:209], v[42:45]
	v_mfma_f32_16x16x32_bf16 v[30:33], v[142:145], v[214:217], v[30:33]
	v_mfma_f32_16x16x32_bf16 v[26:29], v[154:157], v[214:217], v[26:29]
	v_mfma_f32_16x16x32_bf16 v[14:17], v[142:145], v[222:225], v[14:17]
	v_mfma_f32_16x16x32_bf16 v[10:13], v[154:157], v[222:225], v[10:13]
	s_barrier
	s_setprio 0
	s_add_i32 s37, s37, 2
	s_add_u32 s8, s8, 0x100
	s_addc_u32 s9, s9, 0
	s_add_u32 vcc_lo, vcc_lo, 0x100
	s_addc_u32 vcc_hi, vcc_hi, 0
	s_cmp_gt_u32 s37, 13
	s_cbranch_scc0 .LBB0_627
	s_and_b64 vcc, exec, s[12:13]
	s_cbranch_vccz .LBB0_630
	s_barrier
